# SSD: the two waves of an l-tile split the decayed S^T tiles between them and exchange them through LDS (barrier moved mid-step), instead of both computing all tiles
# baseline (speedup 1.0000x reference)
; #define GAS __attribute__((address_space(1)))
; #define LAS __attribute__((address_space(3)))
; __device__ __forceinline__ int launder_v(int v) { asm volatile("" : "+v"(v)); return v; }
; __device__ __forceinline__ int grid_x() { int g = (int)gridDim.x; asm volatile("" : "+s"(g)); return g; }
; __device__ __forceinline__ unsigned f2bf(float f) { return (unsigned)__builtin_bit_cast(unsigned short, (__bf16)f); }
; __device__ __forceinline__ void phase_ssd(const Params& P, int seg, unsigned char* smem) {
;     ...
;     const int tid = launder_v(threadIdx.x), lane = tid & 63, w = tid >> 6, fr = lane & 15, fq = lane >> 4;
;     const unsigned lds0 = (unsigned)(size_t)(LAS unsigned char*)smem;
;     bf16* StS = (bf16*)(smem + T_ST); float* acS = (float*)(smem + T_AC);
;     const int lt = w >> 1, pt = w & 1, tq = (lane & 15) >> 2, tp = lane & 3;
;     if (__builtin_amdgcn_readfirstlane(tid) >= 256) __builtin_amdgcn_s_setprio(1);
;     const int gx = grid_x();
;     for (int item = blockIdx.x; item < 256; item += gx) {
;         const int xcd = item & 7, ix = item >> 3, bg = xcd * 2 + (ix >> 4), b = bg >> 3, g = bg & 7, h = g * 8 + ((ix & 15) >> 1), ph = ix & 1;
;         const float Dh = P.d_skip[h];
;         const GAS float* stg = state + (size_t)(seg & 1) * (2 * 64 * 64 * 128) + ((size_t)(b * 64 + h) * 64 + ph * 32) * 128;
;         GAS float* stw = state + (size_t)((seg + 1) & 1) * (2 * 64 * 64 * 128) + ((size_t)(b * 64 + h) * 64 + ph * 32) * 128;
;         f32x4 st[2];
; #pragma unroll
;         for (int p2 = 0; p2 < 2; ++p2)
; #pragma unroll
;             for (int j = 0; j < 4; ++j) st[p2][j] = (seg == 0) ? 0.f : stg[(size_t)(p2 * 16 + fq * 4 + j) * 128 + w * 16 + fr];
;         __syncthreads();
; #pragma unroll
;         for (int p2 = 0; p2 < 2; ++p2)
; #pragma unroll
;             for (int j = 0; j < 4; ++j) StS[(p2 * 16 + fq * 4 + j) * 136 + w * 16 + fr] = (bf16)f2bf(st[p2][j]);
;         const int nchunks = TSEG / 64 + (seg == 0 ? 1 : 0);
;         struct Pre { v4u Br[2], Cr[2]; v2u Xr, Zr; float dtl, acl, alast, aclane; }; Pre RA, RB;
;         auto chunk_row0 = [&](int ci) -> int { return (seg == 0) ? (ci == 0 ? RS : b * TSEG + (ci - 1) * 64) : b * TSEG + ci * 64; };
.LBB0_292:
	v_readlane_b32 s14, v253, 47
	v_readlane_b32 s15, v253, 48
	s_mov_b32 s9, s82
	s_andn2_b64 vcc, exec, s[14:15]
	v_cndmask_b32_e64 v4, 0, 1, s[14:15]
	v_cmp_ne_u32_e64 s[16:17], 1, v4
	s_nop 1
	v_writelane_b32 v255, s16, 7
	s_nop 1
	v_writelane_b32 v255, s17, 8
	s_cbranch_vccnz .LBB0_338
	s_mov_b64 exec, -1
	s_mov_b64 s[0:1], s[80:81]
	s_mov_b32 s63, s82
	v_readlane_b32 s24, v254, 38
	v_readlane_b32 s52, v252, 28
	v_readlane_b32 s53, v252, 29
	v_and_b32_e32 v184, 63, v172
	v_lshrrev_b32_e32 v185, 6, v172
	v_and_b32_e32 v186, 15, v172
	v_bfe_u32 v187, v172, 4, 2
	v_bfe_u32 v188, v172, 2, 2
	v_and_b32_e32 v189, 3, v172
	v_lshrrev_b32_e32 v190, 7, v172
	v_lshrrev_b32_e32 v191, 8, v172
	v_xor_b32_e32 v190, v190, v191
	v_bfe_u32 v191, v172, 6, 1
	v_readfirstlane_b32 s73, v185
	s_nop 3
	s_and_b32 s74, s73, 1
	s_lshr_b32 s55, s73, 1
	s_lshr_b32 s65, s73, 2
	s_xor_b32 s55, s55, s65
	s_bitcmp1_b32 s55, 0
	s_cbranch_scc1 .Lssd_prio1
	s_setprio 0
	s_branch .Lssd_prio_done
.Lssd_prio1:
	s_setprio 1
.Lssd_prio_done:
	v_lshrrev_b32_e32 v170, 4, v172
	v_and_b32_e32 v171, 7, v170
	v_lshlrev_b32_e32 v171, 1, v171
	v_xor_b32_e32 v171, v171, v186
	v_lshlrev_b32_e32 v171, 4, v171
	v_lshl_add_u32 v212, v170, 8, v171
	v_lshrrev_b32_e32 v171, 3, v172
	v_and_b32_e32 v192, 7, v172
	v_mul_u32_u24_e32 v214, 80, v171
	v_lshl_add_u32 v214, v192, 3, v214
	v_mul_u32_u24_e32 v216, 72, v171
	v_lshl_add_u32 v216, v192, 3, v216
	v_lshlrev_b32_e32 v218, 2, v171
	v_add_u32_e32 v218, 0x1d800, v218
	v_and_b32_e32 v193, 7, v186
	v_lshlrev_b32_e32 v193, 1, v193
	v_lshl_add_u32 v195, v191, 4, v186
	v_lshlrev_b32_e32 v195, 8, v195
	v_add_u32_e32 v195, 0x19800, v195
	v_add_u32_e32 v170, 0, v187
	v_xor_b32_e32 v170, v170, v193
	v_lshlrev_b32_e32 v170, 4, v170
	v_lshl_add_u32 v219, v186, 8, v170
	v_add_u32_e32 v227, v195, v170
	v_add_u32_e32 v170, 4, v187
	v_xor_b32_e32 v170, v170, v193
	v_lshlrev_b32_e32 v170, 4, v170
	v_lshl_add_u32 v220, v186, 8, v170
	v_add_u32_e32 v228, v195, v170
	v_add_u32_e32 v170, 8, v187
	v_xor_b32_e32 v170, v170, v193
	v_lshlrev_b32_e32 v170, 4, v170
	v_lshl_add_u32 v221, v186, 8, v170
	v_add_u32_e32 v229, v195, v170
	v_add_u32_e32 v170, 12, v187
	v_xor_b32_e32 v170, v170, v193
	v_lshlrev_b32_e32 v170, 4, v170
	v_lshl_add_u32 v222, v186, 8, v170
	v_add_u32_e32 v230, v195, v170
	v_and_b32_e32 v250, 63, v172
	v_lshlrev_b32_e32 v250, 4, v250
	v_add_u32_e32 v250, 0x1da00, v250
	v_lshlrev_b32_e32 v231, 2, v186
	v_add_u32_e32 v231, 0x1d800, v231
	v_lshlrev_b32_e32 v232, 4, v187
	v_add_u32_e32 v232, 0x1d800, v232
	v_lshl_add_u32 v170, v187, 2, v188
	v_mul_u32_u24_e32 v233, 80, v170
	v_lshl_add_u32 v233, v191, 5, v233
	v_lshl_add_u32 v233, v189, 3, v233
	v_mul_u32_u24_e32 v235, 72, v186
	v_lshl_add_u32 v235, v191, 5, v235
	v_lshl_add_u32 v235, v187, 3, v235
	v_mul_u32_u24_e32 v237, 80, v170
	v_lshl_add_u32 v237, v189, 3, v237
	v_and_b32_e32 v171, 7, v170
	v_lshlrev_b32_e32 v171, 1, v171
	v_lshrrev_b32_e32 v192, 1, v189
	v_and_b32_e32 v195, 1, v189
	v_lshlrev_b32_e32 v195, 3, v195
	v_lshl_add_u32 v195, v170, 8, v195
	v_and_b32_e32 v194, 3, v185
	v_lshl_add_u32 v193, v194, 2, v192
	v_xor_b32_e32 v193, v193, v171
	v_lshl_add_u32 v244, v193, 4, v195
	v_lshl_add_u32 v193, v194, 2, v192
	v_add_u32_e32 v193, 2, v193
	v_xor_b32_e32 v193, v193, v171
	v_lshl_add_u32 v245, v193, 4, v195
	v_and_b32_e32 v171, 7, v186
	v_lshlrev_b32_e32 v171, 1, v171
	v_lshrrev_b32_e32 v192, 1, v187
	v_and_b32_e32 v195, 1, v187
	v_lshlrev_b32_e32 v195, 3, v195
	v_lshl_add_u32 v195, v186, 8, v195
	v_add_u32_e32 v195, 0x19800, v195
	v_lshl_add_u32 v193, v194, 2, v192
	v_xor_b32_e32 v193, v193, v171
	v_lshl_add_u32 v248, v193, 4, v195
	v_lshl_add_u32 v193, v194, 2, v192
	v_add_u32_e32 v193, 2, v193
	v_xor_b32_e32 v193, v193, v171
	v_lshl_add_u32 v249, v193, 4, v195
	v_add_u32_e32 v213, 0xcc00, v212
	v_add_u32_e32 v215, 0xcc00, v214
	v_add_u32_e32 v217, 0xcc00, v216
	v_add_u32_e32 v234, 0xcc00, v233
	v_add_u32_e32 v236, 0xcc00, v235
	v_add_u32_e32 v243, 0xcc00, v237
	v_add_u32_e32 v223, 0xcc00, v219
	v_add_u32_e32 v224, 0xcc00, v220
	v_add_u32_e32 v225, 0xcc00, v221
	v_add_u32_e32 v226, 0xcc00, v222
	v_add_u32_e32 v246, 0xcc00, v244
	v_add_u32_e32 v247, 0xcc00, v245
	v_lshlrev_b32_e32 v170, 2, v187
	v_add_u32_e32 v171, 0, v170
	v_cmp_le_u32_e64 s[14:15], v171, v186
	v_add_u32_e32 v171, 1, v170
	v_cmp_le_u32_e64 s[16:17], v171, v186
	v_add_u32_e32 v171, 2, v170
	v_cmp_le_u32_e64 s[22:23], v171, v186
	v_add_u32_e32 v171, 3, v170
	v_cmp_le_u32_e64 s[34:35], v171, v186
	v_lshlrev_b32_e32 v211, 9, v186
	v_lshl_add_u32 v211, v194, 7, v211
	v_lshl_add_u32 v211, v187, 4, v211
	s_cmp_eq_u32 s24, 0
	s_cselect_b32 s60, 1, 0
	s_add_u32 s39, s60, 64
	s_mov_b32 s18, s2

; __device__ __forceinline__ unsigned cvt_pk_bf16(float lo, float hi) { unsigned r; asm volatile("v_cvt_pk_bf16_f32 %0, %1, %2" : "=v"(r) : "v"(lo), "v"(hi)); return r; }
; __device__ __forceinline__ void phase_ssd(const Params& P, int seg, unsigned char* smem) {
;     ...
;             { const float e2 = __expf(R.alast - R.acl);
; #pragma unroll
;               for (int i = 0; i < 2; ++i) { const int q = tid + 512 * i, l = q >> 4, c8 = q & 15; *(v4u*)(sb + T_CS + l * 272 + c8 * 16) = R.Cr[i]; *(v4u*)(sb + T_BS + l * 272 + c8 * 16) = R.Br[i]; }
;               const int l = tid >> 3, p4 = (tid & 7) * 4;
;               const float x0 = bflo(R.Xr.x) * R.dtl, x1 = bfhi(R.Xr.x) * R.dtl, x2 = bflo(R.Xr.y) * R.dtl, x3 = bfhi(R.Xr.y) * R.dtl;
;               v2u d; d.x = cvt_pk_bf16(x0, x1); d.y = cvt_pk_bf16(x2, x3); *(v2u*)(sb + T_XD + l * 80 + p4 * 2) = d;
;               v2u e; e.x = cvt_pk_bf16(x0 * e2, x1 * e2); e.y = cvt_pk_bf16(x2 * e2, x3 * e2); *(v2u*)(sb + T_XE + l * 80 + p4 * 2) = e;
;               *(v2u*)(sb + T_XS + l * 64 + p4 * 2) = R.Xr; *(v2u*)(sb + T_ZS + l * 64 + p4 * 2) = R.Zr;
;               if (w == 0) acP[lane] = R.aclane; }
;             BAR_LDS();
;             if (ci + 2 < nchunks) load_chunk(ci + 2, R);
;             bf16x8 cf[4];
; #pragma unroll
;             for (int k = 0; k < 4; ++k) cf[k] = *(const bf16x8*)(sb + T_CS + (lt * 16 + fr) * 272 + (k * 32 + fq * 8) * 2);
;             f32x4 yo = {0.f, 0.f, 0.f, 0.f};
; #pragma unroll
;             for (int k = 0; k < 4; ++k) { const bf16x8 bb = *(const bf16x8*)((const unsigned char*)StR + (pt * 16 + fr) * 272 + (k * 32 + fq * 8) * 2); yo = mfma16(cf[k], bb, yo); }
; { const f32x4 a4 = *(const f32x4*)(acP + lt * 16 + fq * 4);
; #pragma unroll
;               for (int j = 0; j < 4; ++j) yo[j] *= __expf(a4[j]); }
;             const float acl_fr = acP[lt * 16 + fr]; const int lrow = lt * 16 + fr;
; #pragma unroll
;             for (int t = 0; t < 2; ++t) {
;                 if (2 * t <= lt) {
;                     v2u xb0, xb1;
;                     { const unsigned a0 = lds0 + par * T_BUF + T_XD + (32 * t + 4 * fq + tq) * 80 + (pt * 16 + 4 * tp) * 2, a1 = a0 + 16 * 80; TR_ISSUE(xb0, a0); TR_ISSUE(xb1, a1); }
;                     float m[8];
;                     { f32x4 s0 = {0.f, 0.f, 0.f, 0.f}, s1 = {0.f, 0.f, 0.f, 0.f};
; #pragma unroll
.Lssd_noimg:
	ds_write_b128 v212, v[140:143]
	ds_write_b128 v212, v[144:147] offset:8192
	ds_write_b128 v212, v[132:135] offset:16384
	ds_write_b128 v212, v[136:139] offset:24576
	v_sub_f32_e32 v200, v117, v116
	v_mul_f32_e32 v200, 0x3fb8aa3b, v200
	v_exp_f32_e32 v200, v200
	v_lshlrev_b32_e32 v196, 16, v4
	v_and_b32_e32 v197, 0xffff0000, v4
	v_lshlrev_b32_e32 v198, 16, v5
	v_and_b32_e32 v199, 0xffff0000, v5
	v_mul_f32_e32 v196, v196, v6
	v_mul_f32_e32 v197, v197, v6
	v_mul_f32_e32 v198, v198, v6
	v_mul_f32_e32 v199, v199, v6
	v_cvt_pk_bf16_f32 v202, v196, v197
	v_cvt_pk_bf16_f32 v203, v198, v199
	ds_write_b64 v214, v[202:203] offset:32768
	v_mul_f32_e32 v196, v196, v200
	v_mul_f32_e32 v197, v197, v200
	v_mul_f32_e32 v198, v198, v200
	v_mul_f32_e32 v199, v199, v200
	v_cvt_pk_bf16_f32 v192, v196, v197
	v_cvt_pk_bf16_f32 v193, v198, v199
	ds_write_b64 v214, v[192:193] offset:37888
	ds_write_b64 v216, v[4:5] offset:43008
	ds_write_b64 v216, v[36:37] offset:47616
	v_mul_f32_e32 v201, 0x3fb8aa3b, v116
	ds_write_b32 v218, v201
	v_mul_f32_e32 v174, 0x3fb8aa3b, v117
	v_exp_f32_e32 v174, v174
	v_mov_b32_e32 v184, 0
	v_mov_b32_e32 v185, 0
	v_mov_b32_e32 v186, 0
	v_mov_b32_e32 v187, 0
	ds_write_b128 v250, v[184:187]
	ds_write_b128 v250, v[184:187] offset:1024
	ds_write_b128 v250, v[184:187] offset:2048
	ds_write_b128 v250, v[184:187] offset:3072
	ds_write_b128 v250, v[184:187] offset:4096
	ds_write_b128 v250, v[184:187] offset:5120
	s_waitcnt lgkmcnt(11)
	ds_write_b128 v250, v[184:187] offset:6144
	ds_write_b128 v250, v[184:187] offset:7168
	ds_write_b128 v250, v[184:187] offset:8192
	ds_write_b128 v250, v[184:187] offset:9984
	s_waitcnt lgkmcnt(11)
	ds_write_b128 v250, v[184:187] offset:11008
	ds_write_b128 v250, v[184:187] offset:12032
	s_waitcnt lgkmcnt(0)
	s_barrier
	s_lshl_b32 s65, s55, 1
	s_add_u32 s65, s65, s74
	s_cmp_eq_u32 s65, 1
	s_cbranch_scc1 .Lssd_loop01
	s_cmp_eq_u32 s65, 2
	s_cbranch_scc1 .Lssd_loop10
	s_cmp_eq_u32 s65, 3
	s_cbranch_scc1 .Lssd_loop11
	s_cmp_eq_u32 s65, 4
	s_cbranch_scc1 .Lssd_loop20
	s_cmp_eq_u32 s65, 5
	s_cbranch_scc1 .Lssd_loop21
	s_cmp_eq_u32 s65, 6
	s_cbranch_scc1 .Lssd_loop30
	s_cmp_eq_u32 s65, 7
	s_cbranch_scc1 .Lssd_loop31
.Lssd_loop00:
	ds_read_b128 v[28:31], v219
	ds_read_b128 v[32:35], v220
	ds_read_b128 v[40:43], v221
	ds_read_b128 v[44:47], v222
	ds_read_b128 v[48:51], v227
	ds_read_b128 v[52:55], v228
	ds_read_b128 v[56:59], v229
	ds_read_b128 v[60:63], v230
	ds_read_b32 v194, v231
	ds_read_b64_tr_b16 v[96:97], v244 offset:16384
	ds_read_b64_tr_b16 v[98:99], v244 offset:20480
	ds_read_b64_tr_b16 v[100:101], v244 offset:24576
	ds_read_b64_tr_b16 v[102:103], v244 offset:28672
	ds_read_b64_tr_b16 v[104:105], v245 offset:16384
	ds_read_b64_tr_b16 v[106:107], v245 offset:20480
	s_waitcnt lgkmcnt(11)
	ds_read_b64_tr_b16 v[108:109], v245 offset:24576
	ds_read_b64_tr_b16 v[110:111], v245 offset:28672
	ds_read_b64_tr_b16 v[112:113], v237 offset:37888
	ds_read_b64_tr_b16 v[114:115], v237 offset:39168
	s_waitcnt lgkmcnt(11)
	ds_read_b64_tr_b16 v[124:125], v237 offset:37920
	ds_read_b64_tr_b16 v[126:127], v237 offset:39200
	ds_read_b64_tr_b16 v[120:121], v237 offset:40448
	ds_read_b64_tr_b16 v[122:123], v237 offset:41728
	global_load_dwordx4 v[140:143], v204, s[40:41] offset:2048
	s_waitcnt lgkmcnt(11)
	ds_read_b64_tr_b16 v[128:129], v237 offset:40480
	ds_read_b64_tr_b16 v[130:131], v237 offset:41760
	ds_read_b128 v[64:67], v219 offset:16384
	global_load_dwordx4 v[144:147], v205, s[40:41] offset:2048
	ds_read_b128 v[68:71], v220 offset:16384
	s_waitcnt lgkmcnt(11)
	ds_read_b128 v[72:75], v221 offset:16384
	ds_read_b128 v[76:79], v222 offset:16384
	global_load_dwordx4 v[132:135], v204, s[40:41]
	v_mfma_f32_16x16x32_bf16 v[24:27], v[48:51], v[28:31], 0
	v_mfma_f32_16x16x32_bf16 v[24:27], v[52:55], v[32:35], v[24:27]
	v_mfma_f32_16x16x32_bf16 v[24:27], v[56:59], v[40:43], v[24:27]
	global_load_dwordx4 v[136:139], v205, s[40:41]
	v_mfma_f32_16x16x32_bf16 v[24:27], v[60:63], v[44:47], v[24:27]
	ds_read_b64_tr_b16 v[56:57], v233 offset:32768
	ds_read_b64_tr_b16 v[58:59], v233 offset:34048
	global_load_dwordx2 v[4:5], v206, s[40:41]
	v_mul_f32_e32 v8, v8, v174
	v_mul_f32_e32 v9, v9, v174
	v_mul_f32_e32 v10, v10, v174
	global_load_dwordx2 v[36:37], v207, s[42:43] nt
	v_mul_f32_e32 v11, v11, v174
	v_mul_f32_e32 v12, v12, v174
	v_mul_f32_e32 v13, v13, v174
	global_load_dword v6, v208, s[44:45]
	v_mul_f32_e32 v14, v14, v174
	v_mul_f32_e32 v15, v15, v174
	v_mul_f32_e32 v16, v16, v174
	global_load_dword v116, v208, s[46:47]
	v_mul_f32_e32 v17, v17, v174
	v_mul_f32_e32 v18, v18, v174
	v_mul_f32_e32 v19, v19, v174
	global_load_dword v117, v209, s[46:47]
	v_mul_f32_e32 v20, v20, v174
	v_mul_f32_e32 v21, v21, v174
	v_mul_f32_e32 v22, v22, v174
	s_add_u32 s66, s54, 3
	s_cmp_lt_u32 s66, s39
	s_cselect_b32 s75, 0xc0000, 0
	s_cselect_b32 s76, 0x280000, 0
	s_cselect_b32 s77, 0x4000, 0
	s_add_u32 s40, s40, s75
	s_addc_u32 s41, s41, 0
	s_add_u32 s42, s42, s76
	s_addc_u32 s43, s43, 0
	s_add_u32 s44, s44, s77
	s_addc_u32 s45, s45, 0
	s_add_u32 s46, s46, s77
	s_addc_u32 s47, s47, 0
	v_mul_f32_e32 v23, v23, v174
	s_waitcnt lgkmcnt(12)
	v_mfma_f32_16x16x32_bf16 v[8:11], v[96:99], v[112:115], v[8:11]
	s_waitcnt vmcnt(10)
	s_waitcnt lgkmcnt(10)
	v_mfma_f32_16x16x32_bf16 v[12:15], v[96:99], v[124:127], v[12:15]
	ds_write_b128 v213, v[156:159]
	v_mfma_f32_16x16x32_bf16 v[16:19], v[104:107], v[112:115], v[16:19]
	v_mfma_f32_16x16x32_bf16 v[20:23], v[104:107], v[124:127], v[20:23]
	ds_write_b128 v213, v[160:163] offset:8192
	s_waitcnt lgkmcnt(10)
	v_mfma_f32_16x16x32_bf16 v[8:11], v[100:103], v[120:123], v[8:11]
	s_waitcnt lgkmcnt(8)
; __device__ __forceinline__ void phase_ssd(const Params& P, int seg, unsigned char* smem) {
;     ...
; { const f32x4 a4 = *(const f32x4*)(acP + lt * 16 + fq * 4);
; #pragma unroll
;               for (int j = 0; j < 4; ++j) yo[j] *= __expf(a4[j]); }
;             const float acl_fr = acP[lt * 16 + fr]; const int lrow = lt * 16 + fr;
; #pragma unroll
;             for (int t = 0; t < 2; ++t) {
;                 if (2 * t <= lt) {
;                     v2u xb0, xb1;
;                     { const unsigned a0 = lds0 + par * T_BUF + T_XD + (32 * t + 4 * fq + tq) * 80 + (pt * 16 + 4 * tp) * 2, a1 = a0 + 16 * 80; TR_ISSUE(xb0, a0); TR_ISSUE(xb1, a1); }
;                     float m[8];
;                     { f32x4 s0 = {0.f, 0.f, 0.f, 0.f}, s1 = {0.f, 0.f, 0.f, 0.f};
; #pragma unroll
;                       for (int k = 0; k < 4; ++k) { const bf16x8 bf0 = *(const bf16x8*)(sb + T_BS + ((2 * t) * 16 + fr) * 272 + (k * 32 + fq * 8) * 2), bf1 = *(const bf16x8*)(sb + T_BS + ((2 * t + 1) * 16 + fr) * 272 + (k * 32 + fq * 8) * 2);
;                           s0 = mfma16(bf0, cf[k], s0); s1 = mfma16(bf1, cf[k], s1); }
;                       const f32x4 a0 = *(const f32x4*)(acP + (2 * t) * 16 + fq * 4), a1 = *(const f32x4*)(acP + (2 * t + 1) * 16 + fq * 4);
; #pragma unroll
;                       for (int j = 0; j < 4; ++j) { const int si0 = (2 * t) * 16 + fq * 4 + j, si1 = si0 + 16;
;                           const float e0 = s0[j] * __expf(fminf(acl_fr - a0[j], 0.f)), e1 = s1[j] * __expf(fminf(acl_fr - a1[j], 0.f));
;                           m[j] = (si0 <= lrow) ? e0 : 0.f; m[4 + j] = (si1 <= lrow) ? e1 : 0.f; } }
;                     v4u mp; mp.x = cvt_pk_bf16(m[0], m[1]); mp.y = cvt_pk_bf16(m[2], m[3]); mp.z = cvt_pk_bf16(m[4], m[5]); mp.w = cvt_pk_bf16(m[6], m[7]);
;                     asm volatile("s_waitcnt lgkmcnt(0)" : "+v"(xb0), "+v"(xb1) :: "memory");
;                     yo = mfma16(__builtin_bit_cast(bf16x8, mp), mk8(xb0, xb1), yo);
;                 }
;             }
; #pragma unroll
;             for (int j = 0; j < 4; ++j) { const int l = lt * 16 + fq * 4 + j, p = pt * 16 + fr; const float xv = bf2f(*(const bf16*)(sb + T_XS + l * 64 + p * 2)), zv = bf2f(*(const bf16*)(sb + T_ZS + l * 64 + p * 2));
;                 ypre[(size_t)(row0 + l) * DINNER + h * 64 + ph * 32 + p] = f2bfh((yo[j] + Dh * xv) * siluf_(zv)); }
;             { v2u xa[2][2][2], bb[2][2];
	v_mfma_f32_16x16x32_bf16 v[12:15], v[100:103], v[128:131], v[12:15]
	ds_write_b128 v213, v[148:151] offset:16384
	v_mfma_f32_16x16x32_bf16 v[16:19], v[108:111], v[120:123], v[16:19]
	ds_write_b128 v213, v[152:155] offset:24576
	v_mfma_f32_16x16x32_bf16 v[20:23], v[108:111], v[128:131], v[20:23]
	ds_read_b128 v[96:99], v232
	v_sub_f32_e32 v200, v169, v168
	ds_read_b64 v[124:125], v235 offset:43008
	v_mul_f32_e32 v200, 0x3fb8aa3b, v200
	ds_read_b64 v[126:127], v235 offset:47616
	s_waitcnt lgkmcnt(12)
	v_mfma_f32_16x16x32_bf16 v[48:51], v[64:67], v[28:31], 0
	v_exp_f32_e32 v200, v200
	s_waitcnt lgkmcnt(11)
	v_mfma_f32_16x16x32_bf16 v[48:51], v[68:71], v[32:35], v[48:51]
	v_lshlrev_b32_e32 v196, 16, v164
	s_waitcnt lgkmcnt(10)
	v_mfma_f32_16x16x32_bf16 v[48:51], v[72:75], v[40:43], v[48:51]
	s_waitcnt lgkmcnt(9)
	v_mfma_f32_16x16x32_bf16 v[48:51], v[76:79], v[44:47], v[48:51]
	v_and_b32_e32 v197, 0xffff0000, v164
	v_exp_f32_e32 v195, v194
	v_lshlrev_b32_e32 v198, 16, v165
	v_mul_f32_e32 v24, v24, v195
	v_mul_f32_e32 v25, v25, v195
	v_and_b32_e32 v199, 0xffff0000, v165
	v_mul_f32_e32 v26, v26, v195
	v_mul_f32_e32 v27, v27, v195
	v_mul_f32_e32 v196, v196, v118
	v_cvt_pk_bf16_f32 v184, v8, v9
	v_mul_f32_e32 v197, v197, v118
	v_cvt_pk_bf16_f32 v185, v10, v11
	v_cvt_pk_bf16_f32 v186, v12, v13
	v_mul_f32_e32 v198, v198, v118
	v_cvt_pk_bf16_f32 v187, v14, v15
	v_mul_f32_e32 v199, v199, v118
	v_cvt_pk_bf16_f32 v188, v16, v17
	v_cvt_pk_bf16_f32 v189, v18, v19
	v_cvt_pk_bf16_f32 v202, v196, v197
	v_cvt_pk_bf16_f32 v190, v20, v21
	v_cvt_pk_bf16_f32 v203, v198, v199
	v_cvt_pk_bf16_f32 v191, v22, v23
	ds_write_b64 v248, v[184:185] offset:8192
	ds_write_b64 v215, v[202:203] offset:32768
	ds_write_b64 v248, v[186:187] offset:12288
	v_mul_f32_e32 v196, v196, v200
	ds_write_b64 v249, v[188:189] offset:8192
	ds_write_b64 v249, v[190:191] offset:12288
	v_mul_f32_e32 v197, v197, v200
	s_waitcnt lgkmcnt(7)
	v_sub_f32_e32 v184, v194, v96
	v_mul_f32_e32 v198, v198, v200
	v_sub_f32_e32 v185, v194, v97
	v_sub_f32_e32 v186, v194, v98
	v_mul_f32_e32 v199, v199, v200
	v_sub_f32_e32 v187, v194, v99
	v_exp_f32_e32 v184, v184
	v_cvt_pk_bf16_f32 v192, v196, v197
	v_exp_f32_e32 v185, v185
	v_cvt_pk_bf16_f32 v193, v198, v199
	v_exp_f32_e32 v186, v186
	v_exp_f32_e32 v187, v187
	ds_write_b64 v215, v[192:193] offset:37888
	v_mul_f32_e32 v184, v48, v184
	ds_write_b64 v217, v[164:165] offset:43008
	v_mul_f32_e32 v185, v49, v185
	v_mul_f32_e32 v186, v50, v186
	ds_write_b64 v217, v[166:167] offset:47616
	v_mul_f32_e32 v187, v51, v187
	v_mul_f32_e32 v201, 0x3fb8aa3b, v168
	v_cndmask_b32_e64 v184, 0, v184, s[14:15]
	v_cndmask_b32_e64 v185, 0, v185, s[16:17]
	ds_write_b32 v218, v201 offset:256
	v_cndmask_b32_e64 v186, 0, v186, s[22:23]
	v_mul_f32_e32 v174, 0x3fb8aa3b, v169
	v_cndmask_b32_e64 v187, 0, v187, s[34:35]
	v_cvt_pk_bf16_f32 v184, v184, v185
	v_exp_f32_e32 v174, v174
	v_cvt_pk_bf16_f32 v185, v186, v187
	ds_write_b64 v250, v[184:185]
	s_waitcnt lgkmcnt(0)
	s_barrier
	ds_read_b128 v[128:131], v250
	v_lshlrev_b32_e32 v112, 16, v126
	v_and_b32_e32 v113, 0xffff0000, v126
	v_lshlrev_b32_e32 v114, 16, v127
	v_and_b32_e32 v115, 0xffff0000, v127
	v_mul_f32_e32 v120, 0xbfb8aa3b, v112
	v_mul_f32_e32 v121, 0xbfb8aa3b, v113
	v_mul_f32_e32 v122, 0xbfb8aa3b, v114
	v_mul_f32_e32 v123, 0xbfb8aa3b, v115
	v_exp_f32_e32 v120, v120
	v_exp_f32_e32 v121, v121
	v_exp_f32_e32 v122, v122
	v_exp_f32_e32 v123, v123
	v_add_f32_e32 v120, 1.0, v120
	v_add_f32_e32 v121, 1.0, v121
	v_add_f32_e32 v122, 1.0, v122
	v_add_f32_e32 v123, 1.0, v123
	v_rcp_f32_e32 v120, v120
	v_rcp_f32_e32 v121, v121
	v_rcp_f32_e32 v122, v122
	v_rcp_f32_e32 v123, v123
	v_mul_f32_e32 v112, v120, v112
	v_mul_f32_e32 v113, v121, v113
	v_mul_f32_e32 v114, v122, v114
	v_mul_f32_e32 v115, v123, v115
	v_lshlrev_b32_e32 v120, 16, v124
	v_and_b32_e32 v121, 0xffff0000, v124
	v_lshlrev_b32_e32 v122, 16, v125
	v_and_b32_e32 v123, 0xffff0000, v125
	s_waitcnt lgkmcnt(0)
	v_mfma_f32_16x16x32_bf16 v[24:27], v[56:59], v[128:131], v[24:27]
	s_mul_i32 s65, s56, 0x2000
	s_add_u32 s65, s65, 0x304f1000
	s_add_u32 s48, s0, s65
	s_addc_u32 s49, s1, 0
	s_nop 3
	v_fma_f32 v188, s61, v120, v24
	v_fma_f32 v189, s61, v121, v25
	v_fma_f32 v190, s61, v122, v26
	v_fma_f32 v191, s61, v123, v27
	v_mul_f32_e32 v188, v188, v112
	v_mul_f32_e32 v189, v189, v113
	v_mul_f32_e32 v190, v190, v114
	v_mul_f32_e32 v191, v191, v115
	v_cvt_pk_bf16_f32 v170, v188, v189
	v_cvt_pk_bf16_f32 v171, v190, v191
	global_store_dwordx2 v210, v[170:171], s[48:49]
	s_add_u32 s65, s54, 1
	s_sub_u32 s65, s65, s60
	s_lshl_b32 s65, s65, 6
	s_add_u32 s56, s65, s20
	s_add_u32 s54, s54, 1
	s_cmp_ge_u32 s54, s39
	s_cbranch_scc1 .Lssd_done
; __device__ __forceinline__ unsigned cvt_pk_bf16(float lo, float hi) { unsigned r; asm volatile("v_cvt_pk_bf16_f32 %0, %1, %2" : "=v"(r) : "v"(lo), "v"(hi)); return r; }
; __device__ __forceinline__ void phase_ssd(const Params& P, int seg, unsigned char* smem) {
;     ...
;             { const float e2 = __expf(R.alast - R.acl);
; #pragma unroll
;               for (int i = 0; i < 2; ++i) { const int q = tid + 512 * i, l = q >> 4, c8 = q & 15; *(v4u*)(sb + T_CS + l * 272 + c8 * 16) = R.Cr[i]; *(v4u*)(sb + T_BS + l * 272 + c8 * 16) = R.Br[i]; }
;               const int l = tid >> 3, p4 = (tid & 7) * 4;
;               const float x0 = bflo(R.Xr.x) * R.dtl, x1 = bfhi(R.Xr.x) * R.dtl, x2 = bflo(R.Xr.y) * R.dtl, x3 = bfhi(R.Xr.y) * R.dtl;
;               v2u d; d.x = cvt_pk_bf16(x0, x1); d.y = cvt_pk_bf16(x2, x3); *(v2u*)(sb + T_XD + l * 80 + p4 * 2) = d;
;               v2u e; e.x = cvt_pk_bf16(x0 * e2, x1 * e2); e.y = cvt_pk_bf16(x2 * e2, x3 * e2); *(v2u*)(sb + T_XE + l * 80 + p4 * 2) = e;
;               *(v2u*)(sb + T_XS + l * 64 + p4 * 2) = R.Xr; *(v2u*)(sb + T_ZS + l * 64 + p4 * 2) = R.Zr;
;               if (w == 0) acP[lane] = R.aclane; }
;             BAR_LDS();
;             if (ci + 2 < nchunks) load_chunk(ci + 2, R);
;             bf16x8 cf[4];
; #pragma unroll
;             for (int k = 0; k < 4; ++k) cf[k] = *(const bf16x8*)(sb + T_CS + (lt * 16 + fr) * 272 + (k * 32 + fq * 8) * 2);
;             f32x4 yo = {0.f, 0.f, 0.f, 0.f};
; #pragma unroll
;             for (int k = 0; k < 4; ++k) { const bf16x8 bb = *(const bf16x8*)((const unsigned char*)StR + (pt * 16 + fr) * 272 + (k * 32 + fq * 8) * 2); yo = mfma16(cf[k], bb, yo); }
; { const f32x4 a4 = *(const f32x4*)(acP + lt * 16 + fq * 4);
; #pragma unroll
;               for (int j = 0; j < 4; ++j) yo[j] *= __expf(a4[j]); }
;             const float acl_fr = acP[lt * 16 + fr]; const int lrow = lt * 16 + fr;
; #pragma unroll
;             for (int t = 0; t < 2; ++t) {
;                 if (2 * t <= lt) {
;                     v2u xb0, xb1;
;                     { const unsigned a0 = lds0 + par * T_BUF + T_XD + (32 * t + 4 * fq + tq) * 80 + (pt * 16 + 4 * tp) * 2, a1 = a0 + 16 * 80; TR_ISSUE(xb0, a0); TR_ISSUE(xb1, a1); }
;                     float m[8];
;                     { f32x4 s0 = {0.f, 0.f, 0.f, 0.f}, s1 = {0.f, 0.f, 0.f, 0.f};
; #pragma unroll
	ds_read_b128 v[28:31], v223
	ds_read_b128 v[32:35], v224
	ds_read_b128 v[40:43], v225
	ds_read_b128 v[44:47], v226
	ds_read_b128 v[48:51], v227 offset:8192
	ds_read_b128 v[52:55], v228 offset:8192
	ds_read_b128 v[56:59], v229 offset:8192
	ds_read_b128 v[60:63], v230 offset:8192
	ds_read_b32 v194, v231 offset:256
	ds_read_b64_tr_b16 v[96:97], v246 offset:16384
	ds_read_b64_tr_b16 v[98:99], v246 offset:20480
	ds_read_b64_tr_b16 v[100:101], v246 offset:24576
	ds_read_b64_tr_b16 v[102:103], v246 offset:28672
	ds_read_b64_tr_b16 v[104:105], v247 offset:16384
	ds_read_b64_tr_b16 v[106:107], v247 offset:20480
	s_waitcnt lgkmcnt(11)
	ds_read_b64_tr_b16 v[108:109], v247 offset:24576
	ds_read_b64_tr_b16 v[110:111], v247 offset:28672
	ds_read_b64_tr_b16 v[112:113], v243 offset:37888
	ds_read_b64_tr_b16 v[114:115], v243 offset:39168
	s_waitcnt lgkmcnt(11)
	ds_read_b64_tr_b16 v[124:125], v243 offset:37920
	ds_read_b64_tr_b16 v[126:127], v243 offset:39200
	ds_read_b64_tr_b16 v[120:121], v243 offset:40448
	ds_read_b64_tr_b16 v[122:123], v243 offset:41728
	global_load_dwordx4 v[156:159], v204, s[40:41] offset:2048
	s_waitcnt lgkmcnt(11)
	ds_read_b64_tr_b16 v[128:129], v243 offset:40480
	ds_read_b64_tr_b16 v[130:131], v243 offset:41760
	ds_read_b128 v[64:67], v223 offset:16384
	global_load_dwordx4 v[160:163], v205, s[40:41] offset:2048
	ds_read_b128 v[68:71], v224 offset:16384
	s_waitcnt lgkmcnt(11)
	ds_read_b128 v[72:75], v225 offset:16384
	ds_read_b128 v[76:79], v226 offset:16384
	global_load_dwordx4 v[148:151], v204, s[40:41]
	v_mfma_f32_16x16x32_bf16 v[24:27], v[48:51], v[28:31], 0
	v_mfma_f32_16x16x32_bf16 v[24:27], v[52:55], v[32:35], v[24:27]
	v_mfma_f32_16x16x32_bf16 v[24:27], v[56:59], v[40:43], v[24:27]
	global_load_dwordx4 v[152:155], v205, s[40:41]
	v_mfma_f32_16x16x32_bf16 v[24:27], v[60:63], v[44:47], v[24:27]
	ds_read_b64_tr_b16 v[56:57], v234 offset:32768
	ds_read_b64_tr_b16 v[58:59], v234 offset:34048
	global_load_dwordx2 v[164:165], v206, s[40:41]
	v_mul_f32_e32 v8, v8, v174
	v_mul_f32_e32 v9, v9, v174
	v_mul_f32_e32 v10, v10, v174
	global_load_dwordx2 v[166:167], v207, s[42:43] nt
	v_mul_f32_e32 v11, v11, v174
	v_mul_f32_e32 v12, v12, v174
	v_mul_f32_e32 v13, v13, v174
	global_load_dword v118, v208, s[44:45]
	v_mul_f32_e32 v14, v14, v174
	v_mul_f32_e32 v15, v15, v174
	v_mul_f32_e32 v16, v16, v174
	global_load_dword v168, v208, s[46:47]
	v_mul_f32_e32 v17, v17, v174
	v_mul_f32_e32 v18, v18, v174
	v_mul_f32_e32 v19, v19, v174
	global_load_dword v169, v209, s[46:47]
	v_mul_f32_e32 v20, v20, v174
	v_mul_f32_e32 v21, v21, v174
	v_mul_f32_e32 v22, v22, v174
	s_add_u32 s66, s54, 3
	s_cmp_lt_u32 s66, s39
	s_cselect_b32 s75, 0xc0000, 0
	s_cselect_b32 s76, 0x280000, 0
	s_cselect_b32 s77, 0x4000, 0
	s_add_u32 s40, s40, s75
	s_addc_u32 s41, s41, 0
	s_add_u32 s42, s42, s76
	s_addc_u32 s43, s43, 0
	s_add_u32 s44, s44, s77
	s_addc_u32 s45, s45, 0
	s_add_u32 s46, s46, s77
	s_addc_u32 s47, s47, 0
	v_mul_f32_e32 v23, v23, v174
	s_waitcnt lgkmcnt(12)
	v_mfma_f32_16x16x32_bf16 v[8:11], v[96:99], v[112:115], v[8:11]
	s_waitcnt vmcnt(10)
	s_waitcnt lgkmcnt(10)
	v_mfma_f32_16x16x32_bf16 v[12:15], v[96:99], v[124:127], v[12:15]
	ds_write_b128 v212, v[140:143]
	v_mfma_f32_16x16x32_bf16 v[16:19], v[104:107], v[112:115], v[16:19]
	v_mfma_f32_16x16x32_bf16 v[20:23], v[104:107], v[124:127], v[20:23]
	ds_write_b128 v212, v[144:147] offset:8192
	s_waitcnt lgkmcnt(10)
	v_mfma_f32_16x16x32_bf16 v[8:11], v[100:103], v[120:123], v[8:11]
	s_waitcnt lgkmcnt(8)
	v_mfma_f32_16x16x32_bf16 v[12:15], v[100:103], v[128:131], v[12:15]
	ds_write_b128 v212, v[132:135] offset:16384
	v_mfma_f32_16x16x32_bf16 v[16:19], v[108:111], v[120:123], v[16:19]
	ds_write_b128 v212, v[136:139] offset:24576
	v_mfma_f32_16x16x32_bf16 v[20:23], v[108:111], v[128:131], v[20:23]
	ds_read_b128 v[96:99], v232 offset:256
	v_sub_f32_e32 v200, v117, v116
	ds_read_b64 v[124:125], v236 offset:43008
	v_mul_f32_e32 v200, 0x3fb8aa3b, v200
	ds_read_b64 v[126:127], v236 offset:47616
	s_waitcnt lgkmcnt(12)
	v_mfma_f32_16x16x32_bf16 v[48:51], v[64:67], v[28:31], 0
	v_exp_f32_e32 v200, v200
	s_waitcnt lgkmcnt(11)
	v_mfma_f32_16x16x32_bf16 v[48:51], v[68:71], v[32:35], v[48:51]
	v_lshlrev_b32_e32 v196, 16, v4
	s_waitcnt lgkmcnt(10)
	v_mfma_f32_16x16x32_bf16 v[48:51], v[72:75], v[40:43], v[48:51]
	s_waitcnt lgkmcnt(9)
	v_mfma_f32_16x16x32_bf16 v[48:51], v[76:79], v[44:47], v[48:51]
	v_and_b32_e32 v197, 0xffff0000, v4
	v_exp_f32_e32 v195, v194
	v_lshlrev_b32_e32 v198, 16, v5
	v_mul_f32_e32 v24, v24, v195
	v_mul_f32_e32 v25, v25, v195
	v_and_b32_e32 v199, 0xffff0000, v5
	v_mul_f32_e32 v26, v26, v195
	v_mul_f32_e32 v27, v27, v195
	v_mul_f32_e32 v196, v196, v6
	v_cvt_pk_bf16_f32 v184, v8, v9
	v_mul_f32_e32 v197, v197, v6
	v_cvt_pk_bf16_f32 v185, v10, v11
	v_cvt_pk_bf16_f32 v186, v12, v13
	v_mul_f32_e32 v198, v198, v6
	v_cvt_pk_bf16_f32 v187, v14, v15
	v_mul_f32_e32 v199, v199, v6
	v_cvt_pk_bf16_f32 v188, v16, v17
	v_cvt_pk_bf16_f32 v189, v18, v19
	v_cvt_pk_bf16_f32 v202, v196, v197
	v_cvt_pk_bf16_f32 v190, v20, v21
	v_cvt_pk_bf16_f32 v203, v198, v199
	v_cvt_pk_bf16_f32 v191, v22, v23
	ds_write_b64 v248, v[184:185]
	ds_write_b64 v214, v[202:203] offset:32768
	ds_write_b64 v248, v[186:187] offset:4096
	v_mul_f32_e32 v196, v196, v200
	ds_write_b64 v249, v[188:189]
	ds_write_b64 v249, v[190:191] offset:4096
	v_mul_f32_e32 v197, v197, v200
	s_waitcnt lgkmcnt(7)
	v_sub_f32_e32 v184, v194, v96
	v_mul_f32_e32 v198, v198, v200
	v_sub_f32_e32 v185, v194, v97
	v_sub_f32_e32 v186, v194, v98
	v_mul_f32_e32 v199, v199, v200
	v_sub_f32_e32 v187, v194, v99
	v_exp_f32_e32 v184, v184
	v_cvt_pk_bf16_f32 v192, v196, v197
	v_exp_f32_e32 v185, v185
	v_cvt_pk_bf16_f32 v193, v198, v199
	v_exp_f32_e32 v186, v186
	v_exp_f32_e32 v187, v187
	ds_write_b64 v214, v[192:193] offset:37888
	v_mul_f32_e32 v184, v48, v184
	ds_write_b64 v216, v[4:5] offset:43008
	v_mul_f32_e32 v185, v49, v185
	v_mul_f32_e32 v186, v50, v186
	ds_write_b64 v216, v[36:37] offset:47616
	v_mul_f32_e32 v187, v51, v187
	v_mul_f32_e32 v201, 0x3fb8aa3b, v116
	v_cndmask_b32_e64 v184, 0, v184, s[14:15]
	v_cndmask_b32_e64 v185, 0, v185, s[16:17]
	ds_write_b32 v218, v201
	v_cndmask_b32_e64 v186, 0, v186, s[22:23]
	v_mul_f32_e32 v174, 0x3fb8aa3b, v117
	v_cndmask_b32_e64 v187, 0, v187, s[34:35]
	v_cvt_pk_bf16_f32 v184, v184, v185
	v_exp_f32_e32 v174, v174
	v_cvt_pk_bf16_f32 v185, v186, v187
	ds_write_b64 v250, v[184:185] offset:6144
	s_waitcnt lgkmcnt(0)
	s_barrier
; __device__ __forceinline__ unsigned cvt_pk_bf16(float lo, float hi) { unsigned r; asm volatile("v_cvt_pk_bf16_f32 %0, %1, %2" : "=v"(r) : "v"(lo), "v"(hi)); return r; }
; __device__ __forceinline__ void phase_ssd(const Params& P, int seg, unsigned char* smem) {
;     ...
;             { const float e2 = __expf(R.alast - R.acl);
; #pragma unroll
;               for (int i = 0; i < 2; ++i) { const int q = tid + 512 * i, l = q >> 4, c8 = q & 15; *(v4u*)(sb + T_CS + l * 272 + c8 * 16) = R.Cr[i]; *(v4u*)(sb + T_BS + l * 272 + c8 * 16) = R.Br[i]; }
;               const int l = tid >> 3, p4 = (tid & 7) * 4;
;               const float x0 = bflo(R.Xr.x) * R.dtl, x1 = bfhi(R.Xr.x) * R.dtl, x2 = bflo(R.Xr.y) * R.dtl, x3 = bfhi(R.Xr.y) * R.dtl;
;               v2u d; d.x = cvt_pk_bf16(x0, x1); d.y = cvt_pk_bf16(x2, x3); *(v2u*)(sb + T_XD + l * 80 + p4 * 2) = d;
;               v2u e; e.x = cvt_pk_bf16(x0 * e2, x1 * e2); e.y = cvt_pk_bf16(x2 * e2, x3 * e2); *(v2u*)(sb + T_XE + l * 80 + p4 * 2) = e;
;               *(v2u*)(sb + T_XS + l * 64 + p4 * 2) = R.Xr; *(v2u*)(sb + T_ZS + l * 64 + p4 * 2) = R.Zr;
;               if (w == 0) acP[lane] = R.aclane; }
;             BAR_LDS();
;             if (ci + 2 < nchunks) load_chunk(ci + 2, R);
;             bf16x8 cf[4];
; #pragma unroll
;             for (int k = 0; k < 4; ++k) cf[k] = *(const bf16x8*)(sb + T_CS + (lt * 16 + fr) * 272 + (k * 32 + fq * 8) * 2);
;             f32x4 yo = {0.f, 0.f, 0.f, 0.f};
; #pragma unroll
;             for (int k = 0; k < 4; ++k) { const bf16x8 bb = *(const bf16x8*)((const unsigned char*)StR + (pt * 16 + fr) * 272 + (k * 32 + fq * 8) * 2); yo = mfma16(cf[k], bb, yo); }
; { const f32x4 a4 = *(const f32x4*)(acP + lt * 16 + fq * 4);
; #pragma unroll
;               for (int j = 0; j < 4; ++j) yo[j] *= __expf(a4[j]); }
;             const float acl_fr = acP[lt * 16 + fr]; const int lrow = lt * 16 + fr;
; #pragma unroll
;             for (int t = 0; t < 2; ++t) {
;                 if (2 * t <= lt) {
;                     v2u xb0, xb1;
;                     { const unsigned a0 = lds0 + par * T_BUF + T_XD + (32 * t + 4 * fq + tq) * 80 + (pt * 16 + 4 * tp) * 2, a1 = a0 + 16 * 80; TR_ISSUE(xb0, a0); TR_ISSUE(xb1, a1); }
;                     float m[8];
;                     { f32x4 s0 = {0.f, 0.f, 0.f, 0.f}, s1 = {0.f, 0.f, 0.f, 0.f};
; #pragma unroll
	ds_read_b128 v[128:131], v250 offset:6144
	v_lshlrev_b32_e32 v112, 16, v126
	v_and_b32_e32 v113, 0xffff0000, v126
	v_lshlrev_b32_e32 v114, 16, v127
	v_and_b32_e32 v115, 0xffff0000, v127
	v_mul_f32_e32 v120, 0xbfb8aa3b, v112
	v_mul_f32_e32 v121, 0xbfb8aa3b, v113
	v_mul_f32_e32 v122, 0xbfb8aa3b, v114
	v_mul_f32_e32 v123, 0xbfb8aa3b, v115
	v_exp_f32_e32 v120, v120
	v_exp_f32_e32 v121, v121
	v_exp_f32_e32 v122, v122
	v_exp_f32_e32 v123, v123
	v_add_f32_e32 v120, 1.0, v120
	v_add_f32_e32 v121, 1.0, v121
	v_add_f32_e32 v122, 1.0, v122
	v_add_f32_e32 v123, 1.0, v123
	v_rcp_f32_e32 v120, v120
	v_rcp_f32_e32 v121, v121
	v_rcp_f32_e32 v122, v122
	v_rcp_f32_e32 v123, v123
	v_mul_f32_e32 v112, v120, v112
	v_mul_f32_e32 v113, v121, v113
	v_mul_f32_e32 v114, v122, v114
	v_mul_f32_e32 v115, v123, v115
	v_lshlrev_b32_e32 v120, 16, v124
	v_and_b32_e32 v121, 0xffff0000, v124
	v_lshlrev_b32_e32 v122, 16, v125
	v_and_b32_e32 v123, 0xffff0000, v125
	s_waitcnt lgkmcnt(0)
	v_mfma_f32_16x16x32_bf16 v[24:27], v[56:59], v[128:131], v[24:27]
	s_mul_i32 s65, s56, 0x2000
	s_add_u32 s65, s65, 0x304f1000
	s_add_u32 s48, s0, s65
	s_addc_u32 s49, s1, 0
	s_nop 3
	v_fma_f32 v188, s61, v120, v24
	v_fma_f32 v189, s61, v121, v25
	v_fma_f32 v190, s61, v122, v26
	v_fma_f32 v191, s61, v123, v27
	v_mul_f32_e32 v188, v188, v112
	v_mul_f32_e32 v189, v189, v113
	v_mul_f32_e32 v190, v190, v114
	v_mul_f32_e32 v191, v191, v115
	v_cvt_pk_bf16_f32 v170, v188, v189
	v_cvt_pk_bf16_f32 v171, v190, v191
	global_store_dwordx2 v210, v[170:171], s[48:49]
	s_add_u32 s65, s54, 1
	s_sub_u32 s65, s65, s60
	s_lshl_b32 s65, s65, 6
	s_add_u32 s56, s65, s20
	s_add_u32 s54, s54, 1
	s_cmp_lt_u32 s54, s39
	s_cbranch_scc1 .Lssd_loop00
	s_branch .Lssd_done
.Lssd_loop01:
	ds_read_b128 v[28:31], v219
	ds_read_b128 v[32:35], v220
	ds_read_b128 v[40:43], v221
	ds_read_b128 v[44:47], v222
	ds_read_b128 v[48:51], v227
	ds_read_b128 v[52:55], v228
	ds_read_b128 v[56:59], v229
	ds_read_b128 v[60:63], v230
	ds_read_b32 v194, v231
	ds_read_b64_tr_b16 v[96:97], v244 offset:16384
	ds_read_b64_tr_b16 v[98:99], v244 offset:20480
	ds_read_b64_tr_b16 v[100:101], v244 offset:24576
	ds_read_b64_tr_b16 v[102:103], v244 offset:28672
	ds_read_b64_tr_b16 v[104:105], v245 offset:16384
	ds_read_b64_tr_b16 v[106:107], v245 offset:20480
	s_waitcnt lgkmcnt(11)
	ds_read_b64_tr_b16 v[108:109], v245 offset:24576
	ds_read_b64_tr_b16 v[110:111], v245 offset:28672
	ds_read_b64_tr_b16 v[112:113], v237 offset:37888
	ds_read_b64_tr_b16 v[114:115], v237 offset:39168
	global_load_dwordx4 v[140:143], v204, s[40:41] offset:2048
	s_waitcnt lgkmcnt(11)
	ds_read_b64_tr_b16 v[124:125], v237 offset:37920
	ds_read_b64_tr_b16 v[126:127], v237 offset:39200
	global_load_dwordx4 v[144:147], v205, s[40:41] offset:2048
	ds_read_b64_tr_b16 v[120:121], v237 offset:40448
	ds_read_b64_tr_b16 v[122:123], v237 offset:41728
	global_load_dwordx4 v[132:135], v204, s[40:41]
	s_waitcnt lgkmcnt(11)
	ds_read_b64_tr_b16 v[128:129], v237 offset:40480
	ds_read_b64_tr_b16 v[130:131], v237 offset:41760
	global_load_dwordx4 v[136:139], v205, s[40:41]
	v_mfma_f32_16x16x32_bf16 v[24:27], v[48:51], v[28:31], 0
	v_mfma_f32_16x16x32_bf16 v[24:27], v[52:55], v[32:35], v[24:27]
	global_load_dwordx2 v[4:5], v206, s[40:41]
	v_mfma_f32_16x16x32_bf16 v[24:27], v[56:59], v[40:43], v[24:27]
	v_mfma_f32_16x16x32_bf16 v[24:27], v[60:63], v[44:47], v[24:27]
	global_load_dwordx2 v[36:37], v207, s[42:43] nt
	ds_read_b64_tr_b16 v[56:57], v233 offset:32768
	ds_read_b64_tr_b16 v[58:59], v233 offset:34048
	global_load_dword v6, v208, s[44:45]
	v_mul_f32_e32 v8, v8, v174
	v_mul_f32_e32 v9, v9, v174
	v_mul_f32_e32 v10, v10, v174
	global_load_dword v116, v208, s[46:47]
	v_mul_f32_e32 v11, v11, v174
	v_mul_f32_e32 v12, v12, v174
	global_load_dword v117, v209, s[46:47]
	v_mul_f32_e32 v13, v13, v174
	v_mul_f32_e32 v14, v14, v174
	s_add_u32 s66, s54, 3
	s_cmp_lt_u32 s66, s39
	s_cselect_b32 s75, 0xc0000, 0
	s_cselect_b32 s76, 0x280000, 0
	s_cselect_b32 s77, 0x4000, 0
	s_add_u32 s40, s40, s75
	s_addc_u32 s41, s41, 0
	s_add_u32 s42, s42, s76
	s_addc_u32 s43, s43, 0
	s_add_u32 s44, s44, s77
	s_addc_u32 s45, s45, 0
	s_add_u32 s46, s46, s77
	s_addc_u32 s47, s47, 0
	v_mul_f32_e32 v15, v15, v174
	s_waitcnt vmcnt(10)
	v_mul_f32_e32 v16, v16, v174
	s_waitcnt lgkmcnt(11)
	ds_write_b128 v213, v[156:159]
	v_mul_f32_e32 v17, v17, v174
	ds_write_b128 v213, v[160:163] offset:8192
	v_mul_f32_e32 v18, v18, v174
	ds_write_b128 v213, v[148:151] offset:16384
	v_mul_f32_e32 v19, v19, v174
	ds_write_b128 v213, v[152:155] offset:24576
	v_mul_f32_e32 v20, v20, v174
	v_sub_f32_e32 v200, v169, v168
	v_mul_f32_e32 v21, v21, v174
	v_mul_f32_e32 v200, 0x3fb8aa3b, v200
	v_mul_f32_e32 v22, v22, v174
	v_mul_f32_e32 v23, v23, v174
	v_exp_f32_e32 v200, v200
	s_waitcnt lgkmcnt(12)
	v_mfma_f32_16x16x32_bf16 v[8:11], v[96:99], v[112:115], v[8:11]
	v_lshlrev_b32_e32 v196, 16, v164
	s_waitcnt lgkmcnt(10)
	v_mfma_f32_16x16x32_bf16 v[12:15], v[96:99], v[124:127], v[12:15]
	v_and_b32_e32 v197, 0xffff0000, v164
	v_mfma_f32_16x16x32_bf16 v[16:19], v[104:107], v[112:115], v[16:19]
	v_lshlrev_b32_e32 v198, 16, v165
	v_mfma_f32_16x16x32_bf16 v[20:23], v[104:107], v[124:127], v[20:23]
	v_and_b32_e32 v199, 0xffff0000, v165
	s_waitcnt lgkmcnt(8)
	v_mfma_f32_16x16x32_bf16 v[8:11], v[100:103], v[120:123], v[8:11]
	v_mul_f32_e32 v196, v196, v118
	s_waitcnt lgkmcnt(6)
	v_mfma_f32_16x16x32_bf16 v[12:15], v[100:103], v[128:131], v[12:15]
	v_mul_f32_e32 v197, v197, v118
	v_mfma_f32_16x16x32_bf16 v[16:19], v[108:111], v[120:123], v[16:19]
	v_mul_f32_e32 v198, v198, v118
	v_mfma_f32_16x16x32_bf16 v[20:23], v[108:111], v[128:131], v[20:23]
	v_mul_f32_e32 v199, v199, v118
	ds_read_b64 v[124:125], v235 offset:43008
	v_cvt_pk_bf16_f32 v202, v196, v197
	ds_read_b64 v[126:127], v235 offset:47616
	v_cvt_pk_bf16_f32 v203, v198, v199
	v_exp_f32_e32 v195, v194
	ds_write_b64 v215, v[202:203] offset:32768
	v_mul_f32_e32 v24, v24, v195
	v_mul_f32_e32 v196, v196, v200
	v_mul_f32_e32 v25, v25, v195
	v_mul_f32_e32 v26, v26, v195
	v_mul_f32_e32 v197, v197, v200
	v_mul_f32_e32 v27, v27, v195
	v_mul_f32_e32 v198, v198, v200
	v_cvt_pk_bf16_f32 v184, v8, v9
	v_mul_f32_e32 v199, v199, v200
	v_cvt_pk_bf16_f32 v185, v10, v11
	v_cvt_pk_bf16_f32 v192, v196, v197
	v_cvt_pk_bf16_f32 v186, v12, v13
	v_cvt_pk_bf16_f32 v193, v198, v199
	v_cvt_pk_bf16_f32 v187, v14, v15
	ds_write_b64 v215, v[192:193] offset:37888
	v_cvt_pk_bf16_f32 v188, v16, v17
	ds_write_b64 v217, v[164:165] offset:43008
	v_cvt_pk_bf16_f32 v189, v18, v19
	ds_write_b64 v217, v[166:167] offset:47616
	v_cvt_pk_bf16_f32 v190, v20, v21
	v_mul_f32_e32 v201, 0x3fb8aa3b, v168
	v_cvt_pk_bf16_f32 v191, v22, v23
	ds_write_b32 v218, v201 offset:256
	ds_write_b64 v248, v[184:185] offset:8192
	v_mul_f32_e32 v174, 0x3fb8aa3b, v169
	ds_write_b64 v248, v[186:187] offset:12288
	v_exp_f32_e32 v174, v174
	s_waitcnt lgkmcnt(11)
	ds_write_b64 v249, v[188:189] offset:8192
	ds_write_b64 v249, v[190:191] offset:12288
	s_waitcnt lgkmcnt(0)
	s_barrier
; __device__ __forceinline__ void phase_ssd(const Params& P, int seg, unsigned char* smem) {
;     ...
; { const f32x4 a4 = *(const f32x4*)(acP + lt * 16 + fq * 4);
; #pragma unroll
;               for (int j = 0; j < 4; ++j) yo[j] *= __expf(a4[j]); }
;             const float acl_fr = acP[lt * 16 + fr]; const int lrow = lt * 16 + fr;
; #pragma unroll
;             for (int t = 0; t < 2; ++t) {
;                 if (2 * t <= lt) {
;                     v2u xb0, xb1;
;                     { const unsigned a0 = lds0 + par * T_BUF + T_XD + (32 * t + 4 * fq + tq) * 80 + (pt * 16 + 4 * tp) * 2, a1 = a0 + 16 * 80; TR_ISSUE(xb0, a0); TR_ISSUE(xb1, a1); }
;                     float m[8];
;                     { f32x4 s0 = {0.f, 0.f, 0.f, 0.f}, s1 = {0.f, 0.f, 0.f, 0.f};
; #pragma unroll
;                       for (int k = 0; k < 4; ++k) { const bf16x8 bf0 = *(const bf16x8*)(sb + T_BS + ((2 * t) * 16 + fr) * 272 + (k * 32 + fq * 8) * 2), bf1 = *(const bf16x8*)(sb + T_BS + ((2 * t + 1) * 16 + fr) * 272 + (k * 32 + fq * 8) * 2);
;                           s0 = mfma16(bf0, cf[k], s0); s1 = mfma16(bf1, cf[k], s1); }
;                       const f32x4 a0 = *(const f32x4*)(acP + (2 * t) * 16 + fq * 4), a1 = *(const f32x4*)(acP + (2 * t + 1) * 16 + fq * 4);
; #pragma unroll
;                       for (int j = 0; j < 4; ++j) { const int si0 = (2 * t) * 16 + fq * 4 + j, si1 = si0 + 16;
;                           const float e0 = s0[j] * __expf(fminf(acl_fr - a0[j], 0.f)), e1 = s1[j] * __expf(fminf(acl_fr - a1[j], 0.f));
;                           m[j] = (si0 <= lrow) ? e0 : 0.f; m[4 + j] = (si1 <= lrow) ? e1 : 0.f; } }
;                     v4u mp; mp.x = cvt_pk_bf16(m[0], m[1]); mp.y = cvt_pk_bf16(m[2], m[3]); mp.z = cvt_pk_bf16(m[4], m[5]); mp.w = cvt_pk_bf16(m[6], m[7]);
;                     asm volatile("s_waitcnt lgkmcnt(0)" : "+v"(xb0), "+v"(xb1) :: "memory");
;                     yo = mfma16(__builtin_bit_cast(bf16x8, mp), mk8(xb0, xb1), yo);
;                 }
;             }
; #pragma unroll
;             for (int j = 0; j < 4; ++j) { const int l = lt * 16 + fq * 4 + j, p = pt * 16 + fr; const float xv = bf2f(*(const bf16*)(sb + T_XS + l * 64 + p * 2)), zv = bf2f(*(const bf16*)(sb + T_ZS + l * 64 + p * 2));
;                 ypre[(size_t)(row0 + l) * DINNER + h * 64 + ph * 32 + p] = f2bfh((yo[j] + Dh * xv) * siluf_(zv)); }
;             { v2u xa[2][2][2], bb[2][2];
	ds_read_b128 v[128:131], v250
	v_lshlrev_b32_e32 v112, 16, v126
	v_and_b32_e32 v113, 0xffff0000, v126
	v_lshlrev_b32_e32 v114, 16, v127
	v_and_b32_e32 v115, 0xffff0000, v127
	v_mul_f32_e32 v120, 0xbfb8aa3b, v112
	v_mul_f32_e32 v121, 0xbfb8aa3b, v113
	v_mul_f32_e32 v122, 0xbfb8aa3b, v114
	v_mul_f32_e32 v123, 0xbfb8aa3b, v115
	v_exp_f32_e32 v120, v120
	v_exp_f32_e32 v121, v121
	v_exp_f32_e32 v122, v122
	v_exp_f32_e32 v123, v123
	v_add_f32_e32 v120, 1.0, v120
	v_add_f32_e32 v121, 1.0, v121
	v_add_f32_e32 v122, 1.0, v122
	v_add_f32_e32 v123, 1.0, v123
	v_rcp_f32_e32 v120, v120
	v_rcp_f32_e32 v121, v121
	v_rcp_f32_e32 v122, v122
	v_rcp_f32_e32 v123, v123
	v_mul_f32_e32 v112, v120, v112
	v_mul_f32_e32 v113, v121, v113
	v_mul_f32_e32 v114, v122, v114
	v_mul_f32_e32 v115, v123, v115
	v_lshlrev_b32_e32 v120, 16, v124
	v_and_b32_e32 v121, 0xffff0000, v124
	v_lshlrev_b32_e32 v122, 16, v125
	v_and_b32_e32 v123, 0xffff0000, v125
	s_waitcnt lgkmcnt(0)
	v_mfma_f32_16x16x32_bf16 v[24:27], v[56:59], v[128:131], v[24:27]
	s_mul_i32 s65, s56, 0x2000
	s_add_u32 s65, s65, 0x304f1000
	s_add_u32 s48, s0, s65
	s_addc_u32 s49, s1, 0
	s_nop 3
	v_fma_f32 v188, s61, v120, v24
	v_fma_f32 v189, s61, v121, v25
	v_fma_f32 v190, s61, v122, v26
	v_fma_f32 v191, s61, v123, v27
	v_mul_f32_e32 v188, v188, v112
	v_mul_f32_e32 v189, v189, v113
	v_mul_f32_e32 v190, v190, v114
	v_mul_f32_e32 v191, v191, v115
	v_cvt_pk_bf16_f32 v170, v188, v189
	v_cvt_pk_bf16_f32 v171, v190, v191
	global_store_dwordx2 v210, v[170:171], s[48:49]
	s_add_u32 s65, s54, 1
	s_sub_u32 s65, s65, s60
	s_lshl_b32 s65, s65, 6
	s_add_u32 s56, s65, s20
	s_add_u32 s54, s54, 1
	s_cmp_ge_u32 s54, s39
	s_cbranch_scc1 .Lssd_done
	ds_read_b128 v[28:31], v223
	ds_read_b128 v[32:35], v224
	ds_read_b128 v[40:43], v225
	ds_read_b128 v[44:47], v226
	ds_read_b128 v[48:51], v227 offset:8192
	ds_read_b128 v[52:55], v228 offset:8192
	ds_read_b128 v[56:59], v229 offset:8192
	ds_read_b128 v[60:63], v230 offset:8192
	ds_read_b32 v194, v231 offset:256
	ds_read_b64_tr_b16 v[96:97], v246 offset:16384
	ds_read_b64_tr_b16 v[98:99], v246 offset:20480
	ds_read_b64_tr_b16 v[100:101], v246 offset:24576
	ds_read_b64_tr_b16 v[102:103], v246 offset:28672
	ds_read_b64_tr_b16 v[104:105], v247 offset:16384
	ds_read_b64_tr_b16 v[106:107], v247 offset:20480
	s_waitcnt lgkmcnt(11)
	ds_read_b64_tr_b16 v[108:109], v247 offset:24576
	ds_read_b64_tr_b16 v[110:111], v247 offset:28672
	ds_read_b64_tr_b16 v[112:113], v243 offset:37888
	ds_read_b64_tr_b16 v[114:115], v243 offset:39168
	global_load_dwordx4 v[156:159], v204, s[40:41] offset:2048
	s_waitcnt lgkmcnt(11)
	ds_read_b64_tr_b16 v[124:125], v243 offset:37920
	ds_read_b64_tr_b16 v[126:127], v243 offset:39200
	global_load_dwordx4 v[160:163], v205, s[40:41] offset:2048
	ds_read_b64_tr_b16 v[120:121], v243 offset:40448
	ds_read_b64_tr_b16 v[122:123], v243 offset:41728
	global_load_dwordx4 v[148:151], v204, s[40:41]
	s_waitcnt lgkmcnt(11)
	ds_read_b64_tr_b16 v[128:129], v243 offset:40480
	ds_read_b64_tr_b16 v[130:131], v243 offset:41760
	global_load_dwordx4 v[152:155], v205, s[40:41]
	v_mfma_f32_16x16x32_bf16 v[24:27], v[48:51], v[28:31], 0
	v_mfma_f32_16x16x32_bf16 v[24:27], v[52:55], v[32:35], v[24:27]
	global_load_dwordx2 v[164:165], v206, s[40:41]
	v_mfma_f32_16x16x32_bf16 v[24:27], v[56:59], v[40:43], v[24:27]
	v_mfma_f32_16x16x32_bf16 v[24:27], v[60:63], v[44:47], v[24:27]
	global_load_dwordx2 v[166:167], v207, s[42:43] nt
	ds_read_b64_tr_b16 v[56:57], v234 offset:32768
	ds_read_b64_tr_b16 v[58:59], v234 offset:34048
	global_load_dword v118, v208, s[44:45]
	v_mul_f32_e32 v8, v8, v174
	v_mul_f32_e32 v9, v9, v174
	v_mul_f32_e32 v10, v10, v174
	global_load_dword v168, v208, s[46:47]
	v_mul_f32_e32 v11, v11, v174
	v_mul_f32_e32 v12, v12, v174
	global_load_dword v169, v209, s[46:47]
	v_mul_f32_e32 v13, v13, v174
	v_mul_f32_e32 v14, v14, v174
	s_add_u32 s66, s54, 3
	s_cmp_lt_u32 s66, s39
	s_cselect_b32 s75, 0xc0000, 0
	s_cselect_b32 s76, 0x280000, 0
	s_cselect_b32 s77, 0x4000, 0
	s_add_u32 s40, s40, s75
	s_addc_u32 s41, s41, 0
	s_add_u32 s42, s42, s76
	s_addc_u32 s43, s43, 0
	s_add_u32 s44, s44, s77
	s_addc_u32 s45, s45, 0
	s_add_u32 s46, s46, s77
	s_addc_u32 s47, s47, 0
	v_mul_f32_e32 v15, v15, v174
	s_waitcnt vmcnt(10)
	v_mul_f32_e32 v16, v16, v174
	s_waitcnt lgkmcnt(11)
	ds_write_b128 v212, v[140:143]
	v_mul_f32_e32 v17, v17, v174
	ds_write_b128 v212, v[144:147] offset:8192
	v_mul_f32_e32 v18, v18, v174
	ds_write_b128 v212, v[132:135] offset:16384
	v_mul_f32_e32 v19, v19, v174
	ds_write_b128 v212, v[136:139] offset:24576
	v_mul_f32_e32 v20, v20, v174
	v_sub_f32_e32 v200, v117, v116
	v_mul_f32_e32 v21, v21, v174
	v_mul_f32_e32 v200, 0x3fb8aa3b, v200
	v_mul_f32_e32 v22, v22, v174
	v_mul_f32_e32 v23, v23, v174
	v_exp_f32_e32 v200, v200
	s_waitcnt lgkmcnt(12)
	v_mfma_f32_16x16x32_bf16 v[8:11], v[96:99], v[112:115], v[8:11]
	v_lshlrev_b32_e32 v196, 16, v4
	s_waitcnt lgkmcnt(10)
	v_mfma_f32_16x16x32_bf16 v[12:15], v[96:99], v[124:127], v[12:15]
	v_and_b32_e32 v197, 0xffff0000, v4
	v_mfma_f32_16x16x32_bf16 v[16:19], v[104:107], v[112:115], v[16:19]
	v_lshlrev_b32_e32 v198, 16, v5
	v_mfma_f32_16x16x32_bf16 v[20:23], v[104:107], v[124:127], v[20:23]
	v_and_b32_e32 v199, 0xffff0000, v5
	s_waitcnt lgkmcnt(8)
	v_mfma_f32_16x16x32_bf16 v[8:11], v[100:103], v[120:123], v[8:11]
	v_mul_f32_e32 v196, v196, v6
	s_waitcnt lgkmcnt(6)
	v_mfma_f32_16x16x32_bf16 v[12:15], v[100:103], v[128:131], v[12:15]
	v_mul_f32_e32 v197, v197, v6
	v_mfma_f32_16x16x32_bf16 v[16:19], v[108:111], v[120:123], v[16:19]
	v_mul_f32_e32 v198, v198, v6
	v_mfma_f32_16x16x32_bf16 v[20:23], v[108:111], v[128:131], v[20:23]
	v_mul_f32_e32 v199, v199, v6
	ds_read_b64 v[124:125], v236 offset:43008
	v_cvt_pk_bf16_f32 v202, v196, v197
	ds_read_b64 v[126:127], v236 offset:47616
	v_cvt_pk_bf16_f32 v203, v198, v199
	v_exp_f32_e32 v195, v194
	ds_write_b64 v214, v[202:203] offset:32768
	v_mul_f32_e32 v24, v24, v195
	v_mul_f32_e32 v196, v196, v200
	v_mul_f32_e32 v25, v25, v195
	v_mul_f32_e32 v26, v26, v195
	v_mul_f32_e32 v197, v197, v200
	v_mul_f32_e32 v27, v27, v195
	v_mul_f32_e32 v198, v198, v200
	v_cvt_pk_bf16_f32 v184, v8, v9
	v_mul_f32_e32 v199, v199, v200
	v_cvt_pk_bf16_f32 v185, v10, v11
	v_cvt_pk_bf16_f32 v192, v196, v197
	v_cvt_pk_bf16_f32 v186, v12, v13
	v_cvt_pk_bf16_f32 v193, v198, v199
	v_cvt_pk_bf16_f32 v187, v14, v15
	ds_write_b64 v214, v[192:193] offset:37888
	v_cvt_pk_bf16_f32 v188, v16, v17
	ds_write_b64 v216, v[4:5] offset:43008
	v_cvt_pk_bf16_f32 v189, v18, v19
	ds_write_b64 v216, v[36:37] offset:47616
	v_cvt_pk_bf16_f32 v190, v20, v21
	v_mul_f32_e32 v201, 0x3fb8aa3b, v116
	v_cvt_pk_bf16_f32 v191, v22, v23
	ds_write_b32 v218, v201
	ds_write_b64 v248, v[184:185]
	v_mul_f32_e32 v174, 0x3fb8aa3b, v117
	ds_write_b64 v248, v[186:187] offset:4096
	v_exp_f32_e32 v174, v174
	s_waitcnt lgkmcnt(11)
	ds_write_b64 v249, v[188:189]
	ds_write_b64 v249, v[190:191] offset:4096
	s_waitcnt lgkmcnt(0)
	s_barrier
; __device__ __forceinline__ unsigned cvt_pk_bf16(float lo, float hi) { unsigned r; asm volatile("v_cvt_pk_bf16_f32 %0, %1, %2" : "=v"(r) : "v"(lo), "v"(hi)); return r; }
; __device__ __forceinline__ void phase_ssd(const Params& P, int seg, unsigned char* smem) {
;     ...
;             { const float e2 = __expf(R.alast - R.acl);
; #pragma unroll
;               for (int i = 0; i < 2; ++i) { const int q = tid + 512 * i, l = q >> 4, c8 = q & 15; *(v4u*)(sb + T_CS + l * 272 + c8 * 16) = R.Cr[i]; *(v4u*)(sb + T_BS + l * 272 + c8 * 16) = R.Br[i]; }
;               const int l = tid >> 3, p4 = (tid & 7) * 4;
;               const float x0 = bflo(R.Xr.x) * R.dtl, x1 = bfhi(R.Xr.x) * R.dtl, x2 = bflo(R.Xr.y) * R.dtl, x3 = bfhi(R.Xr.y) * R.dtl;
;               v2u d; d.x = cvt_pk_bf16(x0, x1); d.y = cvt_pk_bf16(x2, x3); *(v2u*)(sb + T_XD + l * 80 + p4 * 2) = d;
;               v2u e; e.x = cvt_pk_bf16(x0 * e2, x1 * e2); e.y = cvt_pk_bf16(x2 * e2, x3 * e2); *(v2u*)(sb + T_XE + l * 80 + p4 * 2) = e;
;               *(v2u*)(sb + T_XS + l * 64 + p4 * 2) = R.Xr; *(v2u*)(sb + T_ZS + l * 64 + p4 * 2) = R.Zr;
;               if (w == 0) acP[lane] = R.aclane; }
;             BAR_LDS();
;             if (ci + 2 < nchunks) load_chunk(ci + 2, R);
;             bf16x8 cf[4];
; #pragma unroll
;             for (int k = 0; k < 4; ++k) cf[k] = *(const bf16x8*)(sb + T_CS + (lt * 16 + fr) * 272 + (k * 32 + fq * 8) * 2);
;             f32x4 yo = {0.f, 0.f, 0.f, 0.f};
; #pragma unroll
;             for (int k = 0; k < 4; ++k) { const bf16x8 bb = *(const bf16x8*)((const unsigned char*)StR + (pt * 16 + fr) * 272 + (k * 32 + fq * 8) * 2); yo = mfma16(cf[k], bb, yo); }
; { const f32x4 a4 = *(const f32x4*)(acP + lt * 16 + fq * 4);
; #pragma unroll
;               for (int j = 0; j < 4; ++j) yo[j] *= __expf(a4[j]); }
;             const float acl_fr = acP[lt * 16 + fr]; const int lrow = lt * 16 + fr;
; #pragma unroll
;             for (int t = 0; t < 2; ++t) {
;                 if (2 * t <= lt) {
;                     v2u xb0, xb1;
;                     { const unsigned a0 = lds0 + par * T_BUF + T_XD + (32 * t + 4 * fq + tq) * 80 + (pt * 16 + 4 * tp) * 2, a1 = a0 + 16 * 80; TR_ISSUE(xb0, a0); TR_ISSUE(xb1, a1); }
;                     float m[8];
;                     { f32x4 s0 = {0.f, 0.f, 0.f, 0.f}, s1 = {0.f, 0.f, 0.f, 0.f};
; #pragma unroll
	ds_read_b128 v[128:131], v250 offset:6144
	v_lshlrev_b32_e32 v112, 16, v126
	v_and_b32_e32 v113, 0xffff0000, v126
	v_lshlrev_b32_e32 v114, 16, v127
	v_and_b32_e32 v115, 0xffff0000, v127
	v_mul_f32_e32 v120, 0xbfb8aa3b, v112
	v_mul_f32_e32 v121, 0xbfb8aa3b, v113
	v_mul_f32_e32 v122, 0xbfb8aa3b, v114
	v_mul_f32_e32 v123, 0xbfb8aa3b, v115
	v_exp_f32_e32 v120, v120
	v_exp_f32_e32 v121, v121
	v_exp_f32_e32 v122, v122
	v_exp_f32_e32 v123, v123
	v_add_f32_e32 v120, 1.0, v120
	v_add_f32_e32 v121, 1.0, v121
	v_add_f32_e32 v122, 1.0, v122
	v_add_f32_e32 v123, 1.0, v123
	v_rcp_f32_e32 v120, v120
	v_rcp_f32_e32 v121, v121
	v_rcp_f32_e32 v122, v122
	v_rcp_f32_e32 v123, v123
	v_mul_f32_e32 v112, v120, v112
	v_mul_f32_e32 v113, v121, v113
	v_mul_f32_e32 v114, v122, v114
	v_mul_f32_e32 v115, v123, v115
	v_lshlrev_b32_e32 v120, 16, v124
	v_and_b32_e32 v121, 0xffff0000, v124
	v_lshlrev_b32_e32 v122, 16, v125
	v_and_b32_e32 v123, 0xffff0000, v125
	s_waitcnt lgkmcnt(0)
	v_mfma_f32_16x16x32_bf16 v[24:27], v[56:59], v[128:131], v[24:27]
	s_mul_i32 s65, s56, 0x2000
	s_add_u32 s65, s65, 0x304f1000
	s_add_u32 s48, s0, s65
	s_addc_u32 s49, s1, 0
	s_nop 3
	v_fma_f32 v188, s61, v120, v24
	v_fma_f32 v189, s61, v121, v25
	v_fma_f32 v190, s61, v122, v26
	v_fma_f32 v191, s61, v123, v27
	v_mul_f32_e32 v188, v188, v112
	v_mul_f32_e32 v189, v189, v113
	v_mul_f32_e32 v190, v190, v114
	v_mul_f32_e32 v191, v191, v115
	v_cvt_pk_bf16_f32 v170, v188, v189
	v_cvt_pk_bf16_f32 v171, v190, v191
	global_store_dwordx2 v210, v[170:171], s[48:49]
	s_add_u32 s65, s54, 1
	s_sub_u32 s65, s65, s60
	s_lshl_b32 s65, s65, 6
	s_add_u32 s56, s65, s20
	s_add_u32 s54, s54, 1
	s_cmp_lt_u32 s54, s39
	s_cbranch_scc1 .Lssd_loop01
	s_branch .Lssd_done
.Lssd_loop10:
	ds_read_b128 v[28:31], v219 offset:4096
	ds_read_b128 v[32:35], v220 offset:4096
	ds_read_b128 v[40:43], v221 offset:4096
	ds_read_b128 v[44:47], v222 offset:4096
	ds_read_b128 v[48:51], v227
	ds_read_b128 v[52:55], v228
	ds_read_b128 v[56:59], v229
	ds_read_b128 v[60:63], v230
	ds_read_b32 v194, v231 offset:64
	ds_read_b64_tr_b16 v[96:97], v244 offset:16384
	ds_read_b64_tr_b16 v[98:99], v244 offset:20480
	ds_read_b64_tr_b16 v[100:101], v244 offset:24576
	ds_read_b64_tr_b16 v[102:103], v244 offset:28672
	ds_read_b64_tr_b16 v[104:105], v245 offset:16384
	ds_read_b64_tr_b16 v[106:107], v245 offset:20480
	s_waitcnt lgkmcnt(11)
	ds_read_b64_tr_b16 v[108:109], v245 offset:24576
	ds_read_b64_tr_b16 v[110:111], v245 offset:28672
	ds_read_b64_tr_b16 v[112:113], v237 offset:37888
	ds_read_b64_tr_b16 v[114:115], v237 offset:39168
	s_waitcnt lgkmcnt(11)
	ds_read_b64_tr_b16 v[124:125], v237 offset:37920
	ds_read_b64_tr_b16 v[126:127], v237 offset:39200
	ds_read_b64_tr_b16 v[120:121], v237 offset:40448
	ds_read_b64_tr_b16 v[122:123], v237 offset:41728
	global_load_dwordx4 v[140:143], v204, s[40:41] offset:2048
	s_waitcnt lgkmcnt(11)
	ds_read_b64_tr_b16 v[128:129], v237 offset:40480
	ds_read_b64_tr_b16 v[130:131], v237 offset:41760
	global_load_dwordx4 v[144:147], v205, s[40:41] offset:2048
	ds_read_b128 v[64:67], v219 offset:16384
	ds_read_b128 v[68:71], v220 offset:16384
	s_waitcnt lgkmcnt(11)
	ds_read_b128 v[72:75], v221 offset:16384
	global_load_dwordx4 v[132:135], v204, s[40:41]
	ds_read_b128 v[76:79], v222 offset:16384
	v_mfma_f32_16x16x32_bf16 v[24:27], v[48:51], v[28:31], 0
	v_mfma_f32_16x16x32_bf16 v[24:27], v[52:55], v[32:35], v[24:27]
	global_load_dwordx4 v[136:139], v205, s[40:41]
	v_mfma_f32_16x16x32_bf16 v[24:27], v[56:59], v[40:43], v[24:27]
	v_mfma_f32_16x16x32_bf16 v[24:27], v[60:63], v[44:47], v[24:27]
	ds_read_b64_tr_b16 v[56:57], v233 offset:32768
	global_load_dwordx2 v[4:5], v206, s[40:41]
	ds_read_b64_tr_b16 v[58:59], v233 offset:34048
	v_mul_f32_e32 v8, v8, v174
	v_mul_f32_e32 v9, v9, v174
	global_load_dwordx2 v[36:37], v207, s[42:43] nt
	v_mul_f32_e32 v10, v10, v174
	v_mul_f32_e32 v11, v11, v174
	v_mul_f32_e32 v12, v12, v174
	global_load_dword v6, v208, s[44:45]
	v_mul_f32_e32 v13, v13, v174
	v_mul_f32_e32 v14, v14, v174
	v_mul_f32_e32 v15, v15, v174
	global_load_dword v116, v208, s[46:47]
	v_mul_f32_e32 v16, v16, v174
	v_mul_f32_e32 v17, v17, v174
	v_mul_f32_e32 v18, v18, v174
	global_load_dword v117, v209, s[46:47]
	v_mul_f32_e32 v19, v19, v174
	v_mul_f32_e32 v20, v20, v174
	v_mul_f32_e32 v21, v21, v174
	s_add_u32 s66, s54, 3
	s_cmp_lt_u32 s66, s39
	s_cselect_b32 s75, 0xc0000, 0
	s_cselect_b32 s76, 0x280000, 0
	s_cselect_b32 s77, 0x4000, 0
	s_add_u32 s40, s40, s75
	s_addc_u32 s41, s41, 0
	s_add_u32 s42, s42, s76
	s_addc_u32 s43, s43, 0
	s_add_u32 s44, s44, s77
	s_addc_u32 s45, s45, 0
	s_add_u32 s46, s46, s77
	s_addc_u32 s47, s47, 0
	v_mul_f32_e32 v22, v22, v174
	s_waitcnt vmcnt(10)
	v_mul_f32_e32 v23, v23, v174
	s_waitcnt lgkmcnt(12)
	v_mfma_f32_16x16x32_bf16 v[8:11], v[96:99], v[112:115], v[8:11]
	ds_write_b128 v213, v[156:159]
	s_waitcnt lgkmcnt(11)
	v_mfma_f32_16x16x32_bf16 v[12:15], v[96:99], v[124:127], v[12:15]
	ds_write_b128 v213, v[160:163] offset:8192
	v_mfma_f32_16x16x32_bf16 v[16:19], v[104:107], v[112:115], v[16:19]
	v_mfma_f32_16x16x32_bf16 v[20:23], v[104:107], v[124:127], v[20:23]
	ds_write_b128 v213, v[148:151] offset:16384
	s_waitcnt lgkmcnt(11)
	v_mfma_f32_16x16x32_bf16 v[8:11], v[100:103], v[120:123], v[8:11]
	ds_write_b128 v213, v[152:155] offset:24576
	s_waitcnt lgkmcnt(10)
	v_mfma_f32_16x16x32_bf16 v[12:15], v[100:103], v[128:131], v[12:15]
	v_mfma_f32_16x16x32_bf16 v[16:19], v[108:111], v[120:123], v[16:19]
	v_sub_f32_e32 v200, v169, v168
	v_mfma_f32_16x16x32_bf16 v[20:23], v[108:111], v[128:131], v[20:23]
	v_mul_f32_e32 v200, 0x3fb8aa3b, v200
	ds_read_b128 v[96:99], v232
	ds_read_b64 v[124:125], v235 offset:44160
	v_exp_f32_e32 v200, v200
	ds_read_b64 v[126:127], v235 offset:48768
	v_lshlrev_b32_e32 v196, 16, v164
	s_waitcnt lgkmcnt(12)
; __device__ __forceinline__ void phase_ssd(const Params& P, int seg, unsigned char* smem) {
;     ...
; { const f32x4 a4 = *(const f32x4*)(acP + lt * 16 + fq * 4);
; #pragma unroll
;               for (int j = 0; j < 4; ++j) yo[j] *= __expf(a4[j]); }
;             const float acl_fr = acP[lt * 16 + fr]; const int lrow = lt * 16 + fr;
; #pragma unroll
;             for (int t = 0; t < 2; ++t) {
;                 if (2 * t <= lt) {
;                     v2u xb0, xb1;
;                     { const unsigned a0 = lds0 + par * T_BUF + T_XD + (32 * t + 4 * fq + tq) * 80 + (pt * 16 + 4 * tp) * 2, a1 = a0 + 16 * 80; TR_ISSUE(xb0, a0); TR_ISSUE(xb1, a1); }
;                     float m[8];
;                     { f32x4 s0 = {0.f, 0.f, 0.f, 0.f}, s1 = {0.f, 0.f, 0.f, 0.f};
; #pragma unroll
;                       for (int k = 0; k < 4; ++k) { const bf16x8 bf0 = *(const bf16x8*)(sb + T_BS + ((2 * t) * 16 + fr) * 272 + (k * 32 + fq * 8) * 2), bf1 = *(const bf16x8*)(sb + T_BS + ((2 * t + 1) * 16 + fr) * 272 + (k * 32 + fq * 8) * 2);
;                           s0 = mfma16(bf0, cf[k], s0); s1 = mfma16(bf1, cf[k], s1); }
;                       const f32x4 a0 = *(const f32x4*)(acP + (2 * t) * 16 + fq * 4), a1 = *(const f32x4*)(acP + (2 * t + 1) * 16 + fq * 4);
; #pragma unroll
;                       for (int j = 0; j < 4; ++j) { const int si0 = (2 * t) * 16 + fq * 4 + j, si1 = si0 + 16;
;                           const float e0 = s0[j] * __expf(fminf(acl_fr - a0[j], 0.f)), e1 = s1[j] * __expf(fminf(acl_fr - a1[j], 0.f));
;                           m[j] = (si0 <= lrow) ? e0 : 0.f; m[4 + j] = (si1 <= lrow) ? e1 : 0.f; } }
;                     v4u mp; mp.x = cvt_pk_bf16(m[0], m[1]); mp.y = cvt_pk_bf16(m[2], m[3]); mp.z = cvt_pk_bf16(m[4], m[5]); mp.w = cvt_pk_bf16(m[6], m[7]);
;                     asm volatile("s_waitcnt lgkmcnt(0)" : "+v"(xb0), "+v"(xb1) :: "memory");
;                     yo = mfma16(__builtin_bit_cast(bf16x8, mp), mk8(xb0, xb1), yo);
;                 }
;             }
; #pragma unroll
;             for (int j = 0; j < 4; ++j) { const int l = lt * 16 + fq * 4 + j, p = pt * 16 + fr; const float xv = bf2f(*(const bf16*)(sb + T_XS + l * 64 + p * 2)), zv = bf2f(*(const bf16*)(sb + T_ZS + l * 64 + p * 2));
;                 ypre[(size_t)(row0 + l) * DINNER + h * 64 + ph * 32 + p] = f2bfh((yo[j] + Dh * xv) * siluf_(zv)); }
;             { v2u xa[2][2][2], bb[2][2];
	v_mfma_f32_16x16x32_bf16 v[48:51], v[64:67], v[28:31], 0
	s_waitcnt lgkmcnt(11)
	v_mfma_f32_16x16x32_bf16 v[48:51], v[68:71], v[32:35], v[48:51]
	v_and_b32_e32 v197, 0xffff0000, v164
	s_waitcnt lgkmcnt(10)
	v_mfma_f32_16x16x32_bf16 v[48:51], v[72:75], v[40:43], v[48:51]
	v_lshlrev_b32_e32 v198, 16, v165
	s_waitcnt lgkmcnt(9)
	v_mfma_f32_16x16x32_bf16 v[48:51], v[76:79], v[44:47], v[48:51]
	v_exp_f32_e32 v195, v194
	v_and_b32_e32 v199, 0xffff0000, v165
	v_mul_f32_e32 v24, v24, v195
	v_mul_f32_e32 v196, v196, v118
	v_mul_f32_e32 v25, v25, v195
	v_mul_f32_e32 v26, v26, v195
	v_mul_f32_e32 v197, v197, v118
	v_mul_f32_e32 v27, v27, v195
	v_mul_f32_e32 v198, v198, v118
	v_cvt_pk_bf16_f32 v184, v8, v9
	v_cvt_pk_bf16_f32 v185, v10, v11
	v_mul_f32_e32 v199, v199, v118
	v_cvt_pk_bf16_f32 v186, v12, v13
	v_cvt_pk_bf16_f32 v202, v196, v197
	v_cvt_pk_bf16_f32 v187, v14, v15
	v_cvt_pk_bf16_f32 v203, v198, v199
	v_cvt_pk_bf16_f32 v188, v16, v17
	v_cvt_pk_bf16_f32 v189, v18, v19
	ds_write_b64 v215, v[202:203] offset:32768
	v_cvt_pk_bf16_f32 v190, v20, v21
	v_mul_f32_e32 v196, v196, v200
	v_cvt_pk_bf16_f32 v191, v22, v23
	ds_write_b64 v248, v[184:185] offset:8192
	v_mul_f32_e32 v197, v197, v200
	ds_write_b64 v248, v[186:187] offset:12288
	v_mul_f32_e32 v198, v198, v200
	ds_write_b64 v249, v[188:189] offset:8192
	ds_write_b64 v249, v[190:191] offset:12288
	v_mul_f32_e32 v199, v199, v200
	s_waitcnt lgkmcnt(7)
	v_sub_f32_e32 v184, v194, v96
	v_cvt_pk_bf16_f32 v192, v196, v197
	v_sub_f32_e32 v185, v194, v97
	v_sub_f32_e32 v186, v194, v98
	v_cvt_pk_bf16_f32 v193, v198, v199
	v_sub_f32_e32 v187, v194, v99
	ds_write_b64 v215, v[192:193] offset:37888
	v_exp_f32_e32 v184, v184
	v_exp_f32_e32 v185, v185
	ds_write_b64 v217, v[164:165] offset:43008
	v_exp_f32_e32 v186, v186
	ds_write_b64 v217, v[166:167] offset:47616
	v_exp_f32_e32 v187, v187
	v_mul_f32_e32 v184, v48, v184
	v_mul_f32_e32 v201, 0x3fb8aa3b, v168
	v_mul_f32_e32 v185, v49, v185
	ds_write_b32 v218, v201 offset:256
	v_mul_f32_e32 v186, v50, v186
	v_mul_f32_e32 v187, v51, v187
	v_mul_f32_e32 v174, 0x3fb8aa3b, v169
	v_cvt_pk_bf16_f32 v184, v184, v185
	v_exp_f32_e32 v174, v174
	v_cvt_pk_bf16_f32 v185, v186, v187
	ds_write_b64 v250, v[184:185] offset:1024
	s_waitcnt lgkmcnt(0)
	s_barrier
	ds_read_b128 v[128:131], v250 offset:1024
	v_lshlrev_b32_e32 v112, 16, v126
	v_and_b32_e32 v113, 0xffff0000, v126
	v_lshlrev_b32_e32 v114, 16, v127
	v_and_b32_e32 v115, 0xffff0000, v127
	v_mul_f32_e32 v120, 0xbfb8aa3b, v112
	v_mul_f32_e32 v121, 0xbfb8aa3b, v113
	v_mul_f32_e32 v122, 0xbfb8aa3b, v114
	v_mul_f32_e32 v123, 0xbfb8aa3b, v115
	v_exp_f32_e32 v120, v120
	v_exp_f32_e32 v121, v121
	v_exp_f32_e32 v122, v122
	v_exp_f32_e32 v123, v123
	v_add_f32_e32 v120, 1.0, v120
	v_add_f32_e32 v121, 1.0, v121
	v_add_f32_e32 v122, 1.0, v122
	v_add_f32_e32 v123, 1.0, v123
	v_rcp_f32_e32 v120, v120
	v_rcp_f32_e32 v121, v121
	v_rcp_f32_e32 v122, v122
	v_rcp_f32_e32 v123, v123
	v_mul_f32_e32 v112, v120, v112
	v_mul_f32_e32 v113, v121, v113
	v_mul_f32_e32 v114, v122, v114
	v_mul_f32_e32 v115, v123, v115
	v_lshlrev_b32_e32 v120, 16, v124
	v_and_b32_e32 v121, 0xffff0000, v124
	v_lshlrev_b32_e32 v122, 16, v125
	v_and_b32_e32 v123, 0xffff0000, v125
	s_waitcnt lgkmcnt(0)
	v_mfma_f32_16x16x32_bf16 v[24:27], v[56:59], v[128:131], v[24:27]
	s_mul_i32 s65, s56, 0x2000
	s_add_u32 s65, s65, 0x304f1000
	s_add_u32 s48, s0, s65
	s_addc_u32 s49, s1, 0
	s_nop 3
	v_fma_f32 v188, s61, v120, v24
	v_fma_f32 v189, s61, v121, v25
	v_fma_f32 v190, s61, v122, v26
	v_fma_f32 v191, s61, v123, v27
	v_mul_f32_e32 v188, v188, v112
	v_mul_f32_e32 v189, v189, v113
	v_mul_f32_e32 v190, v190, v114
	v_mul_f32_e32 v191, v191, v115
	v_cvt_pk_bf16_f32 v170, v188, v189
	v_cvt_pk_bf16_f32 v171, v190, v191
	global_store_dwordx2 v210, v[170:171], s[48:49]
	s_add_u32 s65, s54, 1
	s_sub_u32 s65, s65, s60
	s_lshl_b32 s65, s65, 6
	s_add_u32 s56, s65, s20
	s_add_u32 s54, s54, 1
	s_cmp_ge_u32 s54, s39
	s_cbranch_scc1 .Lssd_done
	ds_read_b128 v[28:31], v223 offset:4096
	ds_read_b128 v[32:35], v224 offset:4096
	ds_read_b128 v[40:43], v225 offset:4096
	ds_read_b128 v[44:47], v226 offset:4096
	ds_read_b128 v[48:51], v227 offset:8192
	ds_read_b128 v[52:55], v228 offset:8192
	ds_read_b128 v[56:59], v229 offset:8192
	ds_read_b128 v[60:63], v230 offset:8192
	ds_read_b32 v194, v231 offset:320
	ds_read_b64_tr_b16 v[96:97], v246 offset:16384
	ds_read_b64_tr_b16 v[98:99], v246 offset:20480
	ds_read_b64_tr_b16 v[100:101], v246 offset:24576
	ds_read_b64_tr_b16 v[102:103], v246 offset:28672
	ds_read_b64_tr_b16 v[104:105], v247 offset:16384
	ds_read_b64_tr_b16 v[106:107], v247 offset:20480
	s_waitcnt lgkmcnt(11)
	ds_read_b64_tr_b16 v[108:109], v247 offset:24576
	ds_read_b64_tr_b16 v[110:111], v247 offset:28672
	ds_read_b64_tr_b16 v[112:113], v243 offset:37888
	ds_read_b64_tr_b16 v[114:115], v243 offset:39168
	s_waitcnt lgkmcnt(11)
	ds_read_b64_tr_b16 v[124:125], v243 offset:37920
	ds_read_b64_tr_b16 v[126:127], v243 offset:39200
	ds_read_b64_tr_b16 v[120:121], v243 offset:40448
	ds_read_b64_tr_b16 v[122:123], v243 offset:41728
	global_load_dwordx4 v[156:159], v204, s[40:41] offset:2048
	s_waitcnt lgkmcnt(11)
	ds_read_b64_tr_b16 v[128:129], v243 offset:40480
	ds_read_b64_tr_b16 v[130:131], v243 offset:41760
	global_load_dwordx4 v[160:163], v205, s[40:41] offset:2048
	ds_read_b128 v[64:67], v223 offset:16384
	ds_read_b128 v[68:71], v224 offset:16384
	s_waitcnt lgkmcnt(11)
; __device__ __forceinline__ void phase_ssd(const Params& P, int seg, unsigned char* smem) {
;     ...
;             if (ci + 2 < nchunks) load_chunk(ci + 2, R);
;             bf16x8 cf[4];
; #pragma unroll
;             for (int k = 0; k < 4; ++k) cf[k] = *(const bf16x8*)(sb + T_CS + (lt * 16 + fr) * 272 + (k * 32 + fq * 8) * 2);
;             f32x4 yo = {0.f, 0.f, 0.f, 0.f};
; #pragma unroll
;             for (int k = 0; k < 4; ++k) { const bf16x8 bb = *(const bf16x8*)((const unsigned char*)StR + (pt * 16 + fr) * 272 + (k * 32 + fq * 8) * 2); yo = mfma16(cf[k], bb, yo); }
; { const f32x4 a4 = *(const f32x4*)(acP + lt * 16 + fq * 4);
; #pragma unroll
;               for (int j = 0; j < 4; ++j) yo[j] *= __expf(a4[j]); }
;             const float acl_fr = acP[lt * 16 + fr]; const int lrow = lt * 16 + fr;
; #pragma unroll
;             for (int t = 0; t < 2; ++t) {
;                 if (2 * t <= lt) {
;                     v2u xb0, xb1;
;                     { const unsigned a0 = lds0 + par * T_BUF + T_XD + (32 * t + 4 * fq + tq) * 80 + (pt * 16 + 4 * tp) * 2, a1 = a0 + 16 * 80; TR_ISSUE(xb0, a0); TR_ISSUE(xb1, a1); }
;                     float m[8];
;                     { f32x4 s0 = {0.f, 0.f, 0.f, 0.f}, s1 = {0.f, 0.f, 0.f, 0.f};
; #pragma unroll
;                       for (int k = 0; k < 4; ++k) { const bf16x8 bf0 = *(const bf16x8*)(sb + T_BS + ((2 * t) * 16 + fr) * 272 + (k * 32 + fq * 8) * 2), bf1 = *(const bf16x8*)(sb + T_BS + ((2 * t + 1) * 16 + fr) * 272 + (k * 32 + fq * 8) * 2);
;                           s0 = mfma16(bf0, cf[k], s0); s1 = mfma16(bf1, cf[k], s1); }
;                       const f32x4 a0 = *(const f32x4*)(acP + (2 * t) * 16 + fq * 4), a1 = *(const f32x4*)(acP + (2 * t + 1) * 16 + fq * 4);
; #pragma unroll
;                       for (int j = 0; j < 4; ++j) { const int si0 = (2 * t) * 16 + fq * 4 + j, si1 = si0 + 16;
;                           const float e0 = s0[j] * __expf(fminf(acl_fr - a0[j], 0.f)), e1 = s1[j] * __expf(fminf(acl_fr - a1[j], 0.f));
;                           m[j] = (si0 <= lrow) ? e0 : 0.f; m[4 + j] = (si1 <= lrow) ? e1 : 0.f; } }
;                     v4u mp; mp.x = cvt_pk_bf16(m[0], m[1]); mp.y = cvt_pk_bf16(m[2], m[3]); mp.z = cvt_pk_bf16(m[4], m[5]); mp.w = cvt_pk_bf16(m[6], m[7]);
;                     asm volatile("s_waitcnt lgkmcnt(0)" : "+v"(xb0), "+v"(xb1) :: "memory");
	ds_read_b128 v[72:75], v225 offset:16384
	global_load_dwordx4 v[148:151], v204, s[40:41]
	ds_read_b128 v[76:79], v226 offset:16384
	v_mfma_f32_16x16x32_bf16 v[24:27], v[48:51], v[28:31], 0
	v_mfma_f32_16x16x32_bf16 v[24:27], v[52:55], v[32:35], v[24:27]
	global_load_dwordx4 v[152:155], v205, s[40:41]
	v_mfma_f32_16x16x32_bf16 v[24:27], v[56:59], v[40:43], v[24:27]
	v_mfma_f32_16x16x32_bf16 v[24:27], v[60:63], v[44:47], v[24:27]
	ds_read_b64_tr_b16 v[56:57], v234 offset:32768
	global_load_dwordx2 v[164:165], v206, s[40:41]
	ds_read_b64_tr_b16 v[58:59], v234 offset:34048
	v_mul_f32_e32 v8, v8, v174
	v_mul_f32_e32 v9, v9, v174
	global_load_dwordx2 v[166:167], v207, s[42:43] nt
	v_mul_f32_e32 v10, v10, v174
	v_mul_f32_e32 v11, v11, v174
	v_mul_f32_e32 v12, v12, v174
	global_load_dword v118, v208, s[44:45]
	v_mul_f32_e32 v13, v13, v174
	v_mul_f32_e32 v14, v14, v174
	v_mul_f32_e32 v15, v15, v174
	global_load_dword v168, v208, s[46:47]
	v_mul_f32_e32 v16, v16, v174
	v_mul_f32_e32 v17, v17, v174
	v_mul_f32_e32 v18, v18, v174
	global_load_dword v169, v209, s[46:47]
	v_mul_f32_e32 v19, v19, v174
	v_mul_f32_e32 v20, v20, v174
	v_mul_f32_e32 v21, v21, v174
	s_add_u32 s66, s54, 3
	s_cmp_lt_u32 s66, s39
	s_cselect_b32 s75, 0xc0000, 0
	s_cselect_b32 s76, 0x280000, 0
	s_cselect_b32 s77, 0x4000, 0
	s_add_u32 s40, s40, s75
	s_addc_u32 s41, s41, 0
	s_add_u32 s42, s42, s76
	s_addc_u32 s43, s43, 0
	s_add_u32 s44, s44, s77
	s_addc_u32 s45, s45, 0
	s_add_u32 s46, s46, s77
	s_addc_u32 s47, s47, 0
	v_mul_f32_e32 v22, v22, v174
	s_waitcnt vmcnt(10)
	v_mul_f32_e32 v23, v23, v174
	s_waitcnt lgkmcnt(12)
	v_mfma_f32_16x16x32_bf16 v[8:11], v[96:99], v[112:115], v[8:11]
	ds_write_b128 v212, v[140:143]
	s_waitcnt lgkmcnt(11)
	v_mfma_f32_16x16x32_bf16 v[12:15], v[96:99], v[124:127], v[12:15]
	ds_write_b128 v212, v[144:147] offset:8192
	v_mfma_f32_16x16x32_bf16 v[16:19], v[104:107], v[112:115], v[16:19]
	v_mfma_f32_16x16x32_bf16 v[20:23], v[104:107], v[124:127], v[20:23]
	ds_write_b128 v212, v[132:135] offset:16384
	s_waitcnt lgkmcnt(11)
	v_mfma_f32_16x16x32_bf16 v[8:11], v[100:103], v[120:123], v[8:11]
	ds_write_b128 v212, v[136:139] offset:24576
	s_waitcnt lgkmcnt(10)
	v_mfma_f32_16x16x32_bf16 v[12:15], v[100:103], v[128:131], v[12:15]
	v_mfma_f32_16x16x32_bf16 v[16:19], v[108:111], v[120:123], v[16:19]
	v_sub_f32_e32 v200, v117, v116
	v_mfma_f32_16x16x32_bf16 v[20:23], v[108:111], v[128:131], v[20:23]
	v_mul_f32_e32 v200, 0x3fb8aa3b, v200
	ds_read_b128 v[96:99], v232 offset:256
	ds_read_b64 v[124:125], v236 offset:44160
	v_exp_f32_e32 v200, v200
	ds_read_b64 v[126:127], v236 offset:48768
	v_lshlrev_b32_e32 v196, 16, v4
	s_waitcnt lgkmcnt(12)
	v_mfma_f32_16x16x32_bf16 v[48:51], v[64:67], v[28:31], 0
	s_waitcnt lgkmcnt(11)
	v_mfma_f32_16x16x32_bf16 v[48:51], v[68:71], v[32:35], v[48:51]
	v_and_b32_e32 v197, 0xffff0000, v4
	s_waitcnt lgkmcnt(10)
	v_mfma_f32_16x16x32_bf16 v[48:51], v[72:75], v[40:43], v[48:51]
	v_lshlrev_b32_e32 v198, 16, v5
	s_waitcnt lgkmcnt(9)
	v_mfma_f32_16x16x32_bf16 v[48:51], v[76:79], v[44:47], v[48:51]
	v_exp_f32_e32 v195, v194
	v_and_b32_e32 v199, 0xffff0000, v5
	v_mul_f32_e32 v24, v24, v195
	v_mul_f32_e32 v196, v196, v6
	v_mul_f32_e32 v25, v25, v195
	v_mul_f32_e32 v26, v26, v195
	v_mul_f32_e32 v197, v197, v6
	v_mul_f32_e32 v27, v27, v195
	v_mul_f32_e32 v198, v198, v6
	v_cvt_pk_bf16_f32 v184, v8, v9
	v_cvt_pk_bf16_f32 v185, v10, v11
	v_mul_f32_e32 v199, v199, v6
	v_cvt_pk_bf16_f32 v186, v12, v13
	v_cvt_pk_bf16_f32 v202, v196, v197
	v_cvt_pk_bf16_f32 v187, v14, v15
	v_cvt_pk_bf16_f32 v203, v198, v199
	v_cvt_pk_bf16_f32 v188, v16, v17
	v_cvt_pk_bf16_f32 v189, v18, v19
	ds_write_b64 v214, v[202:203] offset:32768
	v_cvt_pk_bf16_f32 v190, v20, v21
	v_mul_f32_e32 v196, v196, v200
	v_cvt_pk_bf16_f32 v191, v22, v23
	ds_write_b64 v248, v[184:185]
	v_mul_f32_e32 v197, v197, v200
	ds_write_b64 v248, v[186:187] offset:4096
	v_mul_f32_e32 v198, v198, v200
	ds_write_b64 v249, v[188:189]
	ds_write_b64 v249, v[190:191] offset:4096
	v_mul_f32_e32 v199, v199, v200
	s_waitcnt lgkmcnt(7)
	v_sub_f32_e32 v184, v194, v96
	v_cvt_pk_bf16_f32 v192, v196, v197
	v_sub_f32_e32 v185, v194, v97
	v_sub_f32_e32 v186, v194, v98
	v_cvt_pk_bf16_f32 v193, v198, v199
	v_sub_f32_e32 v187, v194, v99
	ds_write_b64 v214, v[192:193] offset:37888
	v_exp_f32_e32 v184, v184
	v_exp_f32_e32 v185, v185
	ds_write_b64 v216, v[4:5] offset:43008
	v_exp_f32_e32 v186, v186
	ds_write_b64 v216, v[36:37] offset:47616
	v_exp_f32_e32 v187, v187
	v_mul_f32_e32 v184, v48, v184
	v_mul_f32_e32 v201, 0x3fb8aa3b, v116
	v_mul_f32_e32 v185, v49, v185
	ds_write_b32 v218, v201
	v_mul_f32_e32 v186, v50, v186
	v_mul_f32_e32 v187, v51, v187
	v_mul_f32_e32 v174, 0x3fb8aa3b, v117
	v_cvt_pk_bf16_f32 v184, v184, v185
	v_exp_f32_e32 v174, v174
	v_cvt_pk_bf16_f32 v185, v186, v187
	ds_write_b64 v250, v[184:185] offset:7168
	s_waitcnt lgkmcnt(0)
	s_barrier
	ds_read_b128 v[128:131], v250 offset:7168
	v_lshlrev_b32_e32 v112, 16, v126
	v_and_b32_e32 v113, 0xffff0000, v126
	v_lshlrev_b32_e32 v114, 16, v127
	v_and_b32_e32 v115, 0xffff0000, v127
	v_mul_f32_e32 v120, 0xbfb8aa3b, v112
	v_mul_f32_e32 v121, 0xbfb8aa3b, v113
	v_mul_f32_e32 v122, 0xbfb8aa3b, v114
	v_mul_f32_e32 v123, 0xbfb8aa3b, v115
	v_exp_f32_e32 v120, v120
	v_exp_f32_e32 v121, v121
	v_exp_f32_e32 v122, v122
	v_exp_f32_e32 v123, v123
	v_add_f32_e32 v120, 1.0, v120
	v_add_f32_e32 v121, 1.0, v121
	v_add_f32_e32 v122, 1.0, v122
	v_add_f32_e32 v123, 1.0, v123
	v_rcp_f32_e32 v120, v120
	v_rcp_f32_e32 v121, v121
	v_rcp_f32_e32 v122, v122
	v_rcp_f32_e32 v123, v123
	v_mul_f32_e32 v112, v120, v112
	v_mul_f32_e32 v113, v121, v113
	v_mul_f32_e32 v114, v122, v114
	v_mul_f32_e32 v115, v123, v115
	v_lshlrev_b32_e32 v120, 16, v124
	v_and_b32_e32 v121, 0xffff0000, v124
	v_lshlrev_b32_e32 v122, 16, v125
	v_and_b32_e32 v123, 0xffff0000, v125
	s_waitcnt lgkmcnt(0)
	v_mfma_f32_16x16x32_bf16 v[24:27], v[56:59], v[128:131], v[24:27]
	s_mul_i32 s65, s56, 0x2000
	s_add_u32 s65, s65, 0x304f1000
	s_add_u32 s48, s0, s65
	s_addc_u32 s49, s1, 0
	s_nop 3
	v_fma_f32 v188, s61, v120, v24
	v_fma_f32 v189, s61, v121, v25
	v_fma_f32 v190, s61, v122, v26
	v_fma_f32 v191, s61, v123, v27
	v_mul_f32_e32 v188, v188, v112
	v_mul_f32_e32 v189, v189, v113
	v_mul_f32_e32 v190, v190, v114
	v_mul_f32_e32 v191, v191, v115
	v_cvt_pk_bf16_f32 v170, v188, v189
	v_cvt_pk_bf16_f32 v171, v190, v191
	global_store_dwordx2 v210, v[170:171], s[48:49]
	s_add_u32 s65, s54, 1
	s_sub_u32 s65, s65, s60
	s_lshl_b32 s65, s65, 6
	s_add_u32 s56, s65, s20
	s_add_u32 s54, s54, 1
	s_cmp_lt_u32 s54, s39
	s_cbranch_scc1 .Lssd_loop10
	s_branch .Lssd_done
; __device__ __forceinline__ unsigned cvt_pk_bf16(float lo, float hi) { unsigned r; asm volatile("v_cvt_pk_bf16_f32 %0, %1, %2" : "=v"(r) : "v"(lo), "v"(hi)); return r; }
; __device__ __forceinline__ void phase_ssd(const Params& P, int seg, unsigned char* smem) {
;     ...
;             { const float e2 = __expf(R.alast - R.acl);
; #pragma unroll
;               for (int i = 0; i < 2; ++i) { const int q = tid + 512 * i, l = q >> 4, c8 = q & 15; *(v4u*)(sb + T_CS + l * 272 + c8 * 16) = R.Cr[i]; *(v4u*)(sb + T_BS + l * 272 + c8 * 16) = R.Br[i]; }
;               const int l = tid >> 3, p4 = (tid & 7) * 4;
;               const float x0 = bflo(R.Xr.x) * R.dtl, x1 = bfhi(R.Xr.x) * R.dtl, x2 = bflo(R.Xr.y) * R.dtl, x3 = bfhi(R.Xr.y) * R.dtl;
;               v2u d; d.x = cvt_pk_bf16(x0, x1); d.y = cvt_pk_bf16(x2, x3); *(v2u*)(sb + T_XD + l * 80 + p4 * 2) = d;
;               v2u e; e.x = cvt_pk_bf16(x0 * e2, x1 * e2); e.y = cvt_pk_bf16(x2 * e2, x3 * e2); *(v2u*)(sb + T_XE + l * 80 + p4 * 2) = e;
;               *(v2u*)(sb + T_XS + l * 64 + p4 * 2) = R.Xr; *(v2u*)(sb + T_ZS + l * 64 + p4 * 2) = R.Zr;
;               if (w == 0) acP[lane] = R.aclane; }
;             BAR_LDS();
;             if (ci + 2 < nchunks) load_chunk(ci + 2, R);
;             bf16x8 cf[4];
; #pragma unroll
;             for (int k = 0; k < 4; ++k) cf[k] = *(const bf16x8*)(sb + T_CS + (lt * 16 + fr) * 272 + (k * 32 + fq * 8) * 2);
;             f32x4 yo = {0.f, 0.f, 0.f, 0.f};
; #pragma unroll
;             for (int k = 0; k < 4; ++k) { const bf16x8 bb = *(const bf16x8*)((const unsigned char*)StR + (pt * 16 + fr) * 272 + (k * 32 + fq * 8) * 2); yo = mfma16(cf[k], bb, yo); }
; { const f32x4 a4 = *(const f32x4*)(acP + lt * 16 + fq * 4);
; #pragma unroll
;               for (int j = 0; j < 4; ++j) yo[j] *= __expf(a4[j]); }
;             const float acl_fr = acP[lt * 16 + fr]; const int lrow = lt * 16 + fr;
; #pragma unroll
;             for (int t = 0; t < 2; ++t) {
;                 if (2 * t <= lt) {
;                     v2u xb0, xb1;
;                     { const unsigned a0 = lds0 + par * T_BUF + T_XD + (32 * t + 4 * fq + tq) * 80 + (pt * 16 + 4 * tp) * 2, a1 = a0 + 16 * 80; TR_ISSUE(xb0, a0); TR_ISSUE(xb1, a1); }
;                     float m[8];
;                     { f32x4 s0 = {0.f, 0.f, 0.f, 0.f}, s1 = {0.f, 0.f, 0.f, 0.f};
; #pragma unroll
.Lssd_loop11:
	ds_read_b128 v[28:31], v219 offset:4096
	ds_read_b128 v[32:35], v220 offset:4096
	ds_read_b128 v[40:43], v221 offset:4096
	ds_read_b128 v[44:47], v222 offset:4096
	ds_read_b128 v[48:51], v227
	ds_read_b128 v[52:55], v228
	ds_read_b128 v[56:59], v229
	ds_read_b128 v[60:63], v230
	ds_read_b32 v194, v231 offset:64
	ds_read_b64_tr_b16 v[96:97], v244 offset:16384
	ds_read_b64_tr_b16 v[98:99], v244 offset:20480
	ds_read_b64_tr_b16 v[100:101], v244 offset:24576
	ds_read_b64_tr_b16 v[102:103], v244 offset:28672
	ds_read_b64_tr_b16 v[104:105], v245 offset:16384
	ds_read_b64_tr_b16 v[106:107], v245 offset:20480
	s_waitcnt lgkmcnt(11)
	ds_read_b64_tr_b16 v[108:109], v245 offset:24576
	ds_read_b64_tr_b16 v[110:111], v245 offset:28672
	ds_read_b64_tr_b16 v[112:113], v237 offset:37888
	ds_read_b64_tr_b16 v[114:115], v237 offset:39168
	s_waitcnt lgkmcnt(11)
	ds_read_b64_tr_b16 v[124:125], v237 offset:37920
	ds_read_b64_tr_b16 v[126:127], v237 offset:39200
	ds_read_b64_tr_b16 v[120:121], v237 offset:40448
	ds_read_b64_tr_b16 v[122:123], v237 offset:41728
	global_load_dwordx4 v[140:143], v204, s[40:41] offset:2048
	s_waitcnt lgkmcnt(11)
	ds_read_b64_tr_b16 v[128:129], v237 offset:40480
	ds_read_b64_tr_b16 v[130:131], v237 offset:41760
	ds_read_b128 v[64:67], v219 offset:20480
	global_load_dwordx4 v[144:147], v205, s[40:41] offset:2048
	ds_read_b128 v[68:71], v220 offset:20480
	s_waitcnt lgkmcnt(11)
	ds_read_b128 v[72:75], v221 offset:20480
	ds_read_b128 v[76:79], v222 offset:20480
	global_load_dwordx4 v[132:135], v204, s[40:41]
	v_mfma_f32_16x16x32_bf16 v[24:27], v[48:51], v[28:31], 0
	v_mfma_f32_16x16x32_bf16 v[24:27], v[52:55], v[32:35], v[24:27]
	v_mfma_f32_16x16x32_bf16 v[24:27], v[56:59], v[40:43], v[24:27]
	global_load_dwordx4 v[136:139], v205, s[40:41]
	v_mfma_f32_16x16x32_bf16 v[24:27], v[60:63], v[44:47], v[24:27]
	ds_read_b64_tr_b16 v[56:57], v233 offset:32768
	ds_read_b64_tr_b16 v[58:59], v233 offset:34048
	global_load_dwordx2 v[4:5], v206, s[40:41]
	v_mul_f32_e32 v8, v8, v174
	v_mul_f32_e32 v9, v9, v174
	v_mul_f32_e32 v10, v10, v174
	global_load_dwordx2 v[36:37], v207, s[42:43] nt
	v_mul_f32_e32 v11, v11, v174
	v_mul_f32_e32 v12, v12, v174
	v_mul_f32_e32 v13, v13, v174
	global_load_dword v6, v208, s[44:45]
	v_mul_f32_e32 v14, v14, v174
	v_mul_f32_e32 v15, v15, v174
	v_mul_f32_e32 v16, v16, v174
	global_load_dword v116, v208, s[46:47]
	v_mul_f32_e32 v17, v17, v174
	v_mul_f32_e32 v18, v18, v174
	v_mul_f32_e32 v19, v19, v174
	global_load_dword v117, v209, s[46:47]
	v_mul_f32_e32 v20, v20, v174
	v_mul_f32_e32 v21, v21, v174
	v_mul_f32_e32 v22, v22, v174
	s_add_u32 s66, s54, 3
	s_cmp_lt_u32 s66, s39
	s_cselect_b32 s75, 0xc0000, 0
	s_cselect_b32 s76, 0x280000, 0
	s_cselect_b32 s77, 0x4000, 0
	s_add_u32 s40, s40, s75
	s_addc_u32 s41, s41, 0
	s_add_u32 s42, s42, s76
	s_addc_u32 s43, s43, 0
	s_add_u32 s44, s44, s77
	s_addc_u32 s45, s45, 0
	s_add_u32 s46, s46, s77
	s_addc_u32 s47, s47, 0
	v_mul_f32_e32 v23, v23, v174
	s_waitcnt lgkmcnt(12)
	v_mfma_f32_16x16x32_bf16 v[8:11], v[96:99], v[112:115], v[8:11]
	s_waitcnt vmcnt(10)
	s_waitcnt lgkmcnt(10)
	v_mfma_f32_16x16x32_bf16 v[12:15], v[96:99], v[124:127], v[12:15]
	ds_write_b128 v213, v[156:159]
	v_mfma_f32_16x16x32_bf16 v[16:19], v[104:107], v[112:115], v[16:19]
	v_mfma_f32_16x16x32_bf16 v[20:23], v[104:107], v[124:127], v[20:23]
	ds_write_b128 v213, v[160:163] offset:8192
	s_waitcnt lgkmcnt(10)
	v_mfma_f32_16x16x32_bf16 v[8:11], v[100:103], v[120:123], v[8:11]
	s_waitcnt lgkmcnt(8)
	v_mfma_f32_16x16x32_bf16 v[12:15], v[100:103], v[128:131], v[12:15]
	ds_write_b128 v213, v[148:151] offset:16384
	v_mfma_f32_16x16x32_bf16 v[16:19], v[108:111], v[120:123], v[16:19]
	ds_write_b128 v213, v[152:155] offset:24576
	v_mfma_f32_16x16x32_bf16 v[20:23], v[108:111], v[128:131], v[20:23]
	ds_read_b128 v[96:99], v232 offset:64
	v_sub_f32_e32 v200, v169, v168
	ds_read_b64 v[124:125], v235 offset:44160
	v_mul_f32_e32 v200, 0x3fb8aa3b, v200
	ds_read_b64 v[126:127], v235 offset:48768
	s_waitcnt lgkmcnt(12)
	v_mfma_f32_16x16x32_bf16 v[48:51], v[64:67], v[28:31], 0
	v_exp_f32_e32 v200, v200
	s_waitcnt lgkmcnt(11)
	v_mfma_f32_16x16x32_bf16 v[48:51], v[68:71], v[32:35], v[48:51]
	v_lshlrev_b32_e32 v196, 16, v164
	s_waitcnt lgkmcnt(10)
	v_mfma_f32_16x16x32_bf16 v[48:51], v[72:75], v[40:43], v[48:51]
	s_waitcnt lgkmcnt(9)
	v_mfma_f32_16x16x32_bf16 v[48:51], v[76:79], v[44:47], v[48:51]
	v_and_b32_e32 v197, 0xffff0000, v164
	v_exp_f32_e32 v195, v194
	v_lshlrev_b32_e32 v198, 16, v165
	v_mul_f32_e32 v24, v24, v195
	v_mul_f32_e32 v25, v25, v195
	v_and_b32_e32 v199, 0xffff0000, v165
	v_mul_f32_e32 v26, v26, v195
	v_mul_f32_e32 v27, v27, v195
	v_mul_f32_e32 v196, v196, v118
	v_cvt_pk_bf16_f32 v184, v8, v9
	v_mul_f32_e32 v197, v197, v118
	v_cvt_pk_bf16_f32 v185, v10, v11
	v_cvt_pk_bf16_f32 v186, v12, v13
	v_mul_f32_e32 v198, v198, v118
	v_cvt_pk_bf16_f32 v187, v14, v15
	v_mul_f32_e32 v199, v199, v118
	v_cvt_pk_bf16_f32 v188, v16, v17
	v_cvt_pk_bf16_f32 v189, v18, v19
	v_cvt_pk_bf16_f32 v202, v196, v197
	v_cvt_pk_bf16_f32 v190, v20, v21
	v_cvt_pk_bf16_f32 v203, v198, v199
	v_cvt_pk_bf16_f32 v191, v22, v23
	ds_write_b64 v248, v[184:185] offset:8192
	ds_write_b64 v215, v[202:203] offset:32768
	ds_write_b64 v248, v[186:187] offset:12288
	v_mul_f32_e32 v196, v196, v200
	ds_write_b64 v249, v[188:189] offset:8192
	ds_write_b64 v249, v[190:191] offset:12288
	v_mul_f32_e32 v197, v197, v200
	s_waitcnt lgkmcnt(7)
	v_sub_f32_e32 v184, v194, v96
	v_mul_f32_e32 v198, v198, v200
	v_sub_f32_e32 v185, v194, v97
	v_sub_f32_e32 v186, v194, v98
	v_mul_f32_e32 v199, v199, v200
	v_sub_f32_e32 v187, v194, v99
	v_exp_f32_e32 v184, v184
	v_cvt_pk_bf16_f32 v192, v196, v197
	v_exp_f32_e32 v185, v185
	v_cvt_pk_bf16_f32 v193, v198, v199
	v_exp_f32_e32 v186, v186
	v_exp_f32_e32 v187, v187
	ds_write_b64 v215, v[192:193] offset:37888
	v_mul_f32_e32 v184, v48, v184
	ds_write_b64 v217, v[164:165] offset:43008
	v_mul_f32_e32 v185, v49, v185
	v_mul_f32_e32 v186, v50, v186
	ds_write_b64 v217, v[166:167] offset:47616
	v_mul_f32_e32 v187, v51, v187
	v_mul_f32_e32 v201, 0x3fb8aa3b, v168
	v_cndmask_b32_e64 v184, 0, v184, s[14:15]
	v_cndmask_b32_e64 v185, 0, v185, s[16:17]
	ds_write_b32 v218, v201 offset:256
	v_cndmask_b32_e64 v186, 0, v186, s[22:23]
	v_mul_f32_e32 v174, 0x3fb8aa3b, v169
	v_cndmask_b32_e64 v187, 0, v187, s[34:35]
	v_cvt_pk_bf16_f32 v184, v184, v185
	v_exp_f32_e32 v174, v174
	v_cvt_pk_bf16_f32 v185, v186, v187
	ds_write_b64 v250, v[184:185] offset:1032
	s_waitcnt lgkmcnt(0)
	s_barrier
; __device__ __forceinline__ void phase_ssd(const Params& P, int seg, unsigned char* smem) {
;     ...
; { const f32x4 a4 = *(const f32x4*)(acP + lt * 16 + fq * 4);
; #pragma unroll
;               for (int j = 0; j < 4; ++j) yo[j] *= __expf(a4[j]); }
;             const float acl_fr = acP[lt * 16 + fr]; const int lrow = lt * 16 + fr;
; #pragma unroll
;             for (int t = 0; t < 2; ++t) {
;                 if (2 * t <= lt) {
;                     v2u xb0, xb1;
;                     { const unsigned a0 = lds0 + par * T_BUF + T_XD + (32 * t + 4 * fq + tq) * 80 + (pt * 16 + 4 * tp) * 2, a1 = a0 + 16 * 80; TR_ISSUE(xb0, a0); TR_ISSUE(xb1, a1); }
;                     float m[8];
;                     { f32x4 s0 = {0.f, 0.f, 0.f, 0.f}, s1 = {0.f, 0.f, 0.f, 0.f};
; #pragma unroll
;                       for (int k = 0; k < 4; ++k) { const bf16x8 bf0 = *(const bf16x8*)(sb + T_BS + ((2 * t) * 16 + fr) * 272 + (k * 32 + fq * 8) * 2), bf1 = *(const bf16x8*)(sb + T_BS + ((2 * t + 1) * 16 + fr) * 272 + (k * 32 + fq * 8) * 2);
;                           s0 = mfma16(bf0, cf[k], s0); s1 = mfma16(bf1, cf[k], s1); }
;                       const f32x4 a0 = *(const f32x4*)(acP + (2 * t) * 16 + fq * 4), a1 = *(const f32x4*)(acP + (2 * t + 1) * 16 + fq * 4);
; #pragma unroll
;                       for (int j = 0; j < 4; ++j) { const int si0 = (2 * t) * 16 + fq * 4 + j, si1 = si0 + 16;
;                           const float e0 = s0[j] * __expf(fminf(acl_fr - a0[j], 0.f)), e1 = s1[j] * __expf(fminf(acl_fr - a1[j], 0.f));
;                           m[j] = (si0 <= lrow) ? e0 : 0.f; m[4 + j] = (si1 <= lrow) ? e1 : 0.f; } }
;                     v4u mp; mp.x = cvt_pk_bf16(m[0], m[1]); mp.y = cvt_pk_bf16(m[2], m[3]); mp.z = cvt_pk_bf16(m[4], m[5]); mp.w = cvt_pk_bf16(m[6], m[7]);
;                     asm volatile("s_waitcnt lgkmcnt(0)" : "+v"(xb0), "+v"(xb1) :: "memory");
;                     yo = mfma16(__builtin_bit_cast(bf16x8, mp), mk8(xb0, xb1), yo);
;                 }
;             }
; #pragma unroll
;             for (int j = 0; j < 4; ++j) { const int l = lt * 16 + fq * 4 + j, p = pt * 16 + fr; const float xv = bf2f(*(const bf16*)(sb + T_XS + l * 64 + p * 2)), zv = bf2f(*(const bf16*)(sb + T_ZS + l * 64 + p * 2));
;                 ypre[(size_t)(row0 + l) * DINNER + h * 64 + ph * 32 + p] = f2bfh((yo[j] + Dh * xv) * siluf_(zv)); }
;             { v2u xa[2][2][2], bb[2][2];
	ds_read_b128 v[128:131], v250 offset:1024
	v_lshlrev_b32_e32 v112, 16, v126
	v_and_b32_e32 v113, 0xffff0000, v126
	v_lshlrev_b32_e32 v114, 16, v127
	v_and_b32_e32 v115, 0xffff0000, v127
	v_mul_f32_e32 v120, 0xbfb8aa3b, v112
	v_mul_f32_e32 v121, 0xbfb8aa3b, v113
	v_mul_f32_e32 v122, 0xbfb8aa3b, v114
	v_mul_f32_e32 v123, 0xbfb8aa3b, v115
	v_exp_f32_e32 v120, v120
	v_exp_f32_e32 v121, v121
	v_exp_f32_e32 v122, v122
	v_exp_f32_e32 v123, v123
	v_add_f32_e32 v120, 1.0, v120
	v_add_f32_e32 v121, 1.0, v121
	v_add_f32_e32 v122, 1.0, v122
	v_add_f32_e32 v123, 1.0, v123
	v_rcp_f32_e32 v120, v120
	v_rcp_f32_e32 v121, v121
	v_rcp_f32_e32 v122, v122
	v_rcp_f32_e32 v123, v123
	v_mul_f32_e32 v112, v120, v112
	v_mul_f32_e32 v113, v121, v113
	v_mul_f32_e32 v114, v122, v114
	v_mul_f32_e32 v115, v123, v115
	v_lshlrev_b32_e32 v120, 16, v124
	v_and_b32_e32 v121, 0xffff0000, v124
	v_lshlrev_b32_e32 v122, 16, v125
	v_and_b32_e32 v123, 0xffff0000, v125
	s_waitcnt lgkmcnt(0)
	v_mfma_f32_16x16x32_bf16 v[24:27], v[56:59], v[128:131], v[24:27]
	s_mul_i32 s65, s56, 0x2000
	s_add_u32 s65, s65, 0x304f1000
	s_add_u32 s48, s0, s65
	s_addc_u32 s49, s1, 0
	s_nop 3
	v_fma_f32 v188, s61, v120, v24
	v_fma_f32 v189, s61, v121, v25
	v_fma_f32 v190, s61, v122, v26
	v_fma_f32 v191, s61, v123, v27
	v_mul_f32_e32 v188, v188, v112
	v_mul_f32_e32 v189, v189, v113
	v_mul_f32_e32 v190, v190, v114
	v_mul_f32_e32 v191, v191, v115
	v_cvt_pk_bf16_f32 v170, v188, v189
	v_cvt_pk_bf16_f32 v171, v190, v191
	global_store_dwordx2 v210, v[170:171], s[48:49]
	s_add_u32 s65, s54, 1
	s_sub_u32 s65, s65, s60
	s_lshl_b32 s65, s65, 6
	s_add_u32 s56, s65, s20
	s_add_u32 s54, s54, 1
	s_cmp_ge_u32 s54, s39
	s_cbranch_scc1 .Lssd_done
	ds_read_b128 v[28:31], v223 offset:4096
	ds_read_b128 v[32:35], v224 offset:4096
	ds_read_b128 v[40:43], v225 offset:4096
	ds_read_b128 v[44:47], v226 offset:4096
	ds_read_b128 v[48:51], v227 offset:8192
	ds_read_b128 v[52:55], v228 offset:8192
	ds_read_b128 v[56:59], v229 offset:8192
	ds_read_b128 v[60:63], v230 offset:8192
	ds_read_b32 v194, v231 offset:320
	ds_read_b64_tr_b16 v[96:97], v246 offset:16384
	ds_read_b64_tr_b16 v[98:99], v246 offset:20480
	ds_read_b64_tr_b16 v[100:101], v246 offset:24576
	ds_read_b64_tr_b16 v[102:103], v246 offset:28672
	ds_read_b64_tr_b16 v[104:105], v247 offset:16384
	ds_read_b64_tr_b16 v[106:107], v247 offset:20480
	s_waitcnt lgkmcnt(11)
	ds_read_b64_tr_b16 v[108:109], v247 offset:24576
	ds_read_b64_tr_b16 v[110:111], v247 offset:28672
	ds_read_b64_tr_b16 v[112:113], v243 offset:37888
	ds_read_b64_tr_b16 v[114:115], v243 offset:39168
	s_waitcnt lgkmcnt(11)
	ds_read_b64_tr_b16 v[124:125], v243 offset:37920
	ds_read_b64_tr_b16 v[126:127], v243 offset:39200
	ds_read_b64_tr_b16 v[120:121], v243 offset:40448
	ds_read_b64_tr_b16 v[122:123], v243 offset:41728
	global_load_dwordx4 v[156:159], v204, s[40:41] offset:2048
	s_waitcnt lgkmcnt(11)
	ds_read_b64_tr_b16 v[128:129], v243 offset:40480
	ds_read_b64_tr_b16 v[130:131], v243 offset:41760
	ds_read_b128 v[64:67], v223 offset:20480
	global_load_dwordx4 v[160:163], v205, s[40:41] offset:2048
	ds_read_b128 v[68:71], v224 offset:20480
	s_waitcnt lgkmcnt(11)
	ds_read_b128 v[72:75], v225 offset:20480
	ds_read_b128 v[76:79], v226 offset:20480
	global_load_dwordx4 v[148:151], v204, s[40:41]
	v_mfma_f32_16x16x32_bf16 v[24:27], v[48:51], v[28:31], 0
	v_mfma_f32_16x16x32_bf16 v[24:27], v[52:55], v[32:35], v[24:27]
	v_mfma_f32_16x16x32_bf16 v[24:27], v[56:59], v[40:43], v[24:27]
	global_load_dwordx4 v[152:155], v205, s[40:41]
	v_mfma_f32_16x16x32_bf16 v[24:27], v[60:63], v[44:47], v[24:27]
	ds_read_b64_tr_b16 v[56:57], v234 offset:32768
	ds_read_b64_tr_b16 v[58:59], v234 offset:34048
	global_load_dwordx2 v[164:165], v206, s[40:41]
	v_mul_f32_e32 v8, v8, v174
	v_mul_f32_e32 v9, v9, v174
	v_mul_f32_e32 v10, v10, v174
	global_load_dwordx2 v[166:167], v207, s[42:43] nt
	v_mul_f32_e32 v11, v11, v174
	v_mul_f32_e32 v12, v12, v174
	v_mul_f32_e32 v13, v13, v174
	global_load_dword v118, v208, s[44:45]
	v_mul_f32_e32 v14, v14, v174
	v_mul_f32_e32 v15, v15, v174
	v_mul_f32_e32 v16, v16, v174
	global_load_dword v168, v208, s[46:47]
	v_mul_f32_e32 v17, v17, v174
	v_mul_f32_e32 v18, v18, v174
	v_mul_f32_e32 v19, v19, v174
	global_load_dword v169, v209, s[46:47]
	v_mul_f32_e32 v20, v20, v174
	v_mul_f32_e32 v21, v21, v174
	v_mul_f32_e32 v22, v22, v174
	s_add_u32 s66, s54, 3
	s_cmp_lt_u32 s66, s39
	s_cselect_b32 s75, 0xc0000, 0
	s_cselect_b32 s76, 0x280000, 0
	s_cselect_b32 s77, 0x4000, 0
	s_add_u32 s40, s40, s75
	s_addc_u32 s41, s41, 0
	s_add_u32 s42, s42, s76
	s_addc_u32 s43, s43, 0
	s_add_u32 s44, s44, s77
	s_addc_u32 s45, s45, 0
	s_add_u32 s46, s46, s77
	s_addc_u32 s47, s47, 0
	v_mul_f32_e32 v23, v23, v174
	s_waitcnt lgkmcnt(12)
	v_mfma_f32_16x16x32_bf16 v[8:11], v[96:99], v[112:115], v[8:11]
	s_waitcnt vmcnt(10)
	s_waitcnt lgkmcnt(10)
	v_mfma_f32_16x16x32_bf16 v[12:15], v[96:99], v[124:127], v[12:15]
	ds_write_b128 v212, v[140:143]
	v_mfma_f32_16x16x32_bf16 v[16:19], v[104:107], v[112:115], v[16:19]
	v_mfma_f32_16x16x32_bf16 v[20:23], v[104:107], v[124:127], v[20:23]
	ds_write_b128 v212, v[144:147] offset:8192
	s_waitcnt lgkmcnt(10)
	v_mfma_f32_16x16x32_bf16 v[8:11], v[100:103], v[120:123], v[8:11]
	s_waitcnt lgkmcnt(8)
	v_mfma_f32_16x16x32_bf16 v[12:15], v[100:103], v[128:131], v[12:15]
	ds_write_b128 v212, v[132:135] offset:16384
	v_mfma_f32_16x16x32_bf16 v[16:19], v[108:111], v[120:123], v[16:19]
	ds_write_b128 v212, v[136:139] offset:24576
	v_mfma_f32_16x16x32_bf16 v[20:23], v[108:111], v[128:131], v[20:23]
	ds_read_b128 v[96:99], v232 offset:320
	v_sub_f32_e32 v200, v117, v116
	ds_read_b64 v[124:125], v236 offset:44160
	v_mul_f32_e32 v200, 0x3fb8aa3b, v200
	ds_read_b64 v[126:127], v236 offset:48768
	s_waitcnt lgkmcnt(12)
; __device__ __forceinline__ void phase_ssd(const Params& P, int seg, unsigned char* smem) {
;     ...
; { const f32x4 a4 = *(const f32x4*)(acP + lt * 16 + fq * 4);
; #pragma unroll
;               for (int j = 0; j < 4; ++j) yo[j] *= __expf(a4[j]); }
;             const float acl_fr = acP[lt * 16 + fr]; const int lrow = lt * 16 + fr;
; #pragma unroll
;             for (int t = 0; t < 2; ++t) {
;                 if (2 * t <= lt) {
;                     v2u xb0, xb1;
;                     { const unsigned a0 = lds0 + par * T_BUF + T_XD + (32 * t + 4 * fq + tq) * 80 + (pt * 16 + 4 * tp) * 2, a1 = a0 + 16 * 80; TR_ISSUE(xb0, a0); TR_ISSUE(xb1, a1); }
;                     float m[8];
;                     { f32x4 s0 = {0.f, 0.f, 0.f, 0.f}, s1 = {0.f, 0.f, 0.f, 0.f};
; #pragma unroll
;                       for (int k = 0; k < 4; ++k) { const bf16x8 bf0 = *(const bf16x8*)(sb + T_BS + ((2 * t) * 16 + fr) * 272 + (k * 32 + fq * 8) * 2), bf1 = *(const bf16x8*)(sb + T_BS + ((2 * t + 1) * 16 + fr) * 272 + (k * 32 + fq * 8) * 2);
;                           s0 = mfma16(bf0, cf[k], s0); s1 = mfma16(bf1, cf[k], s1); }
;                       const f32x4 a0 = *(const f32x4*)(acP + (2 * t) * 16 + fq * 4), a1 = *(const f32x4*)(acP + (2 * t + 1) * 16 + fq * 4);
; #pragma unroll
;                       for (int j = 0; j < 4; ++j) { const int si0 = (2 * t) * 16 + fq * 4 + j, si1 = si0 + 16;
;                           const float e0 = s0[j] * __expf(fminf(acl_fr - a0[j], 0.f)), e1 = s1[j] * __expf(fminf(acl_fr - a1[j], 0.f));
;                           m[j] = (si0 <= lrow) ? e0 : 0.f; m[4 + j] = (si1 <= lrow) ? e1 : 0.f; } }
;                     v4u mp; mp.x = cvt_pk_bf16(m[0], m[1]); mp.y = cvt_pk_bf16(m[2], m[3]); mp.z = cvt_pk_bf16(m[4], m[5]); mp.w = cvt_pk_bf16(m[6], m[7]);
;                     asm volatile("s_waitcnt lgkmcnt(0)" : "+v"(xb0), "+v"(xb1) :: "memory");
;                     yo = mfma16(__builtin_bit_cast(bf16x8, mp), mk8(xb0, xb1), yo);
;                 }
;             }
; #pragma unroll
;             for (int j = 0; j < 4; ++j) { const int l = lt * 16 + fq * 4 + j, p = pt * 16 + fr; const float xv = bf2f(*(const bf16*)(sb + T_XS + l * 64 + p * 2)), zv = bf2f(*(const bf16*)(sb + T_ZS + l * 64 + p * 2));
;                 ypre[(size_t)(row0 + l) * DINNER + h * 64 + ph * 32 + p] = f2bfh((yo[j] + Dh * xv) * siluf_(zv)); }
;             { v2u xa[2][2][2], bb[2][2];
	v_mfma_f32_16x16x32_bf16 v[48:51], v[64:67], v[28:31], 0
	v_exp_f32_e32 v200, v200
	s_waitcnt lgkmcnt(11)
	v_mfma_f32_16x16x32_bf16 v[48:51], v[68:71], v[32:35], v[48:51]
	v_lshlrev_b32_e32 v196, 16, v4
	s_waitcnt lgkmcnt(10)
	v_mfma_f32_16x16x32_bf16 v[48:51], v[72:75], v[40:43], v[48:51]
	s_waitcnt lgkmcnt(9)
	v_mfma_f32_16x16x32_bf16 v[48:51], v[76:79], v[44:47], v[48:51]
	v_and_b32_e32 v197, 0xffff0000, v4
	v_exp_f32_e32 v195, v194
	v_lshlrev_b32_e32 v198, 16, v5
	v_mul_f32_e32 v24, v24, v195
	v_mul_f32_e32 v25, v25, v195
	v_and_b32_e32 v199, 0xffff0000, v5
	v_mul_f32_e32 v26, v26, v195
	v_mul_f32_e32 v27, v27, v195
	v_mul_f32_e32 v196, v196, v6
	v_cvt_pk_bf16_f32 v184, v8, v9
	v_mul_f32_e32 v197, v197, v6
	v_cvt_pk_bf16_f32 v185, v10, v11
	v_cvt_pk_bf16_f32 v186, v12, v13
	v_mul_f32_e32 v198, v198, v6
	v_cvt_pk_bf16_f32 v187, v14, v15
	v_mul_f32_e32 v199, v199, v6
	v_cvt_pk_bf16_f32 v188, v16, v17
	v_cvt_pk_bf16_f32 v189, v18, v19
	v_cvt_pk_bf16_f32 v202, v196, v197
	v_cvt_pk_bf16_f32 v190, v20, v21
	v_cvt_pk_bf16_f32 v203, v198, v199
	v_cvt_pk_bf16_f32 v191, v22, v23
	ds_write_b64 v248, v[184:185]
	ds_write_b64 v214, v[202:203] offset:32768
	ds_write_b64 v248, v[186:187] offset:4096
	v_mul_f32_e32 v196, v196, v200
	ds_write_b64 v249, v[188:189]
	ds_write_b64 v249, v[190:191] offset:4096
	v_mul_f32_e32 v197, v197, v200
	s_waitcnt lgkmcnt(7)
	v_sub_f32_e32 v184, v194, v96
	v_mul_f32_e32 v198, v198, v200
	v_sub_f32_e32 v185, v194, v97
	v_sub_f32_e32 v186, v194, v98
	v_mul_f32_e32 v199, v199, v200
	v_sub_f32_e32 v187, v194, v99
	v_exp_f32_e32 v184, v184
	v_cvt_pk_bf16_f32 v192, v196, v197
	v_exp_f32_e32 v185, v185
	v_cvt_pk_bf16_f32 v193, v198, v199
	v_exp_f32_e32 v186, v186
	v_exp_f32_e32 v187, v187
	ds_write_b64 v214, v[192:193] offset:37888
	v_mul_f32_e32 v184, v48, v184
	ds_write_b64 v216, v[4:5] offset:43008
	v_mul_f32_e32 v185, v49, v185
	v_mul_f32_e32 v186, v50, v186
	ds_write_b64 v216, v[36:37] offset:47616
	v_mul_f32_e32 v187, v51, v187
	v_mul_f32_e32 v201, 0x3fb8aa3b, v116
	v_cndmask_b32_e64 v184, 0, v184, s[14:15]
	v_cndmask_b32_e64 v185, 0, v185, s[16:17]
	ds_write_b32 v218, v201
	v_cndmask_b32_e64 v186, 0, v186, s[22:23]
	v_mul_f32_e32 v174, 0x3fb8aa3b, v117
	v_cndmask_b32_e64 v187, 0, v187, s[34:35]
	v_cvt_pk_bf16_f32 v184, v184, v185
	v_exp_f32_e32 v174, v174
	v_cvt_pk_bf16_f32 v185, v186, v187
	ds_write_b64 v250, v[184:185] offset:7176
	s_waitcnt lgkmcnt(0)
	s_barrier
	ds_read_b128 v[128:131], v250 offset:7168
	v_lshlrev_b32_e32 v112, 16, v126
	v_and_b32_e32 v113, 0xffff0000, v126
	v_lshlrev_b32_e32 v114, 16, v127
	v_and_b32_e32 v115, 0xffff0000, v127
	v_mul_f32_e32 v120, 0xbfb8aa3b, v112
	v_mul_f32_e32 v121, 0xbfb8aa3b, v113
	v_mul_f32_e32 v122, 0xbfb8aa3b, v114
	v_mul_f32_e32 v123, 0xbfb8aa3b, v115
	v_exp_f32_e32 v120, v120
	v_exp_f32_e32 v121, v121
	v_exp_f32_e32 v122, v122
	v_exp_f32_e32 v123, v123
	v_add_f32_e32 v120, 1.0, v120
	v_add_f32_e32 v121, 1.0, v121
	v_add_f32_e32 v122, 1.0, v122
	v_add_f32_e32 v123, 1.0, v123
	v_rcp_f32_e32 v120, v120
	v_rcp_f32_e32 v121, v121
	v_rcp_f32_e32 v122, v122
	v_rcp_f32_e32 v123, v123
	v_mul_f32_e32 v112, v120, v112
	v_mul_f32_e32 v113, v121, v113
	v_mul_f32_e32 v114, v122, v114
	v_mul_f32_e32 v115, v123, v115
	v_lshlrev_b32_e32 v120, 16, v124
	v_and_b32_e32 v121, 0xffff0000, v124
	v_lshlrev_b32_e32 v122, 16, v125
	v_and_b32_e32 v123, 0xffff0000, v125
	s_waitcnt lgkmcnt(0)
	v_mfma_f32_16x16x32_bf16 v[24:27], v[56:59], v[128:131], v[24:27]
	s_mul_i32 s65, s56, 0x2000
	s_add_u32 s65, s65, 0x304f1000
	s_add_u32 s48, s0, s65
	s_addc_u32 s49, s1, 0
	s_nop 3
	v_fma_f32 v188, s61, v120, v24
	v_fma_f32 v189, s61, v121, v25
	v_fma_f32 v190, s61, v122, v26
	v_fma_f32 v191, s61, v123, v27
	v_mul_f32_e32 v188, v188, v112
	v_mul_f32_e32 v189, v189, v113
	v_mul_f32_e32 v190, v190, v114
	v_mul_f32_e32 v191, v191, v115
	v_cvt_pk_bf16_f32 v170, v188, v189
	v_cvt_pk_bf16_f32 v171, v190, v191
	global_store_dwordx2 v210, v[170:171], s[48:49]
	s_add_u32 s65, s54, 1
	s_sub_u32 s65, s65, s60
	s_lshl_b32 s65, s65, 6
	s_add_u32 s56, s65, s20
	s_add_u32 s54, s54, 1
	s_cmp_lt_u32 s54, s39
	s_cbranch_scc1 .Lssd_loop11
	s_branch .Lssd_done
.Lssd_loop20:
	ds_read_b128 v[28:31], v219 offset:8192
	ds_read_b128 v[32:35], v220 offset:8192
	ds_read_b128 v[40:43], v221 offset:8192
	ds_read_b128 v[44:47], v222 offset:8192
	ds_read_b128 v[48:51], v227
	ds_read_b128 v[52:55], v228
	ds_read_b128 v[56:59], v229
	ds_read_b128 v[60:63], v230
	ds_read_b32 v194, v231 offset:128
	ds_read_b128 v[64:67], v219 offset:16384
	ds_read_b128 v[68:71], v220 offset:16384
	ds_read_b128 v[72:75], v221 offset:16384
	ds_read_b128 v[76:79], v222 offset:16384
	ds_read_b128 v[80:83], v219 offset:24576
	ds_read_b128 v[84:87], v220 offset:24576
	global_load_dwordx4 v[140:143], v204, s[40:41] offset:2048
	s_waitcnt lgkmcnt(11)
	ds_read_b128 v[88:91], v221 offset:24576
	ds_read_b128 v[92:95], v222 offset:24576
	global_load_dwordx4 v[144:147], v205, s[40:41] offset:2048
	ds_read_b128 v[96:99], v232
	ds_read_b128 v[100:103], v232 offset:128
	global_load_dwordx4 v[132:135], v204, s[40:41]
	s_waitcnt lgkmcnt(11)
	ds_read_b64 v[124:125], v235 offset:45312
	ds_read_b64 v[126:127], v235 offset:49920
	v_mfma_f32_16x16x32_bf16 v[24:27], v[48:51], v[28:31], 0
	global_load_dwordx4 v[136:139], v205, s[40:41]
	v_mfma_f32_16x16x32_bf16 v[24:27], v[52:55], v[32:35], v[24:27]
	v_mfma_f32_16x16x32_bf16 v[24:27], v[56:59], v[40:43], v[24:27]
	global_load_dwordx2 v[4:5], v206, s[40:41]
	v_mfma_f32_16x16x32_bf16 v[24:27], v[60:63], v[44:47], v[24:27]
	ds_read_b64_tr_b16 v[56:57], v233 offset:32768
	global_load_dwordx2 v[36:37], v207, s[42:43] nt
	ds_read_b64_tr_b16 v[58:59], v233 offset:34048
	s_waitcnt lgkmcnt(11)
; __device__ __forceinline__ void phase_ssd(const Params& P, int seg, unsigned char* smem) {
;     ...
; { const f32x4 a4 = *(const f32x4*)(acP + lt * 16 + fq * 4);
; #pragma unroll
;               for (int j = 0; j < 4; ++j) yo[j] *= __expf(a4[j]); }
;             const float acl_fr = acP[lt * 16 + fr]; const int lrow = lt * 16 + fr;
; #pragma unroll
;             for (int t = 0; t < 2; ++t) {
;                 if (2 * t <= lt) {
;                     v2u xb0, xb1;
;                     { const unsigned a0 = lds0 + par * T_BUF + T_XD + (32 * t + 4 * fq + tq) * 80 + (pt * 16 + 4 * tp) * 2, a1 = a0 + 16 * 80; TR_ISSUE(xb0, a0); TR_ISSUE(xb1, a1); }
;                     float m[8];
;                     { f32x4 s0 = {0.f, 0.f, 0.f, 0.f}, s1 = {0.f, 0.f, 0.f, 0.f};
; #pragma unroll
;                       for (int k = 0; k < 4; ++k) { const bf16x8 bf0 = *(const bf16x8*)(sb + T_BS + ((2 * t) * 16 + fr) * 272 + (k * 32 + fq * 8) * 2), bf1 = *(const bf16x8*)(sb + T_BS + ((2 * t + 1) * 16 + fr) * 272 + (k * 32 + fq * 8) * 2);
;                           s0 = mfma16(bf0, cf[k], s0); s1 = mfma16(bf1, cf[k], s1); }
;                       const f32x4 a0 = *(const f32x4*)(acP + (2 * t) * 16 + fq * 4), a1 = *(const f32x4*)(acP + (2 * t + 1) * 16 + fq * 4);
; #pragma unroll
;                       for (int j = 0; j < 4; ++j) { const int si0 = (2 * t) * 16 + fq * 4 + j, si1 = si0 + 16;
;                           const float e0 = s0[j] * __expf(fminf(acl_fr - a0[j], 0.f)), e1 = s1[j] * __expf(fminf(acl_fr - a1[j], 0.f));
;                           m[j] = (si0 <= lrow) ? e0 : 0.f; m[4 + j] = (si1 <= lrow) ? e1 : 0.f; } }
;                     v4u mp; mp.x = cvt_pk_bf16(m[0], m[1]); mp.y = cvt_pk_bf16(m[2], m[3]); mp.z = cvt_pk_bf16(m[4], m[5]); mp.w = cvt_pk_bf16(m[6], m[7]);
;                     asm volatile("s_waitcnt lgkmcnt(0)" : "+v"(xb0), "+v"(xb1) :: "memory");
;                     yo = mfma16(__builtin_bit_cast(bf16x8, mp), mk8(xb0, xb1), yo);
;                 }
;             }
; #pragma unroll
;             for (int j = 0; j < 4; ++j) { const int l = lt * 16 + fq * 4 + j, p = pt * 16 + fr; const float xv = bf2f(*(const bf16*)(sb + T_XS + l * 64 + p * 2)), zv = bf2f(*(const bf16*)(sb + T_ZS + l * 64 + p * 2));
;                 ypre[(size_t)(row0 + l) * DINNER + h * 64 + ph * 32 + p] = f2bfh((yo[j] + Dh * xv) * siluf_(zv)); }
	ds_read_b64_tr_b16 v[60:61], v233 offset:35328
	ds_read_b64_tr_b16 v[62:63], v233 offset:36608
	global_load_dword v6, v208, s[44:45]
	v_mfma_f32_16x16x32_bf16 v[48:51], v[64:67], v[28:31], 0
	s_waitcnt lgkmcnt(11)
	v_mfma_f32_16x16x32_bf16 v[52:55], v[80:83], v[28:31], 0
	global_load_dword v116, v208, s[46:47]
	v_mfma_f32_16x16x32_bf16 v[48:51], v[68:71], v[32:35], v[48:51]
	s_waitcnt lgkmcnt(10)
	v_mfma_f32_16x16x32_bf16 v[52:55], v[84:87], v[32:35], v[52:55]
	v_mfma_f32_16x16x32_bf16 v[48:51], v[72:75], v[40:43], v[48:51]
	global_load_dword v117, v209, s[46:47]
	s_waitcnt lgkmcnt(9)
	v_mfma_f32_16x16x32_bf16 v[52:55], v[88:91], v[40:43], v[52:55]
	v_mfma_f32_16x16x32_bf16 v[48:51], v[76:79], v[44:47], v[48:51]
	s_add_u32 s66, s54, 3
	s_cmp_lt_u32 s66, s39
	s_cselect_b32 s75, 0xc0000, 0
	s_cselect_b32 s76, 0x280000, 0
	s_cselect_b32 s77, 0x4000, 0
	s_add_u32 s40, s40, s75
	s_addc_u32 s41, s41, 0
	s_add_u32 s42, s42, s76
	s_addc_u32 s43, s43, 0
	s_add_u32 s44, s44, s77
	s_addc_u32 s45, s45, 0
	s_add_u32 s46, s46, s77
	s_addc_u32 s47, s47, 0
	s_waitcnt lgkmcnt(8)
	v_mfma_f32_16x16x32_bf16 v[52:55], v[92:95], v[44:47], v[52:55]
	s_waitcnt vmcnt(10)
	v_exp_f32_e32 v195, v194
	ds_write_b128 v213, v[156:159]
	v_mul_f32_e32 v24, v24, v195
	v_mul_f32_e32 v25, v25, v195
	ds_write_b128 v213, v[160:163] offset:8192
	v_mul_f32_e32 v26, v26, v195
	ds_write_b128 v213, v[148:151] offset:16384
	v_mul_f32_e32 v27, v27, v195
	ds_write_b128 v213, v[152:155] offset:24576
	s_waitcnt lgkmcnt(11)
	v_sub_f32_e32 v184, v194, v96
	v_sub_f32_e32 v200, v169, v168
	v_sub_f32_e32 v185, v194, v97
	v_mul_f32_e32 v200, 0x3fb8aa3b, v200
	v_sub_f32_e32 v186, v194, v98
	v_sub_f32_e32 v187, v194, v99
	v_exp_f32_e32 v200, v200
	v_exp_f32_e32 v184, v184
	v_lshlrev_b32_e32 v196, 16, v164
	v_exp_f32_e32 v185, v185
	v_and_b32_e32 v197, 0xffff0000, v164
	v_exp_f32_e32 v186, v186
	v_lshlrev_b32_e32 v198, 16, v165
	v_exp_f32_e32 v187, v187
	v_and_b32_e32 v199, 0xffff0000, v165
	v_mul_f32_e32 v184, v48, v184
	v_mul_f32_e32 v185, v49, v185
	v_mul_f32_e32 v196, v196, v118
	v_mul_f32_e32 v186, v50, v186
	v_mul_f32_e32 v197, v197, v118
	v_mul_f32_e32 v187, v51, v187
	v_mul_f32_e32 v198, v198, v118
	v_cvt_pk_bf16_f32 v184, v184, v185
	v_mul_f32_e32 v199, v199, v118
	v_cvt_pk_bf16_f32 v185, v186, v187
	v_cvt_pk_bf16_f32 v202, v196, v197
	ds_write_b64 v250, v[184:185] offset:2048
	s_waitcnt lgkmcnt(11)
	v_sub_f32_e32 v188, v194, v100
	v_cvt_pk_bf16_f32 v203, v198, v199
	v_sub_f32_e32 v189, v194, v101
	ds_write_b64 v215, v[202:203] offset:32768
	v_sub_f32_e32 v190, v194, v102
	v_mul_f32_e32 v196, v196, v200
	v_sub_f32_e32 v191, v194, v103
	v_mul_f32_e32 v197, v197, v200
	v_exp_f32_e32 v188, v188
	v_mul_f32_e32 v198, v198, v200
	v_exp_f32_e32 v189, v189
	v_exp_f32_e32 v190, v190
	v_mul_f32_e32 v199, v199, v200
	v_exp_f32_e32 v191, v191
	v_cvt_pk_bf16_f32 v192, v196, v197
	v_mul_f32_e32 v188, v52, v188
	v_cvt_pk_bf16_f32 v193, v198, v199
	v_mul_f32_e32 v189, v53, v189
	ds_write_b64 v215, v[192:193] offset:37888
	v_mul_f32_e32 v190, v54, v190
	ds_write_b64 v217, v[164:165] offset:43008
	v_mul_f32_e32 v191, v55, v191
	v_cndmask_b32_e64 v188, 0, v188, s[14:15]
	ds_write_b64 v217, v[166:167] offset:47616
	v_cndmask_b32_e64 v189, 0, v189, s[16:17]
	v_mul_f32_e32 v201, 0x3fb8aa3b, v168
	v_cndmask_b32_e64 v190, 0, v190, s[22:23]
	s_waitcnt lgkmcnt(11)
	ds_write_b32 v218, v201 offset:256
	v_cndmask_b32_e64 v191, 0, v191, s[34:35]
	v_mul_f32_e32 v174, 0x3fb8aa3b, v169
	v_cvt_pk_bf16_f32 v188, v188, v189
	v_exp_f32_e32 v174, v174
	v_cvt_pk_bf16_f32 v189, v190, v191
	ds_write_b64 v250, v[188:189] offset:3072
	s_waitcnt lgkmcnt(0)
	s_barrier
	ds_read_b128 v[128:131], v250 offset:2048
	ds_read_b128 v[184:187], v250 offset:3072
	v_lshlrev_b32_e32 v112, 16, v126
	v_and_b32_e32 v113, 0xffff0000, v126
	v_lshlrev_b32_e32 v114, 16, v127
	v_and_b32_e32 v115, 0xffff0000, v127
	v_mul_f32_e32 v120, 0xbfb8aa3b, v112
	v_mul_f32_e32 v121, 0xbfb8aa3b, v113
	v_mul_f32_e32 v122, 0xbfb8aa3b, v114
	v_mul_f32_e32 v123, 0xbfb8aa3b, v115
	v_exp_f32_e32 v120, v120
	v_exp_f32_e32 v121, v121
	v_exp_f32_e32 v122, v122
	v_exp_f32_e32 v123, v123
	v_add_f32_e32 v120, 1.0, v120
	v_add_f32_e32 v121, 1.0, v121
	v_add_f32_e32 v122, 1.0, v122
	v_add_f32_e32 v123, 1.0, v123
	v_rcp_f32_e32 v120, v120
	v_rcp_f32_e32 v121, v121
	v_rcp_f32_e32 v122, v122
	v_rcp_f32_e32 v123, v123
	v_mul_f32_e32 v112, v120, v112
	v_mul_f32_e32 v113, v121, v113
	v_mul_f32_e32 v114, v122, v114
	v_mul_f32_e32 v115, v123, v115
	v_lshlrev_b32_e32 v120, 16, v124
	v_and_b32_e32 v121, 0xffff0000, v124
	v_lshlrev_b32_e32 v122, 16, v125
	v_and_b32_e32 v123, 0xffff0000, v125
	s_waitcnt lgkmcnt(1)
	v_mfma_f32_16x16x32_bf16 v[24:27], v[56:59], v[128:131], v[24:27]
	s_waitcnt lgkmcnt(0)
	v_mfma_f32_16x16x32_bf16 v[24:27], v[60:63], v[184:187], v[24:27]
	s_mul_i32 s65, s56, 0x2000
	s_add_u32 s65, s65, 0x304f1000
	s_add_u32 s48, s0, s65
	s_addc_u32 s49, s1, 0
	s_nop 3
	v_fma_f32 v188, s61, v120, v24
	v_fma_f32 v189, s61, v121, v25
	v_fma_f32 v190, s61, v122, v26
	v_fma_f32 v191, s61, v123, v27
	v_mul_f32_e32 v188, v188, v112
	v_mul_f32_e32 v189, v189, v113
	v_mul_f32_e32 v190, v190, v114
	v_mul_f32_e32 v191, v191, v115
	v_cvt_pk_bf16_f32 v170, v188, v189
	v_cvt_pk_bf16_f32 v171, v190, v191
	global_store_dwordx2 v210, v[170:171], s[48:49]
	s_add_u32 s65, s54, 1
	s_sub_u32 s65, s65, s60
	s_lshl_b32 s65, s65, 6
	s_add_u32 s56, s65, s20
	s_add_u32 s54, s54, 1
	s_cmp_ge_u32 s54, s39
	s_cbranch_scc1 .Lssd_done
; __device__ __forceinline__ unsigned cvt_pk_bf16(float lo, float hi) { unsigned r; asm volatile("v_cvt_pk_bf16_f32 %0, %1, %2" : "=v"(r) : "v"(lo), "v"(hi)); return r; }
; __device__ __forceinline__ void phase_ssd(const Params& P, int seg, unsigned char* smem) {
;     ...
;             { const float e2 = __expf(R.alast - R.acl);
; #pragma unroll
;               for (int i = 0; i < 2; ++i) { const int q = tid + 512 * i, l = q >> 4, c8 = q & 15; *(v4u*)(sb + T_CS + l * 272 + c8 * 16) = R.Cr[i]; *(v4u*)(sb + T_BS + l * 272 + c8 * 16) = R.Br[i]; }
;               const int l = tid >> 3, p4 = (tid & 7) * 4;
;               const float x0 = bflo(R.Xr.x) * R.dtl, x1 = bfhi(R.Xr.x) * R.dtl, x2 = bflo(R.Xr.y) * R.dtl, x3 = bfhi(R.Xr.y) * R.dtl;
;               v2u d; d.x = cvt_pk_bf16(x0, x1); d.y = cvt_pk_bf16(x2, x3); *(v2u*)(sb + T_XD + l * 80 + p4 * 2) = d;
;               v2u e; e.x = cvt_pk_bf16(x0 * e2, x1 * e2); e.y = cvt_pk_bf16(x2 * e2, x3 * e2); *(v2u*)(sb + T_XE + l * 80 + p4 * 2) = e;
;               *(v2u*)(sb + T_XS + l * 64 + p4 * 2) = R.Xr; *(v2u*)(sb + T_ZS + l * 64 + p4 * 2) = R.Zr;
;               if (w == 0) acP[lane] = R.aclane; }
;             BAR_LDS();
;             if (ci + 2 < nchunks) load_chunk(ci + 2, R);
;             bf16x8 cf[4];
; #pragma unroll
;             for (int k = 0; k < 4; ++k) cf[k] = *(const bf16x8*)(sb + T_CS + (lt * 16 + fr) * 272 + (k * 32 + fq * 8) * 2);
;             f32x4 yo = {0.f, 0.f, 0.f, 0.f};
; #pragma unroll
;             for (int k = 0; k < 4; ++k) { const bf16x8 bb = *(const bf16x8*)((const unsigned char*)StR + (pt * 16 + fr) * 272 + (k * 32 + fq * 8) * 2); yo = mfma16(cf[k], bb, yo); }
; { const f32x4 a4 = *(const f32x4*)(acP + lt * 16 + fq * 4);
; #pragma unroll
;               for (int j = 0; j < 4; ++j) yo[j] *= __expf(a4[j]); }
;             const float acl_fr = acP[lt * 16 + fr]; const int lrow = lt * 16 + fr;
; #pragma unroll
;             for (int t = 0; t < 2; ++t) {
;                 if (2 * t <= lt) {
;                     v2u xb0, xb1;
;                     { const unsigned a0 = lds0 + par * T_BUF + T_XD + (32 * t + 4 * fq + tq) * 80 + (pt * 16 + 4 * tp) * 2, a1 = a0 + 16 * 80; TR_ISSUE(xb0, a0); TR_ISSUE(xb1, a1); }
;                     float m[8];
;                     { f32x4 s0 = {0.f, 0.f, 0.f, 0.f}, s1 = {0.f, 0.f, 0.f, 0.f};
; #pragma unroll
	ds_read_b128 v[28:31], v223 offset:8192
	ds_read_b128 v[32:35], v224 offset:8192
	ds_read_b128 v[40:43], v225 offset:8192
	ds_read_b128 v[44:47], v226 offset:8192
	ds_read_b128 v[48:51], v227 offset:8192
	ds_read_b128 v[52:55], v228 offset:8192
	ds_read_b128 v[56:59], v229 offset:8192
	ds_read_b128 v[60:63], v230 offset:8192
	ds_read_b32 v194, v231 offset:384
	ds_read_b128 v[64:67], v223 offset:16384
	ds_read_b128 v[68:71], v224 offset:16384
	ds_read_b128 v[72:75], v225 offset:16384
	ds_read_b128 v[76:79], v226 offset:16384
	ds_read_b128 v[80:83], v223 offset:24576
	ds_read_b128 v[84:87], v224 offset:24576
	global_load_dwordx4 v[156:159], v204, s[40:41] offset:2048
	s_waitcnt lgkmcnt(11)
	ds_read_b128 v[88:91], v225 offset:24576
	ds_read_b128 v[92:95], v226 offset:24576
	global_load_dwordx4 v[160:163], v205, s[40:41] offset:2048
	ds_read_b128 v[96:99], v232 offset:256
	ds_read_b128 v[100:103], v232 offset:384
	global_load_dwordx4 v[148:151], v204, s[40:41]
	s_waitcnt lgkmcnt(11)
	ds_read_b64 v[124:125], v236 offset:45312
	ds_read_b64 v[126:127], v236 offset:49920
	v_mfma_f32_16x16x32_bf16 v[24:27], v[48:51], v[28:31], 0
	global_load_dwordx4 v[152:155], v205, s[40:41]
	v_mfma_f32_16x16x32_bf16 v[24:27], v[52:55], v[32:35], v[24:27]
	v_mfma_f32_16x16x32_bf16 v[24:27], v[56:59], v[40:43], v[24:27]
	global_load_dwordx2 v[164:165], v206, s[40:41]
	v_mfma_f32_16x16x32_bf16 v[24:27], v[60:63], v[44:47], v[24:27]
	ds_read_b64_tr_b16 v[56:57], v234 offset:32768
	global_load_dwordx2 v[166:167], v207, s[42:43] nt
	ds_read_b64_tr_b16 v[58:59], v234 offset:34048
	s_waitcnt lgkmcnt(11)
	ds_read_b64_tr_b16 v[60:61], v234 offset:35328
	ds_read_b64_tr_b16 v[62:63], v234 offset:36608
	global_load_dword v118, v208, s[44:45]
	v_mfma_f32_16x16x32_bf16 v[48:51], v[64:67], v[28:31], 0
	s_waitcnt lgkmcnt(11)
	v_mfma_f32_16x16x32_bf16 v[52:55], v[80:83], v[28:31], 0
	global_load_dword v168, v208, s[46:47]
	v_mfma_f32_16x16x32_bf16 v[48:51], v[68:71], v[32:35], v[48:51]
	s_waitcnt lgkmcnt(10)
	v_mfma_f32_16x16x32_bf16 v[52:55], v[84:87], v[32:35], v[52:55]
	v_mfma_f32_16x16x32_bf16 v[48:51], v[72:75], v[40:43], v[48:51]
	global_load_dword v169, v209, s[46:47]
	s_waitcnt lgkmcnt(9)
	v_mfma_f32_16x16x32_bf16 v[52:55], v[88:91], v[40:43], v[52:55]
	v_mfma_f32_16x16x32_bf16 v[48:51], v[76:79], v[44:47], v[48:51]
	s_add_u32 s66, s54, 3
	s_cmp_lt_u32 s66, s39
	s_cselect_b32 s75, 0xc0000, 0
	s_cselect_b32 s76, 0x280000, 0
	s_cselect_b32 s77, 0x4000, 0
	s_add_u32 s40, s40, s75
	s_addc_u32 s41, s41, 0
	s_add_u32 s42, s42, s76
	s_addc_u32 s43, s43, 0
	s_add_u32 s44, s44, s77
	s_addc_u32 s45, s45, 0
	s_add_u32 s46, s46, s77
	s_addc_u32 s47, s47, 0
	s_waitcnt lgkmcnt(8)
	v_mfma_f32_16x16x32_bf16 v[52:55], v[92:95], v[44:47], v[52:55]
	s_waitcnt vmcnt(10)
	v_exp_f32_e32 v195, v194
	ds_write_b128 v212, v[140:143]
	v_mul_f32_e32 v24, v24, v195
	v_mul_f32_e32 v25, v25, v195
	ds_write_b128 v212, v[144:147] offset:8192
	v_mul_f32_e32 v26, v26, v195
	ds_write_b128 v212, v[132:135] offset:16384
	v_mul_f32_e32 v27, v27, v195
	ds_write_b128 v212, v[136:139] offset:24576
	s_waitcnt lgkmcnt(11)
	v_sub_f32_e32 v184, v194, v96
	v_sub_f32_e32 v200, v117, v116
	v_sub_f32_e32 v185, v194, v97
	v_mul_f32_e32 v200, 0x3fb8aa3b, v200
	v_sub_f32_e32 v186, v194, v98
	v_sub_f32_e32 v187, v194, v99
	v_exp_f32_e32 v200, v200
	v_exp_f32_e32 v184, v184
	v_lshlrev_b32_e32 v196, 16, v4
	v_exp_f32_e32 v185, v185
	v_and_b32_e32 v197, 0xffff0000, v4
	v_exp_f32_e32 v186, v186
	v_lshlrev_b32_e32 v198, 16, v5
	v_exp_f32_e32 v187, v187
	v_and_b32_e32 v199, 0xffff0000, v5
	v_mul_f32_e32 v184, v48, v184
	v_mul_f32_e32 v185, v49, v185
	v_mul_f32_e32 v196, v196, v6
	v_mul_f32_e32 v186, v50, v186
	v_mul_f32_e32 v197, v197, v6
	v_mul_f32_e32 v187, v51, v187
	v_mul_f32_e32 v198, v198, v6
	v_cvt_pk_bf16_f32 v184, v184, v185
	v_mul_f32_e32 v199, v199, v6
	v_cvt_pk_bf16_f32 v185, v186, v187
	v_cvt_pk_bf16_f32 v202, v196, v197
	ds_write_b64 v250, v[184:185] offset:8192
	s_waitcnt lgkmcnt(11)
	v_sub_f32_e32 v188, v194, v100
	v_cvt_pk_bf16_f32 v203, v198, v199
	v_sub_f32_e32 v189, v194, v101
	ds_write_b64 v214, v[202:203] offset:32768
	v_sub_f32_e32 v190, v194, v102
	v_mul_f32_e32 v196, v196, v200
	v_sub_f32_e32 v191, v194, v103
	v_mul_f32_e32 v197, v197, v200
	v_exp_f32_e32 v188, v188
	v_mul_f32_e32 v198, v198, v200
	v_exp_f32_e32 v189, v189
	v_exp_f32_e32 v190, v190
	v_mul_f32_e32 v199, v199, v200
	v_exp_f32_e32 v191, v191
	v_cvt_pk_bf16_f32 v192, v196, v197
	v_mul_f32_e32 v188, v52, v188
	v_cvt_pk_bf16_f32 v193, v198, v199
	v_mul_f32_e32 v189, v53, v189
	ds_write_b64 v214, v[192:193] offset:37888
	v_mul_f32_e32 v190, v54, v190
	ds_write_b64 v216, v[4:5] offset:43008
	v_mul_f32_e32 v191, v55, v191
	v_cndmask_b32_e64 v188, 0, v188, s[14:15]
	ds_write_b64 v216, v[36:37] offset:47616
	v_cndmask_b32_e64 v189, 0, v189, s[16:17]
	v_mul_f32_e32 v201, 0x3fb8aa3b, v116
	v_cndmask_b32_e64 v190, 0, v190, s[22:23]
	s_waitcnt lgkmcnt(11)
	ds_write_b32 v218, v201
	v_cndmask_b32_e64 v191, 0, v191, s[34:35]
	v_mul_f32_e32 v174, 0x3fb8aa3b, v117
	v_cvt_pk_bf16_f32 v188, v188, v189
	v_exp_f32_e32 v174, v174
	v_cvt_pk_bf16_f32 v189, v190, v191
	ds_write_b64 v250, v[188:189] offset:9984
	s_waitcnt lgkmcnt(0)
	s_barrier
; __device__ __forceinline__ void phase_ssd(const Params& P, int seg, unsigned char* smem) {
;     ...
;               for (int i = 0; i < 2; ++i) { const int q = tid + 512 * i, l = q >> 4, c8 = q & 15; *(v4u*)(sb + T_CS + l * 272 + c8 * 16) = R.Cr[i]; *(v4u*)(sb + T_BS + l * 272 + c8 * 16) = R.Br[i]; }
;               const int l = tid >> 3, p4 = (tid & 7) * 4;
;               const float x0 = bflo(R.Xr.x) * R.dtl, x1 = bfhi(R.Xr.x) * R.dtl, x2 = bflo(R.Xr.y) * R.dtl, x3 = bfhi(R.Xr.y) * R.dtl;
;               v2u d; d.x = cvt_pk_bf16(x0, x1); d.y = cvt_pk_bf16(x2, x3); *(v2u*)(sb + T_XD + l * 80 + p4 * 2) = d;
;               v2u e; e.x = cvt_pk_bf16(x0 * e2, x1 * e2); e.y = cvt_pk_bf16(x2 * e2, x3 * e2); *(v2u*)(sb + T_XE + l * 80 + p4 * 2) = e;
;               *(v2u*)(sb + T_XS + l * 64 + p4 * 2) = R.Xr; *(v2u*)(sb + T_ZS + l * 64 + p4 * 2) = R.Zr;
;               if (w == 0) acP[lane] = R.aclane; }
;             BAR_LDS();
;             if (ci + 2 < nchunks) load_chunk(ci + 2, R);
;             bf16x8 cf[4];
; #pragma unroll
;             for (int k = 0; k < 4; ++k) cf[k] = *(const bf16x8*)(sb + T_CS + (lt * 16 + fr) * 272 + (k * 32 + fq * 8) * 2);
;             f32x4 yo = {0.f, 0.f, 0.f, 0.f};
; #pragma unroll
;             for (int k = 0; k < 4; ++k) { const bf16x8 bb = *(const bf16x8*)((const unsigned char*)StR + (pt * 16 + fr) * 272 + (k * 32 + fq * 8) * 2); yo = mfma16(cf[k], bb, yo); }
; { const f32x4 a4 = *(const f32x4*)(acP + lt * 16 + fq * 4);
; #pragma unroll
;               for (int j = 0; j < 4; ++j) yo[j] *= __expf(a4[j]); }
;             const float acl_fr = acP[lt * 16 + fr]; const int lrow = lt * 16 + fr;
; #pragma unroll
;             for (int t = 0; t < 2; ++t) {
;                 if (2 * t <= lt) {
;                     v2u xb0, xb1;
;                     { const unsigned a0 = lds0 + par * T_BUF + T_XD + (32 * t + 4 * fq + tq) * 80 + (pt * 16 + 4 * tp) * 2, a1 = a0 + 16 * 80; TR_ISSUE(xb0, a0); TR_ISSUE(xb1, a1); }
;                     float m[8];
;                     { f32x4 s0 = {0.f, 0.f, 0.f, 0.f}, s1 = {0.f, 0.f, 0.f, 0.f};
; #pragma unroll
;                       for (int k = 0; k < 4; ++k) { const bf16x8 bf0 = *(const bf16x8*)(sb + T_BS + ((2 * t) * 16 + fr) * 272 + (k * 32 + fq * 8) * 2), bf1 = *(const bf16x8*)(sb + T_BS + ((2 * t + 1) * 16 + fr) * 272 + (k * 32 + fq * 8) * 2);
	ds_read_b128 v[128:131], v250 offset:8192
	ds_read_b128 v[184:187], v250 offset:9984
	v_lshlrev_b32_e32 v112, 16, v126
	v_and_b32_e32 v113, 0xffff0000, v126
	v_lshlrev_b32_e32 v114, 16, v127
	v_and_b32_e32 v115, 0xffff0000, v127
	v_mul_f32_e32 v120, 0xbfb8aa3b, v112
	v_mul_f32_e32 v121, 0xbfb8aa3b, v113
	v_mul_f32_e32 v122, 0xbfb8aa3b, v114
	v_mul_f32_e32 v123, 0xbfb8aa3b, v115
	v_exp_f32_e32 v120, v120
	v_exp_f32_e32 v121, v121
	v_exp_f32_e32 v122, v122
	v_exp_f32_e32 v123, v123
	v_add_f32_e32 v120, 1.0, v120
	v_add_f32_e32 v121, 1.0, v121
	v_add_f32_e32 v122, 1.0, v122
	v_add_f32_e32 v123, 1.0, v123
	v_rcp_f32_e32 v120, v120
	v_rcp_f32_e32 v121, v121
	v_rcp_f32_e32 v122, v122
	v_rcp_f32_e32 v123, v123
	v_mul_f32_e32 v112, v120, v112
	v_mul_f32_e32 v113, v121, v113
	v_mul_f32_e32 v114, v122, v114
	v_mul_f32_e32 v115, v123, v115
	v_lshlrev_b32_e32 v120, 16, v124
	v_and_b32_e32 v121, 0xffff0000, v124
	v_lshlrev_b32_e32 v122, 16, v125
	v_and_b32_e32 v123, 0xffff0000, v125
	s_waitcnt lgkmcnt(1)
	v_mfma_f32_16x16x32_bf16 v[24:27], v[56:59], v[128:131], v[24:27]
	s_waitcnt lgkmcnt(0)
	v_mfma_f32_16x16x32_bf16 v[24:27], v[60:63], v[184:187], v[24:27]
	s_mul_i32 s65, s56, 0x2000
	s_add_u32 s65, s65, 0x304f1000
	s_add_u32 s48, s0, s65
	s_addc_u32 s49, s1, 0
	s_nop 3
	v_fma_f32 v188, s61, v120, v24
	v_fma_f32 v189, s61, v121, v25
	v_fma_f32 v190, s61, v122, v26
	v_fma_f32 v191, s61, v123, v27
	v_mul_f32_e32 v188, v188, v112
	v_mul_f32_e32 v189, v189, v113
	v_mul_f32_e32 v190, v190, v114
	v_mul_f32_e32 v191, v191, v115
	v_cvt_pk_bf16_f32 v170, v188, v189
	v_cvt_pk_bf16_f32 v171, v190, v191
	global_store_dwordx2 v210, v[170:171], s[48:49]
	s_add_u32 s65, s54, 1
	s_sub_u32 s65, s65, s60
	s_lshl_b32 s65, s65, 6
	s_add_u32 s56, s65, s20
	s_add_u32 s54, s54, 1
	s_cmp_lt_u32 s54, s39
	s_cbranch_scc1 .Lssd_loop20
	s_branch .Lssd_done
.Lssd_loop21:
	ds_read_b128 v[28:31], v219 offset:8192
	ds_read_b128 v[32:35], v220 offset:8192
	ds_read_b128 v[40:43], v221 offset:8192
	ds_read_b128 v[44:47], v222 offset:8192
	ds_read_b128 v[48:51], v227
	ds_read_b128 v[52:55], v228
	ds_read_b128 v[56:59], v229
	ds_read_b128 v[60:63], v230
	ds_read_b32 v194, v231 offset:128
	ds_read_b128 v[64:67], v219 offset:20480
	global_load_dwordx4 v[140:143], v204, s[40:41] offset:2048
	ds_read_b128 v[68:71], v220 offset:20480
	global_load_dwordx4 v[144:147], v205, s[40:41] offset:2048
	ds_read_b128 v[72:75], v221 offset:20480
	global_load_dwordx4 v[132:135], v204, s[40:41]
	ds_read_b128 v[76:79], v222 offset:20480
	ds_read_b128 v[96:99], v232 offset:64
	global_load_dwordx4 v[136:139], v205, s[40:41]
	ds_read_b64 v[124:125], v235 offset:45312
	global_load_dwordx2 v[4:5], v206, s[40:41]
	s_waitcnt lgkmcnt(11)
	ds_read_b64 v[126:127], v235 offset:49920
	s_waitcnt lgkmcnt(11)
	v_mfma_f32_16x16x32_bf16 v[24:27], v[48:51], v[28:31], 0
	global_load_dwordx2 v[36:37], v207, s[42:43] nt
	s_waitcnt lgkmcnt(10)
	v_mfma_f32_16x16x32_bf16 v[24:27], v[52:55], v[32:35], v[24:27]
	global_load_dword v6, v208, s[44:45]
	s_waitcnt lgkmcnt(9)
	v_mfma_f32_16x16x32_bf16 v[24:27], v[56:59], v[40:43], v[24:27]
	s_waitcnt lgkmcnt(8)
	v_mfma_f32_16x16x32_bf16 v[24:27], v[60:63], v[44:47], v[24:27]
	global_load_dword v116, v208, s[46:47]
	ds_read_b64_tr_b16 v[56:57], v233 offset:32768
	global_load_dword v117, v209, s[46:47]
	ds_read_b64_tr_b16 v[58:59], v233 offset:34048
	ds_read_b64_tr_b16 v[60:61], v233 offset:35328
	s_add_u32 s66, s54, 3
	s_cmp_lt_u32 s66, s39
	s_cselect_b32 s75, 0xc0000, 0
	s_cselect_b32 s76, 0x280000, 0
	s_cselect_b32 s77, 0x4000, 0
	s_add_u32 s40, s40, s75
	s_addc_u32 s41, s41, 0
	s_add_u32 s42, s42, s76
	s_addc_u32 s43, s43, 0
	s_add_u32 s44, s44, s77
	s_addc_u32 s45, s45, 0
	s_add_u32 s46, s46, s77
	s_addc_u32 s47, s47, 0
	ds_read_b64_tr_b16 v[62:63], v233 offset:36608
	s_waitcnt vmcnt(10)
	ds_write_b128 v213, v[156:159]
	s_waitcnt lgkmcnt(11)
	v_mfma_f32_16x16x32_bf16 v[48:51], v[64:67], v[28:31], 0
	ds_write_b128 v213, v[160:163] offset:8192
	s_waitcnt lgkmcnt(11)
	v_mfma_f32_16x16x32_bf16 v[48:51], v[68:71], v[32:35], v[48:51]
	ds_write_b128 v213, v[148:151] offset:16384
	s_waitcnt lgkmcnt(11)
	v_mfma_f32_16x16x32_bf16 v[48:51], v[72:75], v[40:43], v[48:51]
	ds_write_b128 v213, v[152:155] offset:24576
	v_sub_f32_e32 v200, v169, v168
	s_waitcnt lgkmcnt(11)
	v_mfma_f32_16x16x32_bf16 v[48:51], v[76:79], v[44:47], v[48:51]
	v_mul_f32_e32 v200, 0x3fb8aa3b, v200
	v_exp_f32_e32 v195, v194
	v_exp_f32_e32 v200, v200
	v_mul_f32_e32 v24, v24, v195
	v_lshlrev_b32_e32 v196, 16, v164
	v_and_b32_e32 v197, 0xffff0000, v164
	v_mul_f32_e32 v25, v25, v195
	v_lshlrev_b32_e32 v198, 16, v165
	v_mul_f32_e32 v26, v26, v195
	v_and_b32_e32 v199, 0xffff0000, v165
	v_mul_f32_e32 v27, v27, v195
	v_mul_f32_e32 v196, v196, v118
	v_mul_f32_e32 v197, v197, v118
	s_waitcnt lgkmcnt(10)
	v_sub_f32_e32 v184, v194, v96
	v_mul_f32_e32 v198, v198, v118
	v_sub_f32_e32 v185, v194, v97
	v_mul_f32_e32 v199, v199, v118
	v_sub_f32_e32 v186, v194, v98
	v_cvt_pk_bf16_f32 v202, v196, v197
	v_cvt_pk_bf16_f32 v203, v198, v199
	v_sub_f32_e32 v187, v194, v99
	ds_write_b64 v215, v[202:203] offset:32768
	v_exp_f32_e32 v184, v184
	v_mul_f32_e32 v196, v196, v200
	v_exp_f32_e32 v185, v185
	v_mul_f32_e32 v197, v197, v200
	v_mul_f32_e32 v198, v198, v200
	v_exp_f32_e32 v186, v186
	v_mul_f32_e32 v199, v199, v200
	v_exp_f32_e32 v187, v187
	v_cvt_pk_bf16_f32 v192, v196, v197
	v_mul_f32_e32 v184, v48, v184
	v_cvt_pk_bf16_f32 v193, v198, v199
	ds_write_b64 v215, v[192:193] offset:37888
	v_mul_f32_e32 v185, v49, v185
	ds_write_b64 v217, v[164:165] offset:43008
	v_mul_f32_e32 v186, v50, v186
	ds_write_b64 v217, v[166:167] offset:47616
	v_mul_f32_e32 v187, v51, v187
	v_mul_f32_e32 v201, 0x3fb8aa3b, v168
	ds_write_b32 v218, v201 offset:256
	v_cvt_pk_bf16_f32 v184, v184, v185
	v_mul_f32_e32 v174, 0x3fb8aa3b, v169
	v_cvt_pk_bf16_f32 v185, v186, v187
	v_exp_f32_e32 v174, v174
	s_waitcnt lgkmcnt(11)
	ds_write_b64 v250, v[184:185] offset:2056
	s_waitcnt lgkmcnt(0)
	s_barrier
; __device__ __forceinline__ void phase_ssd(const Params& P, int seg, unsigned char* smem) {
;     ...
;               for (int i = 0; i < 2; ++i) { const int q = tid + 512 * i, l = q >> 4, c8 = q & 15; *(v4u*)(sb + T_CS + l * 272 + c8 * 16) = R.Cr[i]; *(v4u*)(sb + T_BS + l * 272 + c8 * 16) = R.Br[i]; }
;               const int l = tid >> 3, p4 = (tid & 7) * 4;
;               const float x0 = bflo(R.Xr.x) * R.dtl, x1 = bfhi(R.Xr.x) * R.dtl, x2 = bflo(R.Xr.y) * R.dtl, x3 = bfhi(R.Xr.y) * R.dtl;
;               v2u d; d.x = cvt_pk_bf16(x0, x1); d.y = cvt_pk_bf16(x2, x3); *(v2u*)(sb + T_XD + l * 80 + p4 * 2) = d;
;               v2u e; e.x = cvt_pk_bf16(x0 * e2, x1 * e2); e.y = cvt_pk_bf16(x2 * e2, x3 * e2); *(v2u*)(sb + T_XE + l * 80 + p4 * 2) = e;
;               *(v2u*)(sb + T_XS + l * 64 + p4 * 2) = R.Xr; *(v2u*)(sb + T_ZS + l * 64 + p4 * 2) = R.Zr;
;               if (w == 0) acP[lane] = R.aclane; }
;             BAR_LDS();
;             if (ci + 2 < nchunks) load_chunk(ci + 2, R);
;             bf16x8 cf[4];
; #pragma unroll
;             for (int k = 0; k < 4; ++k) cf[k] = *(const bf16x8*)(sb + T_CS + (lt * 16 + fr) * 272 + (k * 32 + fq * 8) * 2);
;             f32x4 yo = {0.f, 0.f, 0.f, 0.f};
; #pragma unroll
;             for (int k = 0; k < 4; ++k) { const bf16x8 bb = *(const bf16x8*)((const unsigned char*)StR + (pt * 16 + fr) * 272 + (k * 32 + fq * 8) * 2); yo = mfma16(cf[k], bb, yo); }
; { const f32x4 a4 = *(const f32x4*)(acP + lt * 16 + fq * 4);
; #pragma unroll
;               for (int j = 0; j < 4; ++j) yo[j] *= __expf(a4[j]); }
;             const float acl_fr = acP[lt * 16 + fr]; const int lrow = lt * 16 + fr;
; #pragma unroll
;             for (int t = 0; t < 2; ++t) {
;                 if (2 * t <= lt) {
;                     v2u xb0, xb1;
;                     { const unsigned a0 = lds0 + par * T_BUF + T_XD + (32 * t + 4 * fq + tq) * 80 + (pt * 16 + 4 * tp) * 2, a1 = a0 + 16 * 80; TR_ISSUE(xb0, a0); TR_ISSUE(xb1, a1); }
;                     float m[8];
;                     { f32x4 s0 = {0.f, 0.f, 0.f, 0.f}, s1 = {0.f, 0.f, 0.f, 0.f};
; #pragma unroll
;                       for (int k = 0; k < 4; ++k) { const bf16x8 bf0 = *(const bf16x8*)(sb + T_BS + ((2 * t) * 16 + fr) * 272 + (k * 32 + fq * 8) * 2), bf1 = *(const bf16x8*)(sb + T_BS + ((2 * t + 1) * 16 + fr) * 272 + (k * 32 + fq * 8) * 2);
	ds_read_b128 v[128:131], v250 offset:2048
	ds_read_b128 v[184:187], v250 offset:3072
	v_lshlrev_b32_e32 v112, 16, v126
	v_and_b32_e32 v113, 0xffff0000, v126
	v_lshlrev_b32_e32 v114, 16, v127
	v_and_b32_e32 v115, 0xffff0000, v127
	v_mul_f32_e32 v120, 0xbfb8aa3b, v112
	v_mul_f32_e32 v121, 0xbfb8aa3b, v113
	v_mul_f32_e32 v122, 0xbfb8aa3b, v114
	v_mul_f32_e32 v123, 0xbfb8aa3b, v115
	v_exp_f32_e32 v120, v120
	v_exp_f32_e32 v121, v121
	v_exp_f32_e32 v122, v122
	v_exp_f32_e32 v123, v123
	v_add_f32_e32 v120, 1.0, v120
	v_add_f32_e32 v121, 1.0, v121
	v_add_f32_e32 v122, 1.0, v122
	v_add_f32_e32 v123, 1.0, v123
	v_rcp_f32_e32 v120, v120
	v_rcp_f32_e32 v121, v121
	v_rcp_f32_e32 v122, v122
	v_rcp_f32_e32 v123, v123
	v_mul_f32_e32 v112, v120, v112
	v_mul_f32_e32 v113, v121, v113
	v_mul_f32_e32 v114, v122, v114
	v_mul_f32_e32 v115, v123, v115
	v_lshlrev_b32_e32 v120, 16, v124
	v_and_b32_e32 v121, 0xffff0000, v124
	v_lshlrev_b32_e32 v122, 16, v125
	v_and_b32_e32 v123, 0xffff0000, v125
	s_waitcnt lgkmcnt(1)
	v_mfma_f32_16x16x32_bf16 v[24:27], v[56:59], v[128:131], v[24:27]
	s_waitcnt lgkmcnt(0)
	v_mfma_f32_16x16x32_bf16 v[24:27], v[60:63], v[184:187], v[24:27]
	s_mul_i32 s65, s56, 0x2000
	s_add_u32 s65, s65, 0x304f1000
	s_add_u32 s48, s0, s65
	s_addc_u32 s49, s1, 0
	s_nop 3
	v_fma_f32 v188, s61, v120, v24
	v_fma_f32 v189, s61, v121, v25
	v_fma_f32 v190, s61, v122, v26
	v_fma_f32 v191, s61, v123, v27
	v_mul_f32_e32 v188, v188, v112
	v_mul_f32_e32 v189, v189, v113
	v_mul_f32_e32 v190, v190, v114
	v_mul_f32_e32 v191, v191, v115
	v_cvt_pk_bf16_f32 v170, v188, v189
	v_cvt_pk_bf16_f32 v171, v190, v191
	global_store_dwordx2 v210, v[170:171], s[48:49]
	s_add_u32 s65, s54, 1
	s_sub_u32 s65, s65, s60
	s_lshl_b32 s65, s65, 6
	s_add_u32 s56, s65, s20
	s_add_u32 s54, s54, 1
	s_cmp_ge_u32 s54, s39
	s_cbranch_scc1 .Lssd_done
	ds_read_b128 v[28:31], v223 offset:8192
	ds_read_b128 v[32:35], v224 offset:8192
	ds_read_b128 v[40:43], v225 offset:8192
	ds_read_b128 v[44:47], v226 offset:8192
	ds_read_b128 v[48:51], v227 offset:8192
	ds_read_b128 v[52:55], v228 offset:8192
	ds_read_b128 v[56:59], v229 offset:8192
	ds_read_b128 v[60:63], v230 offset:8192
	ds_read_b32 v194, v231 offset:384
	ds_read_b128 v[64:67], v223 offset:20480
	global_load_dwordx4 v[156:159], v204, s[40:41] offset:2048
	ds_read_b128 v[68:71], v224 offset:20480
	global_load_dwordx4 v[160:163], v205, s[40:41] offset:2048
	ds_read_b128 v[72:75], v225 offset:20480
	global_load_dwordx4 v[148:151], v204, s[40:41]
	ds_read_b128 v[76:79], v226 offset:20480
	ds_read_b128 v[96:99], v232 offset:320
	global_load_dwordx4 v[152:155], v205, s[40:41]
	ds_read_b64 v[124:125], v236 offset:45312
	global_load_dwordx2 v[164:165], v206, s[40:41]
	s_waitcnt lgkmcnt(11)
	ds_read_b64 v[126:127], v236 offset:49920
	s_waitcnt lgkmcnt(11)
	v_mfma_f32_16x16x32_bf16 v[24:27], v[48:51], v[28:31], 0
	global_load_dwordx2 v[166:167], v207, s[42:43] nt
	s_waitcnt lgkmcnt(10)
	v_mfma_f32_16x16x32_bf16 v[24:27], v[52:55], v[32:35], v[24:27]
	global_load_dword v118, v208, s[44:45]
	s_waitcnt lgkmcnt(9)
	v_mfma_f32_16x16x32_bf16 v[24:27], v[56:59], v[40:43], v[24:27]
	s_waitcnt lgkmcnt(8)
	v_mfma_f32_16x16x32_bf16 v[24:27], v[60:63], v[44:47], v[24:27]
	global_load_dword v168, v208, s[46:47]
	ds_read_b64_tr_b16 v[56:57], v234 offset:32768
	global_load_dword v169, v209, s[46:47]
	ds_read_b64_tr_b16 v[58:59], v234 offset:34048
	ds_read_b64_tr_b16 v[60:61], v234 offset:35328
	s_add_u32 s66, s54, 3
	s_cmp_lt_u32 s66, s39
	s_cselect_b32 s75, 0xc0000, 0
	s_cselect_b32 s76, 0x280000, 0
	s_cselect_b32 s77, 0x4000, 0
	s_add_u32 s40, s40, s75
	s_addc_u32 s41, s41, 0
	s_add_u32 s42, s42, s76
	s_addc_u32 s43, s43, 0
	s_add_u32 s44, s44, s77
	s_addc_u32 s45, s45, 0
	s_add_u32 s46, s46, s77
	s_addc_u32 s47, s47, 0
	ds_read_b64_tr_b16 v[62:63], v234 offset:36608
	s_waitcnt vmcnt(10)
	ds_write_b128 v212, v[140:143]
	s_waitcnt lgkmcnt(11)
	v_mfma_f32_16x16x32_bf16 v[48:51], v[64:67], v[28:31], 0
	ds_write_b128 v212, v[144:147] offset:8192
	s_waitcnt lgkmcnt(11)
	v_mfma_f32_16x16x32_bf16 v[48:51], v[68:71], v[32:35], v[48:51]
	ds_write_b128 v212, v[132:135] offset:16384
	s_waitcnt lgkmcnt(11)
	v_mfma_f32_16x16x32_bf16 v[48:51], v[72:75], v[40:43], v[48:51]
	ds_write_b128 v212, v[136:139] offset:24576
	v_sub_f32_e32 v200, v117, v116
	s_waitcnt lgkmcnt(11)
	v_mfma_f32_16x16x32_bf16 v[48:51], v[76:79], v[44:47], v[48:51]
	v_mul_f32_e32 v200, 0x3fb8aa3b, v200
	v_exp_f32_e32 v195, v194
	v_exp_f32_e32 v200, v200
	v_mul_f32_e32 v24, v24, v195
	v_lshlrev_b32_e32 v196, 16, v4
	v_and_b32_e32 v197, 0xffff0000, v4
	v_mul_f32_e32 v25, v25, v195
	v_lshlrev_b32_e32 v198, 16, v5
	v_mul_f32_e32 v26, v26, v195
	v_and_b32_e32 v199, 0xffff0000, v5
	v_mul_f32_e32 v27, v27, v195
	v_mul_f32_e32 v196, v196, v6
	v_mul_f32_e32 v197, v197, v6
	s_waitcnt lgkmcnt(10)
	v_sub_f32_e32 v184, v194, v96
	v_mul_f32_e32 v198, v198, v6
	v_sub_f32_e32 v185, v194, v97
	v_mul_f32_e32 v199, v199, v6
	v_sub_f32_e32 v186, v194, v98
	v_cvt_pk_bf16_f32 v202, v196, v197
	v_cvt_pk_bf16_f32 v203, v198, v199
	v_sub_f32_e32 v187, v194, v99
	ds_write_b64 v214, v[202:203] offset:32768
	v_exp_f32_e32 v184, v184
	v_mul_f32_e32 v196, v196, v200
	v_exp_f32_e32 v185, v185
	v_mul_f32_e32 v197, v197, v200
	v_mul_f32_e32 v198, v198, v200
	v_exp_f32_e32 v186, v186
	v_mul_f32_e32 v199, v199, v200
	v_exp_f32_e32 v187, v187
	v_cvt_pk_bf16_f32 v192, v196, v197
	v_mul_f32_e32 v184, v48, v184
	v_cvt_pk_bf16_f32 v193, v198, v199
	ds_write_b64 v214, v[192:193] offset:37888
	v_mul_f32_e32 v185, v49, v185
	ds_write_b64 v216, v[4:5] offset:43008
	v_mul_f32_e32 v186, v50, v186
	ds_write_b64 v216, v[36:37] offset:47616
	v_mul_f32_e32 v187, v51, v187
	v_mul_f32_e32 v201, 0x3fb8aa3b, v116
	ds_write_b32 v218, v201
	v_cvt_pk_bf16_f32 v184, v184, v185
	v_mul_f32_e32 v174, 0x3fb8aa3b, v117
	v_cvt_pk_bf16_f32 v185, v186, v187
	v_exp_f32_e32 v174, v174
	s_waitcnt lgkmcnt(11)
	ds_write_b64 v250, v[184:185] offset:8200
	s_waitcnt lgkmcnt(0)
	s_barrier
; __device__ __forceinline__ void phase_ssd(const Params& P, int seg, unsigned char* smem) {
;     ...
;               for (int i = 0; i < 2; ++i) { const int q = tid + 512 * i, l = q >> 4, c8 = q & 15; *(v4u*)(sb + T_CS + l * 272 + c8 * 16) = R.Cr[i]; *(v4u*)(sb + T_BS + l * 272 + c8 * 16) = R.Br[i]; }
;               const int l = tid >> 3, p4 = (tid & 7) * 4;
;               const float x0 = bflo(R.Xr.x) * R.dtl, x1 = bfhi(R.Xr.x) * R.dtl, x2 = bflo(R.Xr.y) * R.dtl, x3 = bfhi(R.Xr.y) * R.dtl;
;               v2u d; d.x = cvt_pk_bf16(x0, x1); d.y = cvt_pk_bf16(x2, x3); *(v2u*)(sb + T_XD + l * 80 + p4 * 2) = d;
;               v2u e; e.x = cvt_pk_bf16(x0 * e2, x1 * e2); e.y = cvt_pk_bf16(x2 * e2, x3 * e2); *(v2u*)(sb + T_XE + l * 80 + p4 * 2) = e;
;               *(v2u*)(sb + T_XS + l * 64 + p4 * 2) = R.Xr; *(v2u*)(sb + T_ZS + l * 64 + p4 * 2) = R.Zr;
;               if (w == 0) acP[lane] = R.aclane; }
;             BAR_LDS();
;             if (ci + 2 < nchunks) load_chunk(ci + 2, R);
;             bf16x8 cf[4];
; #pragma unroll
;             for (int k = 0; k < 4; ++k) cf[k] = *(const bf16x8*)(sb + T_CS + (lt * 16 + fr) * 272 + (k * 32 + fq * 8) * 2);
;             f32x4 yo = {0.f, 0.f, 0.f, 0.f};
; #pragma unroll
;             for (int k = 0; k < 4; ++k) { const bf16x8 bb = *(const bf16x8*)((const unsigned char*)StR + (pt * 16 + fr) * 272 + (k * 32 + fq * 8) * 2); yo = mfma16(cf[k], bb, yo); }
; { const f32x4 a4 = *(const f32x4*)(acP + lt * 16 + fq * 4);
; #pragma unroll
;               for (int j = 0; j < 4; ++j) yo[j] *= __expf(a4[j]); }
;             const float acl_fr = acP[lt * 16 + fr]; const int lrow = lt * 16 + fr;
; #pragma unroll
;             for (int t = 0; t < 2; ++t) {
;                 if (2 * t <= lt) {
;                     v2u xb0, xb1;
;                     { const unsigned a0 = lds0 + par * T_BUF + T_XD + (32 * t + 4 * fq + tq) * 80 + (pt * 16 + 4 * tp) * 2, a1 = a0 + 16 * 80; TR_ISSUE(xb0, a0); TR_ISSUE(xb1, a1); }
;                     float m[8];
;                     { f32x4 s0 = {0.f, 0.f, 0.f, 0.f}, s1 = {0.f, 0.f, 0.f, 0.f};
; #pragma unroll
;                       for (int k = 0; k < 4; ++k) { const bf16x8 bf0 = *(const bf16x8*)(sb + T_BS + ((2 * t) * 16 + fr) * 272 + (k * 32 + fq * 8) * 2), bf1 = *(const bf16x8*)(sb + T_BS + ((2 * t + 1) * 16 + fr) * 272 + (k * 32 + fq * 8) * 2);
	ds_read_b128 v[128:131], v250 offset:8192
	ds_read_b128 v[184:187], v250 offset:9984
	v_lshlrev_b32_e32 v112, 16, v126
	v_and_b32_e32 v113, 0xffff0000, v126
	v_lshlrev_b32_e32 v114, 16, v127
	v_and_b32_e32 v115, 0xffff0000, v127
	v_mul_f32_e32 v120, 0xbfb8aa3b, v112
	v_mul_f32_e32 v121, 0xbfb8aa3b, v113
	v_mul_f32_e32 v122, 0xbfb8aa3b, v114
	v_mul_f32_e32 v123, 0xbfb8aa3b, v115
	v_exp_f32_e32 v120, v120
	v_exp_f32_e32 v121, v121
	v_exp_f32_e32 v122, v122
	v_exp_f32_e32 v123, v123
	v_add_f32_e32 v120, 1.0, v120
	v_add_f32_e32 v121, 1.0, v121
	v_add_f32_e32 v122, 1.0, v122
	v_add_f32_e32 v123, 1.0, v123
	v_rcp_f32_e32 v120, v120
	v_rcp_f32_e32 v121, v121
	v_rcp_f32_e32 v122, v122
	v_rcp_f32_e32 v123, v123
	v_mul_f32_e32 v112, v120, v112
	v_mul_f32_e32 v113, v121, v113
	v_mul_f32_e32 v114, v122, v114
	v_mul_f32_e32 v115, v123, v115
	v_lshlrev_b32_e32 v120, 16, v124
	v_and_b32_e32 v121, 0xffff0000, v124
	v_lshlrev_b32_e32 v122, 16, v125
	v_and_b32_e32 v123, 0xffff0000, v125
	s_waitcnt lgkmcnt(1)
	v_mfma_f32_16x16x32_bf16 v[24:27], v[56:59], v[128:131], v[24:27]
	s_waitcnt lgkmcnt(0)
	v_mfma_f32_16x16x32_bf16 v[24:27], v[60:63], v[184:187], v[24:27]
	s_mul_i32 s65, s56, 0x2000
	s_add_u32 s65, s65, 0x304f1000
	s_add_u32 s48, s0, s65
	s_addc_u32 s49, s1, 0
	s_nop 3
	v_fma_f32 v188, s61, v120, v24
	v_fma_f32 v189, s61, v121, v25
	v_fma_f32 v190, s61, v122, v26
	v_fma_f32 v191, s61, v123, v27
	v_mul_f32_e32 v188, v188, v112
	v_mul_f32_e32 v189, v189, v113
	v_mul_f32_e32 v190, v190, v114
	v_mul_f32_e32 v191, v191, v115
	v_cvt_pk_bf16_f32 v170, v188, v189
	v_cvt_pk_bf16_f32 v171, v190, v191
	global_store_dwordx2 v210, v[170:171], s[48:49]
	s_add_u32 s65, s54, 1
	s_sub_u32 s65, s65, s60
	s_lshl_b32 s65, s65, 6
	s_add_u32 s56, s65, s20
	s_add_u32 s54, s54, 1
	s_cmp_lt_u32 s54, s39
	s_cbranch_scc1 .Lssd_loop21
	s_branch .Lssd_done
.Lssd_loop30:
	ds_read_b128 v[28:31], v219 offset:12288
	ds_read_b128 v[32:35], v220 offset:12288
	ds_read_b128 v[40:43], v221 offset:12288
	ds_read_b128 v[44:47], v222 offset:12288
	ds_read_b128 v[48:51], v227
	ds_read_b128 v[52:55], v228
	ds_read_b128 v[56:59], v229
	ds_read_b128 v[60:63], v230
	ds_read_b32 v194, v231 offset:192
	ds_read_b128 v[64:67], v219 offset:16384
	ds_read_b128 v[68:71], v220 offset:16384
	ds_read_b128 v[72:75], v221 offset:16384
	ds_read_b128 v[76:79], v222 offset:16384
	ds_read_b128 v[80:83], v219 offset:24576
	ds_read_b128 v[84:87], v220 offset:24576
	global_load_dwordx4 v[140:143], v204, s[40:41] offset:2048
	s_waitcnt lgkmcnt(11)
	ds_read_b128 v[88:91], v221 offset:24576
	ds_read_b128 v[92:95], v222 offset:24576
	global_load_dwordx4 v[144:147], v205, s[40:41] offset:2048
	ds_read_b128 v[96:99], v232
	ds_read_b128 v[100:103], v232 offset:128
	global_load_dwordx4 v[132:135], v204, s[40:41]
	s_waitcnt lgkmcnt(11)
	ds_read_b64 v[124:125], v235 offset:46464
	ds_read_b64 v[126:127], v235 offset:51072
	global_load_dwordx4 v[136:139], v205, s[40:41]
	v_mfma_f32_16x16x32_bf16 v[24:27], v[48:51], v[28:31], 0
	v_mfma_f32_16x16x32_bf16 v[24:27], v[52:55], v[32:35], v[24:27]
	global_load_dwordx2 v[4:5], v206, s[40:41]
	v_mfma_f32_16x16x32_bf16 v[24:27], v[56:59], v[40:43], v[24:27]
	v_mfma_f32_16x16x32_bf16 v[24:27], v[60:63], v[44:47], v[24:27]
	ds_read_b64_tr_b16 v[56:57], v233 offset:32768
	global_load_dwordx2 v[36:37], v207, s[42:43] nt
	ds_read_b64_tr_b16 v[58:59], v233 offset:34048
	s_waitcnt lgkmcnt(11)
	ds_read_b64_tr_b16 v[60:61], v233 offset:35328
	global_load_dword v6, v208, s[44:45]
	ds_read_b64_tr_b16 v[62:63], v233 offset:36608
	v_mfma_f32_16x16x32_bf16 v[48:51], v[64:67], v[28:31], 0
	global_load_dword v116, v208, s[46:47]
	s_waitcnt lgkmcnt(11)
	v_mfma_f32_16x16x32_bf16 v[52:55], v[80:83], v[28:31], 0
	v_mfma_f32_16x16x32_bf16 v[48:51], v[68:71], v[32:35], v[48:51]
	global_load_dword v117, v209, s[46:47]
	s_waitcnt lgkmcnt(10)
	v_mfma_f32_16x16x32_bf16 v[52:55], v[84:87], v[32:35], v[52:55]
	v_mfma_f32_16x16x32_bf16 v[48:51], v[72:75], v[40:43], v[48:51]
	s_waitcnt lgkmcnt(9)
	v_mfma_f32_16x16x32_bf16 v[52:55], v[88:91], v[40:43], v[52:55]
	s_add_u32 s66, s54, 3
	s_cmp_lt_u32 s66, s39
	s_cselect_b32 s75, 0xc0000, 0
	s_cselect_b32 s76, 0x280000, 0
	s_cselect_b32 s77, 0x4000, 0
	s_add_u32 s40, s40, s75
	s_addc_u32 s41, s41, 0
	s_add_u32 s42, s42, s76
	s_addc_u32 s43, s43, 0
	s_add_u32 s44, s44, s77
	s_addc_u32 s45, s45, 0
	s_add_u32 s46, s46, s77
	s_addc_u32 s47, s47, 0
	v_mfma_f32_16x16x32_bf16 v[48:51], v[76:79], v[44:47], v[48:51]
	s_waitcnt vmcnt(10)
	s_waitcnt lgkmcnt(8)
	v_mfma_f32_16x16x32_bf16 v[52:55], v[92:95], v[44:47], v[52:55]
	ds_write_b128 v213, v[156:159]
	v_exp_f32_e32 v195, v194
	ds_write_b128 v213, v[160:163] offset:8192
	v_mul_f32_e32 v24, v24, v195
	ds_write_b128 v213, v[148:151] offset:16384
	v_mul_f32_e32 v25, v25, v195
	ds_write_b128 v213, v[152:155] offset:24576
	v_mul_f32_e32 v26, v26, v195
	v_sub_f32_e32 v200, v169, v168
	v_mul_f32_e32 v27, v27, v195
	v_mul_f32_e32 v200, 0x3fb8aa3b, v200
	s_waitcnt lgkmcnt(11)
	v_sub_f32_e32 v184, v194, v96
	v_sub_f32_e32 v185, v194, v97
	v_exp_f32_e32 v200, v200
	v_sub_f32_e32 v186, v194, v98
	v_lshlrev_b32_e32 v196, 16, v164
	v_sub_f32_e32 v187, v194, v99
	v_and_b32_e32 v197, 0xffff0000, v164
	v_exp_f32_e32 v184, v184
	v_lshlrev_b32_e32 v198, 16, v165
	v_exp_f32_e32 v185, v185
	v_and_b32_e32 v199, 0xffff0000, v165
	v_exp_f32_e32 v186, v186
	v_mul_f32_e32 v196, v196, v118
	v_exp_f32_e32 v187, v187
	v_mul_f32_e32 v197, v197, v118
	v_mul_f32_e32 v184, v48, v184
	v_mul_f32_e32 v198, v198, v118
	v_mul_f32_e32 v185, v49, v185
	v_mul_f32_e32 v186, v50, v186
	v_mul_f32_e32 v199, v199, v118
	v_mul_f32_e32 v187, v51, v187
	v_cvt_pk_bf16_f32 v202, v196, v197
	v_cvt_pk_bf16_f32 v184, v184, v185
	v_cvt_pk_bf16_f32 v203, v198, v199
	v_cvt_pk_bf16_f32 v185, v186, v187
	ds_write_b64 v215, v[202:203] offset:32768
	ds_write_b64 v250, v[184:185] offset:4096
	v_mul_f32_e32 v196, v196, v200
	s_waitcnt lgkmcnt(12)
	v_sub_f32_e32 v188, v194, v100
	v_mul_f32_e32 v197, v197, v200
	v_sub_f32_e32 v189, v194, v101
	v_mul_f32_e32 v198, v198, v200
	v_sub_f32_e32 v190, v194, v102
	v_mul_f32_e32 v199, v199, v200
	v_sub_f32_e32 v191, v194, v103
	v_cvt_pk_bf16_f32 v192, v196, v197
	v_exp_f32_e32 v188, v188
	v_exp_f32_e32 v189, v189
	v_cvt_pk_bf16_f32 v193, v198, v199
	v_exp_f32_e32 v190, v190
	ds_write_b64 v215, v[192:193] offset:37888
	v_exp_f32_e32 v191, v191
	ds_write_b64 v217, v[164:165] offset:43008
	v_mul_f32_e32 v188, v52, v188
	ds_write_b64 v217, v[166:167] offset:47616
	v_mul_f32_e32 v189, v53, v189
	v_mul_f32_e32 v201, 0x3fb8aa3b, v168
	v_mul_f32_e32 v190, v54, v190
	s_waitcnt lgkmcnt(11)
	ds_write_b32 v218, v201 offset:256
	v_mul_f32_e32 v191, v55, v191
	v_mul_f32_e32 v174, 0x3fb8aa3b, v169
	v_cvt_pk_bf16_f32 v188, v188, v189
	v_exp_f32_e32 v174, v174
	v_cvt_pk_bf16_f32 v189, v190, v191
	ds_write_b64 v250, v[188:189] offset:5120
	s_waitcnt lgkmcnt(0)
	s_barrier
; __device__ __forceinline__ void phase_ssd(const Params& P, int seg, unsigned char* smem) {
;     ...
;               for (int i = 0; i < 2; ++i) { const int q = tid + 512 * i, l = q >> 4, c8 = q & 15; *(v4u*)(sb + T_CS + l * 272 + c8 * 16) = R.Cr[i]; *(v4u*)(sb + T_BS + l * 272 + c8 * 16) = R.Br[i]; }
;               const int l = tid >> 3, p4 = (tid & 7) * 4;
;               const float x0 = bflo(R.Xr.x) * R.dtl, x1 = bfhi(R.Xr.x) * R.dtl, x2 = bflo(R.Xr.y) * R.dtl, x3 = bfhi(R.Xr.y) * R.dtl;
;               v2u d; d.x = cvt_pk_bf16(x0, x1); d.y = cvt_pk_bf16(x2, x3); *(v2u*)(sb + T_XD + l * 80 + p4 * 2) = d;
;               v2u e; e.x = cvt_pk_bf16(x0 * e2, x1 * e2); e.y = cvt_pk_bf16(x2 * e2, x3 * e2); *(v2u*)(sb + T_XE + l * 80 + p4 * 2) = e;
;               *(v2u*)(sb + T_XS + l * 64 + p4 * 2) = R.Xr; *(v2u*)(sb + T_ZS + l * 64 + p4 * 2) = R.Zr;
;               if (w == 0) acP[lane] = R.aclane; }
;             BAR_LDS();
;             if (ci + 2 < nchunks) load_chunk(ci + 2, R);
;             bf16x8 cf[4];
; #pragma unroll
;             for (int k = 0; k < 4; ++k) cf[k] = *(const bf16x8*)(sb + T_CS + (lt * 16 + fr) * 272 + (k * 32 + fq * 8) * 2);
;             f32x4 yo = {0.f, 0.f, 0.f, 0.f};
; #pragma unroll
;             for (int k = 0; k < 4; ++k) { const bf16x8 bb = *(const bf16x8*)((const unsigned char*)StR + (pt * 16 + fr) * 272 + (k * 32 + fq * 8) * 2); yo = mfma16(cf[k], bb, yo); }
; { const f32x4 a4 = *(const f32x4*)(acP + lt * 16 + fq * 4);
; #pragma unroll
;               for (int j = 0; j < 4; ++j) yo[j] *= __expf(a4[j]); }
;             const float acl_fr = acP[lt * 16 + fr]; const int lrow = lt * 16 + fr;
; #pragma unroll
;             for (int t = 0; t < 2; ++t) {
;                 if (2 * t <= lt) {
;                     v2u xb0, xb1;
;                     { const unsigned a0 = lds0 + par * T_BUF + T_XD + (32 * t + 4 * fq + tq) * 80 + (pt * 16 + 4 * tp) * 2, a1 = a0 + 16 * 80; TR_ISSUE(xb0, a0); TR_ISSUE(xb1, a1); }
;                     float m[8];
;                     { f32x4 s0 = {0.f, 0.f, 0.f, 0.f}, s1 = {0.f, 0.f, 0.f, 0.f};
; #pragma unroll
;                       for (int k = 0; k < 4; ++k) { const bf16x8 bf0 = *(const bf16x8*)(sb + T_BS + ((2 * t) * 16 + fr) * 272 + (k * 32 + fq * 8) * 2), bf1 = *(const bf16x8*)(sb + T_BS + ((2 * t + 1) * 16 + fr) * 272 + (k * 32 + fq * 8) * 2);
	ds_read_b128 v[128:131], v250 offset:4096
	ds_read_b128 v[184:187], v250 offset:5120
	v_lshlrev_b32_e32 v112, 16, v126
	v_and_b32_e32 v113, 0xffff0000, v126
	v_lshlrev_b32_e32 v114, 16, v127
	v_and_b32_e32 v115, 0xffff0000, v127
	v_mul_f32_e32 v120, 0xbfb8aa3b, v112
	v_mul_f32_e32 v121, 0xbfb8aa3b, v113
	v_mul_f32_e32 v122, 0xbfb8aa3b, v114
	v_mul_f32_e32 v123, 0xbfb8aa3b, v115
	v_exp_f32_e32 v120, v120
	v_exp_f32_e32 v121, v121
	v_exp_f32_e32 v122, v122
	v_exp_f32_e32 v123, v123
	v_add_f32_e32 v120, 1.0, v120
	v_add_f32_e32 v121, 1.0, v121
	v_add_f32_e32 v122, 1.0, v122
	v_add_f32_e32 v123, 1.0, v123
	v_rcp_f32_e32 v120, v120
	v_rcp_f32_e32 v121, v121
	v_rcp_f32_e32 v122, v122
	v_rcp_f32_e32 v123, v123
	v_mul_f32_e32 v112, v120, v112
	v_mul_f32_e32 v113, v121, v113
	v_mul_f32_e32 v114, v122, v114
	v_mul_f32_e32 v115, v123, v115
	v_lshlrev_b32_e32 v120, 16, v124
	v_and_b32_e32 v121, 0xffff0000, v124
	v_lshlrev_b32_e32 v122, 16, v125
	v_and_b32_e32 v123, 0xffff0000, v125
	s_waitcnt lgkmcnt(1)
	v_mfma_f32_16x16x32_bf16 v[24:27], v[56:59], v[128:131], v[24:27]
	s_waitcnt lgkmcnt(0)
	v_mfma_f32_16x16x32_bf16 v[24:27], v[60:63], v[184:187], v[24:27]
	s_mul_i32 s65, s56, 0x2000
	s_add_u32 s65, s65, 0x304f1000
	s_add_u32 s48, s0, s65
	s_addc_u32 s49, s1, 0
	s_nop 3
	v_fma_f32 v188, s61, v120, v24
	v_fma_f32 v189, s61, v121, v25
	v_fma_f32 v190, s61, v122, v26
	v_fma_f32 v191, s61, v123, v27
	v_mul_f32_e32 v188, v188, v112
	v_mul_f32_e32 v189, v189, v113
	v_mul_f32_e32 v190, v190, v114
	v_mul_f32_e32 v191, v191, v115
	v_cvt_pk_bf16_f32 v170, v188, v189
	v_cvt_pk_bf16_f32 v171, v190, v191
	global_store_dwordx2 v210, v[170:171], s[48:49]
	s_add_u32 s65, s54, 1
	s_sub_u32 s65, s65, s60
	s_lshl_b32 s65, s65, 6
	s_add_u32 s56, s65, s20
	s_add_u32 s54, s54, 1
	s_cmp_ge_u32 s54, s39
	s_cbranch_scc1 .Lssd_done
	ds_read_b128 v[28:31], v223 offset:12288
	ds_read_b128 v[32:35], v224 offset:12288
	ds_read_b128 v[40:43], v225 offset:12288
	ds_read_b128 v[44:47], v226 offset:12288
	ds_read_b128 v[48:51], v227 offset:8192
	ds_read_b128 v[52:55], v228 offset:8192
	ds_read_b128 v[56:59], v229 offset:8192
	ds_read_b128 v[60:63], v230 offset:8192
	ds_read_b32 v194, v231 offset:448
	ds_read_b128 v[64:67], v223 offset:16384
	ds_read_b128 v[68:71], v224 offset:16384
	ds_read_b128 v[72:75], v225 offset:16384
	ds_read_b128 v[76:79], v226 offset:16384
	ds_read_b128 v[80:83], v223 offset:24576
	ds_read_b128 v[84:87], v224 offset:24576
	global_load_dwordx4 v[156:159], v204, s[40:41] offset:2048
	s_waitcnt lgkmcnt(11)
	ds_read_b128 v[88:91], v225 offset:24576
	ds_read_b128 v[92:95], v226 offset:24576
	global_load_dwordx4 v[160:163], v205, s[40:41] offset:2048
	ds_read_b128 v[96:99], v232 offset:256
	ds_read_b128 v[100:103], v232 offset:384
	global_load_dwordx4 v[148:151], v204, s[40:41]
	s_waitcnt lgkmcnt(11)
	ds_read_b64 v[124:125], v236 offset:46464
	ds_read_b64 v[126:127], v236 offset:51072
	global_load_dwordx4 v[152:155], v205, s[40:41]
	v_mfma_f32_16x16x32_bf16 v[24:27], v[48:51], v[28:31], 0
	v_mfma_f32_16x16x32_bf16 v[24:27], v[52:55], v[32:35], v[24:27]
	global_load_dwordx2 v[164:165], v206, s[40:41]
	v_mfma_f32_16x16x32_bf16 v[24:27], v[56:59], v[40:43], v[24:27]
	v_mfma_f32_16x16x32_bf16 v[24:27], v[60:63], v[44:47], v[24:27]
	ds_read_b64_tr_b16 v[56:57], v234 offset:32768
	global_load_dwordx2 v[166:167], v207, s[42:43] nt
	ds_read_b64_tr_b16 v[58:59], v234 offset:34048
	s_waitcnt lgkmcnt(11)
	ds_read_b64_tr_b16 v[60:61], v234 offset:35328
	global_load_dword v118, v208, s[44:45]
	ds_read_b64_tr_b16 v[62:63], v234 offset:36608
	v_mfma_f32_16x16x32_bf16 v[48:51], v[64:67], v[28:31], 0
	global_load_dword v168, v208, s[46:47]
	s_waitcnt lgkmcnt(11)
	v_mfma_f32_16x16x32_bf16 v[52:55], v[80:83], v[28:31], 0
	v_mfma_f32_16x16x32_bf16 v[48:51], v[68:71], v[32:35], v[48:51]
	global_load_dword v169, v209, s[46:47]
	s_waitcnt lgkmcnt(10)
	v_mfma_f32_16x16x32_bf16 v[52:55], v[84:87], v[32:35], v[52:55]
	v_mfma_f32_16x16x32_bf16 v[48:51], v[72:75], v[40:43], v[48:51]
	s_waitcnt lgkmcnt(9)
	v_mfma_f32_16x16x32_bf16 v[52:55], v[88:91], v[40:43], v[52:55]
	s_add_u32 s66, s54, 3
	s_cmp_lt_u32 s66, s39
	s_cselect_b32 s75, 0xc0000, 0
	s_cselect_b32 s76, 0x280000, 0
	s_cselect_b32 s77, 0x4000, 0
	s_add_u32 s40, s40, s75
	s_addc_u32 s41, s41, 0
	s_add_u32 s42, s42, s76
	s_addc_u32 s43, s43, 0
	s_add_u32 s44, s44, s77
	s_addc_u32 s45, s45, 0
	s_add_u32 s46, s46, s77
	s_addc_u32 s47, s47, 0
	v_mfma_f32_16x16x32_bf16 v[48:51], v[76:79], v[44:47], v[48:51]
	s_waitcnt vmcnt(10)
	s_waitcnt lgkmcnt(8)
	v_mfma_f32_16x16x32_bf16 v[52:55], v[92:95], v[44:47], v[52:55]
	ds_write_b128 v212, v[140:143]
	v_exp_f32_e32 v195, v194
	ds_write_b128 v212, v[144:147] offset:8192
	v_mul_f32_e32 v24, v24, v195
	ds_write_b128 v212, v[132:135] offset:16384
	v_mul_f32_e32 v25, v25, v195
	ds_write_b128 v212, v[136:139] offset:24576
	v_mul_f32_e32 v26, v26, v195
	v_sub_f32_e32 v200, v117, v116
	v_mul_f32_e32 v27, v27, v195
	v_mul_f32_e32 v200, 0x3fb8aa3b, v200
	s_waitcnt lgkmcnt(11)
	v_sub_f32_e32 v184, v194, v96
	v_sub_f32_e32 v185, v194, v97
	v_exp_f32_e32 v200, v200
	v_sub_f32_e32 v186, v194, v98
	v_lshlrev_b32_e32 v196, 16, v4
	v_sub_f32_e32 v187, v194, v99
	v_and_b32_e32 v197, 0xffff0000, v4
	v_exp_f32_e32 v184, v184
	v_lshlrev_b32_e32 v198, 16, v5
	v_exp_f32_e32 v185, v185
	v_and_b32_e32 v199, 0xffff0000, v5
	v_exp_f32_e32 v186, v186
	v_mul_f32_e32 v196, v196, v6
	v_exp_f32_e32 v187, v187
	v_mul_f32_e32 v197, v197, v6
	v_mul_f32_e32 v184, v48, v184
	v_mul_f32_e32 v198, v198, v6
	v_mul_f32_e32 v185, v49, v185
	v_mul_f32_e32 v186, v50, v186
	v_mul_f32_e32 v199, v199, v6
	v_mul_f32_e32 v187, v51, v187
	v_cvt_pk_bf16_f32 v202, v196, v197
	v_cvt_pk_bf16_f32 v184, v184, v185
	v_cvt_pk_bf16_f32 v203, v198, v199
	v_cvt_pk_bf16_f32 v185, v186, v187
	ds_write_b64 v214, v[202:203] offset:32768
	ds_write_b64 v250, v[184:185] offset:11008
	v_mul_f32_e32 v196, v196, v200
	s_waitcnt lgkmcnt(12)
	v_sub_f32_e32 v188, v194, v100
	v_mul_f32_e32 v197, v197, v200
	v_sub_f32_e32 v189, v194, v101
	v_mul_f32_e32 v198, v198, v200
	v_sub_f32_e32 v190, v194, v102
	v_mul_f32_e32 v199, v199, v200
	v_sub_f32_e32 v191, v194, v103
	v_cvt_pk_bf16_f32 v192, v196, v197
	v_exp_f32_e32 v188, v188
	v_exp_f32_e32 v189, v189
	v_cvt_pk_bf16_f32 v193, v198, v199
	v_exp_f32_e32 v190, v190
	ds_write_b64 v214, v[192:193] offset:37888
	v_exp_f32_e32 v191, v191
	ds_write_b64 v216, v[4:5] offset:43008
	v_mul_f32_e32 v188, v52, v188
	ds_write_b64 v216, v[36:37] offset:47616
	v_mul_f32_e32 v189, v53, v189
	v_mul_f32_e32 v201, 0x3fb8aa3b, v116
	v_mul_f32_e32 v190, v54, v190
	s_waitcnt lgkmcnt(11)
	ds_write_b32 v218, v201
	v_mul_f32_e32 v191, v55, v191
	v_mul_f32_e32 v174, 0x3fb8aa3b, v117
	v_cvt_pk_bf16_f32 v188, v188, v189
	v_exp_f32_e32 v174, v174
	v_cvt_pk_bf16_f32 v189, v190, v191
	ds_write_b64 v250, v[188:189] offset:12032
	s_waitcnt lgkmcnt(0)
	s_barrier
; __device__ __forceinline__ void phase_ssd(const Params& P, int seg, unsigned char* smem) {
;     ...
;               for (int i = 0; i < 2; ++i) { const int q = tid + 512 * i, l = q >> 4, c8 = q & 15; *(v4u*)(sb + T_CS + l * 272 + c8 * 16) = R.Cr[i]; *(v4u*)(sb + T_BS + l * 272 + c8 * 16) = R.Br[i]; }
;               const int l = tid >> 3, p4 = (tid & 7) * 4;
;               const float x0 = bflo(R.Xr.x) * R.dtl, x1 = bfhi(R.Xr.x) * R.dtl, x2 = bflo(R.Xr.y) * R.dtl, x3 = bfhi(R.Xr.y) * R.dtl;
;               v2u d; d.x = cvt_pk_bf16(x0, x1); d.y = cvt_pk_bf16(x2, x3); *(v2u*)(sb + T_XD + l * 80 + p4 * 2) = d;
;               v2u e; e.x = cvt_pk_bf16(x0 * e2, x1 * e2); e.y = cvt_pk_bf16(x2 * e2, x3 * e2); *(v2u*)(sb + T_XE + l * 80 + p4 * 2) = e;
;               *(v2u*)(sb + T_XS + l * 64 + p4 * 2) = R.Xr; *(v2u*)(sb + T_ZS + l * 64 + p4 * 2) = R.Zr;
;               if (w == 0) acP[lane] = R.aclane; }
;             BAR_LDS();
;             if (ci + 2 < nchunks) load_chunk(ci + 2, R);
;             bf16x8 cf[4];
; #pragma unroll
;             for (int k = 0; k < 4; ++k) cf[k] = *(const bf16x8*)(sb + T_CS + (lt * 16 + fr) * 272 + (k * 32 + fq * 8) * 2);
;             f32x4 yo = {0.f, 0.f, 0.f, 0.f};
; #pragma unroll
;             for (int k = 0; k < 4; ++k) { const bf16x8 bb = *(const bf16x8*)((const unsigned char*)StR + (pt * 16 + fr) * 272 + (k * 32 + fq * 8) * 2); yo = mfma16(cf[k], bb, yo); }
; { const f32x4 a4 = *(const f32x4*)(acP + lt * 16 + fq * 4);
; #pragma unroll
;               for (int j = 0; j < 4; ++j) yo[j] *= __expf(a4[j]); }
;             const float acl_fr = acP[lt * 16 + fr]; const int lrow = lt * 16 + fr;
; #pragma unroll
;             for (int t = 0; t < 2; ++t) {
;                 if (2 * t <= lt) {
;                     v2u xb0, xb1;
;                     { const unsigned a0 = lds0 + par * T_BUF + T_XD + (32 * t + 4 * fq + tq) * 80 + (pt * 16 + 4 * tp) * 2, a1 = a0 + 16 * 80; TR_ISSUE(xb0, a0); TR_ISSUE(xb1, a1); }
;                     float m[8];
;                     { f32x4 s0 = {0.f, 0.f, 0.f, 0.f}, s1 = {0.f, 0.f, 0.f, 0.f};
; #pragma unroll
;                       for (int k = 0; k < 4; ++k) { const bf16x8 bf0 = *(const bf16x8*)(sb + T_BS + ((2 * t) * 16 + fr) * 272 + (k * 32 + fq * 8) * 2), bf1 = *(const bf16x8*)(sb + T_BS + ((2 * t + 1) * 16 + fr) * 272 + (k * 32 + fq * 8) * 2);
	ds_read_b128 v[128:131], v250 offset:11008
	ds_read_b128 v[184:187], v250 offset:12032
	v_lshlrev_b32_e32 v112, 16, v126
	v_and_b32_e32 v113, 0xffff0000, v126
	v_lshlrev_b32_e32 v114, 16, v127
	v_and_b32_e32 v115, 0xffff0000, v127
	v_mul_f32_e32 v120, 0xbfb8aa3b, v112
	v_mul_f32_e32 v121, 0xbfb8aa3b, v113
	v_mul_f32_e32 v122, 0xbfb8aa3b, v114
	v_mul_f32_e32 v123, 0xbfb8aa3b, v115
	v_exp_f32_e32 v120, v120
	v_exp_f32_e32 v121, v121
	v_exp_f32_e32 v122, v122
	v_exp_f32_e32 v123, v123
	v_add_f32_e32 v120, 1.0, v120
	v_add_f32_e32 v121, 1.0, v121
	v_add_f32_e32 v122, 1.0, v122
	v_add_f32_e32 v123, 1.0, v123
	v_rcp_f32_e32 v120, v120
	v_rcp_f32_e32 v121, v121
	v_rcp_f32_e32 v122, v122
	v_rcp_f32_e32 v123, v123
	v_mul_f32_e32 v112, v120, v112
	v_mul_f32_e32 v113, v121, v113
	v_mul_f32_e32 v114, v122, v114
	v_mul_f32_e32 v115, v123, v115
	v_lshlrev_b32_e32 v120, 16, v124
	v_and_b32_e32 v121, 0xffff0000, v124
	v_lshlrev_b32_e32 v122, 16, v125
	v_and_b32_e32 v123, 0xffff0000, v125
	s_waitcnt lgkmcnt(1)
	v_mfma_f32_16x16x32_bf16 v[24:27], v[56:59], v[128:131], v[24:27]
	s_waitcnt lgkmcnt(0)
	v_mfma_f32_16x16x32_bf16 v[24:27], v[60:63], v[184:187], v[24:27]
	s_mul_i32 s65, s56, 0x2000
	s_add_u32 s65, s65, 0x304f1000
	s_add_u32 s48, s0, s65
	s_addc_u32 s49, s1, 0
	s_nop 3
	v_fma_f32 v188, s61, v120, v24
	v_fma_f32 v189, s61, v121, v25
	v_fma_f32 v190, s61, v122, v26
	v_fma_f32 v191, s61, v123, v27
	v_mul_f32_e32 v188, v188, v112
	v_mul_f32_e32 v189, v189, v113
	v_mul_f32_e32 v190, v190, v114
	v_mul_f32_e32 v191, v191, v115
	v_cvt_pk_bf16_f32 v170, v188, v189
	v_cvt_pk_bf16_f32 v171, v190, v191
	global_store_dwordx2 v210, v[170:171], s[48:49]
	s_add_u32 s65, s54, 1
	s_sub_u32 s65, s65, s60
	s_lshl_b32 s65, s65, 6
	s_add_u32 s56, s65, s20
	s_add_u32 s54, s54, 1
	s_cmp_lt_u32 s54, s39
	s_cbranch_scc1 .Lssd_loop30
	s_branch .Lssd_done
.Lssd_loop31:
	ds_read_b128 v[28:31], v219 offset:12288
	ds_read_b128 v[32:35], v220 offset:12288
	ds_read_b128 v[40:43], v221 offset:12288
	ds_read_b128 v[44:47], v222 offset:12288
	ds_read_b128 v[48:51], v227
	ds_read_b128 v[52:55], v228
	ds_read_b128 v[56:59], v229
	ds_read_b128 v[60:63], v230
	ds_read_b32 v194, v231 offset:192
	ds_read_b128 v[64:67], v219 offset:20480
	ds_read_b128 v[68:71], v220 offset:20480
	ds_read_b128 v[72:75], v221 offset:20480
	ds_read_b128 v[76:79], v222 offset:20480
	ds_read_b128 v[80:83], v219 offset:28672
	ds_read_b128 v[84:87], v220 offset:28672
	global_load_dwordx4 v[140:143], v204, s[40:41] offset:2048
	s_waitcnt lgkmcnt(11)
	ds_read_b128 v[88:91], v221 offset:28672
	ds_read_b128 v[92:95], v222 offset:28672
	global_load_dwordx4 v[144:147], v205, s[40:41] offset:2048
	ds_read_b128 v[96:99], v232 offset:64
	ds_read_b128 v[100:103], v232 offset:192
	global_load_dwordx4 v[132:135], v204, s[40:41]
	s_waitcnt lgkmcnt(11)
	ds_read_b64 v[124:125], v235 offset:46464
	ds_read_b64 v[126:127], v235 offset:51072
	v_mfma_f32_16x16x32_bf16 v[24:27], v[48:51], v[28:31], 0
	global_load_dwordx4 v[136:139], v205, s[40:41]
	v_mfma_f32_16x16x32_bf16 v[24:27], v[52:55], v[32:35], v[24:27]
	v_mfma_f32_16x16x32_bf16 v[24:27], v[56:59], v[40:43], v[24:27]
	global_load_dwordx2 v[4:5], v206, s[40:41]
	v_mfma_f32_16x16x32_bf16 v[24:27], v[60:63], v[44:47], v[24:27]
	ds_read_b64_tr_b16 v[56:57], v233 offset:32768
	global_load_dwordx2 v[36:37], v207, s[42:43] nt
	ds_read_b64_tr_b16 v[58:59], v233 offset:34048
	s_waitcnt lgkmcnt(11)
	ds_read_b64_tr_b16 v[60:61], v233 offset:35328
	ds_read_b64_tr_b16 v[62:63], v233 offset:36608
	global_load_dword v6, v208, s[44:45]
	v_mfma_f32_16x16x32_bf16 v[48:51], v[64:67], v[28:31], 0
	s_waitcnt lgkmcnt(11)
	v_mfma_f32_16x16x32_bf16 v[52:55], v[80:83], v[28:31], 0
	global_load_dword v116, v208, s[46:47]
	v_mfma_f32_16x16x32_bf16 v[48:51], v[68:71], v[32:35], v[48:51]
	s_waitcnt lgkmcnt(10)
	v_mfma_f32_16x16x32_bf16 v[52:55], v[84:87], v[32:35], v[52:55]
	v_mfma_f32_16x16x32_bf16 v[48:51], v[72:75], v[40:43], v[48:51]
	global_load_dword v117, v209, s[46:47]
	s_waitcnt lgkmcnt(9)
	v_mfma_f32_16x16x32_bf16 v[52:55], v[88:91], v[40:43], v[52:55]
	v_mfma_f32_16x16x32_bf16 v[48:51], v[76:79], v[44:47], v[48:51]
	s_add_u32 s66, s54, 3
	s_cmp_lt_u32 s66, s39
	s_cselect_b32 s75, 0xc0000, 0
	s_cselect_b32 s76, 0x280000, 0
	s_cselect_b32 s77, 0x4000, 0
	s_add_u32 s40, s40, s75
	s_addc_u32 s41, s41, 0
	s_add_u32 s42, s42, s76
	s_addc_u32 s43, s43, 0
	s_add_u32 s44, s44, s77
	s_addc_u32 s45, s45, 0
	s_add_u32 s46, s46, s77
	s_addc_u32 s47, s47, 0
	s_waitcnt lgkmcnt(8)
	v_mfma_f32_16x16x32_bf16 v[52:55], v[92:95], v[44:47], v[52:55]
	s_waitcnt vmcnt(10)
	v_exp_f32_e32 v195, v194
	ds_write_b128 v213, v[156:159]
	v_mul_f32_e32 v24, v24, v195
	v_mul_f32_e32 v25, v25, v195
	ds_write_b128 v213, v[160:163] offset:8192
	v_mul_f32_e32 v26, v26, v195
	ds_write_b128 v213, v[148:151] offset:16384
	v_mul_f32_e32 v27, v27, v195
	ds_write_b128 v213, v[152:155] offset:24576
	s_waitcnt lgkmcnt(11)
	v_sub_f32_e32 v184, v194, v96
	v_sub_f32_e32 v200, v169, v168
	v_sub_f32_e32 v185, v194, v97
	v_mul_f32_e32 v200, 0x3fb8aa3b, v200
	v_sub_f32_e32 v186, v194, v98
	v_sub_f32_e32 v187, v194, v99
	v_exp_f32_e32 v200, v200
	v_exp_f32_e32 v184, v184
	v_lshlrev_b32_e32 v196, 16, v164
	v_exp_f32_e32 v185, v185
	v_and_b32_e32 v197, 0xffff0000, v164
	v_exp_f32_e32 v186, v186
	v_lshlrev_b32_e32 v198, 16, v165
	v_exp_f32_e32 v187, v187
	v_and_b32_e32 v199, 0xffff0000, v165
	v_mul_f32_e32 v184, v48, v184
	v_mul_f32_e32 v185, v49, v185
	v_mul_f32_e32 v196, v196, v118
	v_mul_f32_e32 v186, v50, v186
	v_mul_f32_e32 v197, v197, v118
	v_mul_f32_e32 v187, v51, v187
	v_mul_f32_e32 v198, v198, v118
	v_cvt_pk_bf16_f32 v184, v184, v185
	v_mul_f32_e32 v199, v199, v118
	v_cvt_pk_bf16_f32 v185, v186, v187
	v_cvt_pk_bf16_f32 v202, v196, v197
	ds_write_b64 v250, v[184:185] offset:4104
	s_waitcnt lgkmcnt(11)
; __device__ __forceinline__ unsigned cvt_pk_bf16(float lo, float hi) { unsigned r; asm volatile("v_cvt_pk_bf16_f32 %0, %1, %2" : "=v"(r) : "v"(lo), "v"(hi)); return r; }
; __device__ __forceinline__ bf16 f2bfh(float f) { return (bf16)(cvt_pk_bf16(f, f) & 0xffffu); }
; __device__ __forceinline__ void phase_ssd(const Params& P, int seg, unsigned char* smem) {
;     ...
;             for (int t = 0; t < 2; ++t) {
;                 if (2 * t <= lt) {
;                     v2u xb0, xb1;
;                     { const unsigned a0 = lds0 + par * T_BUF + T_XD + (32 * t + 4 * fq + tq) * 80 + (pt * 16 + 4 * tp) * 2, a1 = a0 + 16 * 80; TR_ISSUE(xb0, a0); TR_ISSUE(xb1, a1); }
;                     float m[8];
;                     { f32x4 s0 = {0.f, 0.f, 0.f, 0.f}, s1 = {0.f, 0.f, 0.f, 0.f};
; #pragma unroll
;                       for (int k = 0; k < 4; ++k) { const bf16x8 bf0 = *(const bf16x8*)(sb + T_BS + ((2 * t) * 16 + fr) * 272 + (k * 32 + fq * 8) * 2), bf1 = *(const bf16x8*)(sb + T_BS + ((2 * t + 1) * 16 + fr) * 272 + (k * 32 + fq * 8) * 2);
;                           s0 = mfma16(bf0, cf[k], s0); s1 = mfma16(bf1, cf[k], s1); }
;                       const f32x4 a0 = *(const f32x4*)(acP + (2 * t) * 16 + fq * 4), a1 = *(const f32x4*)(acP + (2 * t + 1) * 16 + fq * 4);
; #pragma unroll
;                       for (int j = 0; j < 4; ++j) { const int si0 = (2 * t) * 16 + fq * 4 + j, si1 = si0 + 16;
;                           const float e0 = s0[j] * __expf(fminf(acl_fr - a0[j], 0.f)), e1 = s1[j] * __expf(fminf(acl_fr - a1[j], 0.f));
;                           m[j] = (si0 <= lrow) ? e0 : 0.f; m[4 + j] = (si1 <= lrow) ? e1 : 0.f; } }
;                     v4u mp; mp.x = cvt_pk_bf16(m[0], m[1]); mp.y = cvt_pk_bf16(m[2], m[3]); mp.z = cvt_pk_bf16(m[4], m[5]); mp.w = cvt_pk_bf16(m[6], m[7]);
;                     asm volatile("s_waitcnt lgkmcnt(0)" : "+v"(xb0), "+v"(xb1) :: "memory");
;                     yo = mfma16(__builtin_bit_cast(bf16x8, mp), mk8(xb0, xb1), yo);
;                 }
;             }
; #pragma unroll
;             for (int j = 0; j < 4; ++j) { const int l = lt * 16 + fq * 4 + j, p = pt * 16 + fr; const float xv = bf2f(*(const bf16*)(sb + T_XS + l * 64 + p * 2)), zv = bf2f(*(const bf16*)(sb + T_ZS + l * 64 + p * 2));
;                 ypre[(size_t)(row0 + l) * DINNER + h * 64 + ph * 32 + p] = f2bfh((yo[j] + Dh * xv) * siluf_(zv)); }
	v_sub_f32_e32 v188, v194, v100
	v_cvt_pk_bf16_f32 v203, v198, v199
	v_sub_f32_e32 v189, v194, v101
	ds_write_b64 v215, v[202:203] offset:32768
	v_sub_f32_e32 v190, v194, v102
	v_mul_f32_e32 v196, v196, v200
	v_sub_f32_e32 v191, v194, v103
	v_mul_f32_e32 v197, v197, v200
	v_exp_f32_e32 v188, v188
	v_mul_f32_e32 v198, v198, v200
	v_exp_f32_e32 v189, v189
	v_exp_f32_e32 v190, v190
	v_mul_f32_e32 v199, v199, v200
	v_exp_f32_e32 v191, v191
	v_cvt_pk_bf16_f32 v192, v196, v197
	v_mul_f32_e32 v188, v52, v188
	v_cvt_pk_bf16_f32 v193, v198, v199
	v_mul_f32_e32 v189, v53, v189
	ds_write_b64 v215, v[192:193] offset:37888
	v_mul_f32_e32 v190, v54, v190
	ds_write_b64 v217, v[164:165] offset:43008
	v_mul_f32_e32 v191, v55, v191
	v_cndmask_b32_e64 v188, 0, v188, s[14:15]
	ds_write_b64 v217, v[166:167] offset:47616
	v_cndmask_b32_e64 v189, 0, v189, s[16:17]
	v_mul_f32_e32 v201, 0x3fb8aa3b, v168
	v_cndmask_b32_e64 v190, 0, v190, s[22:23]
	s_waitcnt lgkmcnt(11)
	ds_write_b32 v218, v201 offset:256
	v_cndmask_b32_e64 v191, 0, v191, s[34:35]
	v_mul_f32_e32 v174, 0x3fb8aa3b, v169
	v_cvt_pk_bf16_f32 v188, v188, v189
	v_exp_f32_e32 v174, v174
	v_cvt_pk_bf16_f32 v189, v190, v191
	ds_write_b64 v250, v[188:189] offset:5128
	s_waitcnt lgkmcnt(0)
	s_barrier
	ds_read_b128 v[128:131], v250 offset:4096
	ds_read_b128 v[184:187], v250 offset:5120
	v_lshlrev_b32_e32 v112, 16, v126
	v_and_b32_e32 v113, 0xffff0000, v126
	v_lshlrev_b32_e32 v114, 16, v127
	v_and_b32_e32 v115, 0xffff0000, v127
	v_mul_f32_e32 v120, 0xbfb8aa3b, v112
	v_mul_f32_e32 v121, 0xbfb8aa3b, v113
	v_mul_f32_e32 v122, 0xbfb8aa3b, v114
	v_mul_f32_e32 v123, 0xbfb8aa3b, v115
	v_exp_f32_e32 v120, v120
	v_exp_f32_e32 v121, v121
	v_exp_f32_e32 v122, v122
	v_exp_f32_e32 v123, v123
	v_add_f32_e32 v120, 1.0, v120
	v_add_f32_e32 v121, 1.0, v121
	v_add_f32_e32 v122, 1.0, v122
	v_add_f32_e32 v123, 1.0, v123
	v_rcp_f32_e32 v120, v120
	v_rcp_f32_e32 v121, v121
	v_rcp_f32_e32 v122, v122
	v_rcp_f32_e32 v123, v123
	v_mul_f32_e32 v112, v120, v112
	v_mul_f32_e32 v113, v121, v113
	v_mul_f32_e32 v114, v122, v114
	v_mul_f32_e32 v115, v123, v115
	v_lshlrev_b32_e32 v120, 16, v124
	v_and_b32_e32 v121, 0xffff0000, v124
	v_lshlrev_b32_e32 v122, 16, v125
	v_and_b32_e32 v123, 0xffff0000, v125
	s_waitcnt lgkmcnt(1)
	v_mfma_f32_16x16x32_bf16 v[24:27], v[56:59], v[128:131], v[24:27]
	s_waitcnt lgkmcnt(0)
	v_mfma_f32_16x16x32_bf16 v[24:27], v[60:63], v[184:187], v[24:27]
	s_mul_i32 s65, s56, 0x2000
	s_add_u32 s65, s65, 0x304f1000
	s_add_u32 s48, s0, s65
	s_addc_u32 s49, s1, 0
	s_nop 3
	v_fma_f32 v188, s61, v120, v24
	v_fma_f32 v189, s61, v121, v25
	v_fma_f32 v190, s61, v122, v26
	v_fma_f32 v191, s61, v123, v27
	v_mul_f32_e32 v188, v188, v112
	v_mul_f32_e32 v189, v189, v113
	v_mul_f32_e32 v190, v190, v114
	v_mul_f32_e32 v191, v191, v115
	v_cvt_pk_bf16_f32 v170, v188, v189
	v_cvt_pk_bf16_f32 v171, v190, v191
	global_store_dwordx2 v210, v[170:171], s[48:49]
	s_add_u32 s65, s54, 1
	s_sub_u32 s65, s65, s60
	s_lshl_b32 s65, s65, 6
	s_add_u32 s56, s65, s20
	s_add_u32 s54, s54, 1
	s_cmp_ge_u32 s54, s39
	s_cbranch_scc1 .Lssd_done
; __device__ __forceinline__ void phase_ssd(const Params& P, int seg, unsigned char* smem) {
;     ...
;               for (int i = 0; i < 2; ++i) { const int q = tid + 512 * i, l = q >> 4, c8 = q & 15; *(v4u*)(sb + T_CS + l * 272 + c8 * 16) = R.Cr[i]; *(v4u*)(sb + T_BS + l * 272 + c8 * 16) = R.Br[i]; }
;               const int l = tid >> 3, p4 = (tid & 7) * 4;
;               const float x0 = bflo(R.Xr.x) * R.dtl, x1 = bfhi(R.Xr.x) * R.dtl, x2 = bflo(R.Xr.y) * R.dtl, x3 = bfhi(R.Xr.y) * R.dtl;
;               v2u d; d.x = cvt_pk_bf16(x0, x1); d.y = cvt_pk_bf16(x2, x3); *(v2u*)(sb + T_XD + l * 80 + p4 * 2) = d;
;               v2u e; e.x = cvt_pk_bf16(x0 * e2, x1 * e2); e.y = cvt_pk_bf16(x2 * e2, x3 * e2); *(v2u*)(sb + T_XE + l * 80 + p4 * 2) = e;
;               *(v2u*)(sb + T_XS + l * 64 + p4 * 2) = R.Xr; *(v2u*)(sb + T_ZS + l * 64 + p4 * 2) = R.Zr;
;               if (w == 0) acP[lane] = R.aclane; }
;             BAR_LDS();
;             if (ci + 2 < nchunks) load_chunk(ci + 2, R);
;             bf16x8 cf[4];
; #pragma unroll
;             for (int k = 0; k < 4; ++k) cf[k] = *(const bf16x8*)(sb + T_CS + (lt * 16 + fr) * 272 + (k * 32 + fq * 8) * 2);
;             f32x4 yo = {0.f, 0.f, 0.f, 0.f};
; #pragma unroll
;             for (int k = 0; k < 4; ++k) { const bf16x8 bb = *(const bf16x8*)((const unsigned char*)StR + (pt * 16 + fr) * 272 + (k * 32 + fq * 8) * 2); yo = mfma16(cf[k], bb, yo); }
; { const f32x4 a4 = *(const f32x4*)(acP + lt * 16 + fq * 4);
; #pragma unroll
;               for (int j = 0; j < 4; ++j) yo[j] *= __expf(a4[j]); }
;             const float acl_fr = acP[lt * 16 + fr]; const int lrow = lt * 16 + fr;
; #pragma unroll
;             for (int t = 0; t < 2; ++t) {
;                 if (2 * t <= lt) {
;                     v2u xb0, xb1;
;                     { const unsigned a0 = lds0 + par * T_BUF + T_XD + (32 * t + 4 * fq + tq) * 80 + (pt * 16 + 4 * tp) * 2, a1 = a0 + 16 * 80; TR_ISSUE(xb0, a0); TR_ISSUE(xb1, a1); }
;                     float m[8];
;                     { f32x4 s0 = {0.f, 0.f, 0.f, 0.f}, s1 = {0.f, 0.f, 0.f, 0.f};
; #pragma unroll
;                       for (int k = 0; k < 4; ++k) { const bf16x8 bf0 = *(const bf16x8*)(sb + T_BS + ((2 * t) * 16 + fr) * 272 + (k * 32 + fq * 8) * 2), bf1 = *(const bf16x8*)(sb + T_BS + ((2 * t + 1) * 16 + fr) * 272 + (k * 32 + fq * 8) * 2);
	ds_read_b128 v[28:31], v223 offset:12288
	ds_read_b128 v[32:35], v224 offset:12288
	ds_read_b128 v[40:43], v225 offset:12288
	ds_read_b128 v[44:47], v226 offset:12288
	ds_read_b128 v[48:51], v227 offset:8192
	ds_read_b128 v[52:55], v228 offset:8192
	ds_read_b128 v[56:59], v229 offset:8192
	ds_read_b128 v[60:63], v230 offset:8192
	ds_read_b32 v194, v231 offset:448
	ds_read_b128 v[64:67], v223 offset:20480
	ds_read_b128 v[68:71], v224 offset:20480
	ds_read_b128 v[72:75], v225 offset:20480
	ds_read_b128 v[76:79], v226 offset:20480
	ds_read_b128 v[80:83], v223 offset:28672
	ds_read_b128 v[84:87], v224 offset:28672
	global_load_dwordx4 v[156:159], v204, s[40:41] offset:2048
	s_waitcnt lgkmcnt(11)
	ds_read_b128 v[88:91], v225 offset:28672
	ds_read_b128 v[92:95], v226 offset:28672
	global_load_dwordx4 v[160:163], v205, s[40:41] offset:2048
	ds_read_b128 v[96:99], v232 offset:320
	ds_read_b128 v[100:103], v232 offset:448
	global_load_dwordx4 v[148:151], v204, s[40:41]
	s_waitcnt lgkmcnt(11)
	ds_read_b64 v[124:125], v236 offset:46464
	ds_read_b64 v[126:127], v236 offset:51072
	v_mfma_f32_16x16x32_bf16 v[24:27], v[48:51], v[28:31], 0
	global_load_dwordx4 v[152:155], v205, s[40:41]
	v_mfma_f32_16x16x32_bf16 v[24:27], v[52:55], v[32:35], v[24:27]
	v_mfma_f32_16x16x32_bf16 v[24:27], v[56:59], v[40:43], v[24:27]
	global_load_dwordx2 v[164:165], v206, s[40:41]
	v_mfma_f32_16x16x32_bf16 v[24:27], v[60:63], v[44:47], v[24:27]
	ds_read_b64_tr_b16 v[56:57], v234 offset:32768
	global_load_dwordx2 v[166:167], v207, s[42:43] nt
	ds_read_b64_tr_b16 v[58:59], v234 offset:34048
	s_waitcnt lgkmcnt(11)
	ds_read_b64_tr_b16 v[60:61], v234 offset:35328
	ds_read_b64_tr_b16 v[62:63], v234 offset:36608
	global_load_dword v118, v208, s[44:45]
	v_mfma_f32_16x16x32_bf16 v[48:51], v[64:67], v[28:31], 0
	s_waitcnt lgkmcnt(11)
	v_mfma_f32_16x16x32_bf16 v[52:55], v[80:83], v[28:31], 0
	global_load_dword v168, v208, s[46:47]
	v_mfma_f32_16x16x32_bf16 v[48:51], v[68:71], v[32:35], v[48:51]
	s_waitcnt lgkmcnt(10)
	v_mfma_f32_16x16x32_bf16 v[52:55], v[84:87], v[32:35], v[52:55]
	v_mfma_f32_16x16x32_bf16 v[48:51], v[72:75], v[40:43], v[48:51]
	global_load_dword v169, v209, s[46:47]
	s_waitcnt lgkmcnt(9)
	v_mfma_f32_16x16x32_bf16 v[52:55], v[88:91], v[40:43], v[52:55]
	v_mfma_f32_16x16x32_bf16 v[48:51], v[76:79], v[44:47], v[48:51]
	s_add_u32 s66, s54, 3
	s_cmp_lt_u32 s66, s39
	s_cselect_b32 s75, 0xc0000, 0
	s_cselect_b32 s76, 0x280000, 0
	s_cselect_b32 s77, 0x4000, 0
	s_add_u32 s40, s40, s75
	s_addc_u32 s41, s41, 0
	s_add_u32 s42, s42, s76
	s_addc_u32 s43, s43, 0
	s_add_u32 s44, s44, s77
	s_addc_u32 s45, s45, 0
	s_add_u32 s46, s46, s77
	s_addc_u32 s47, s47, 0
	s_waitcnt lgkmcnt(8)
	v_mfma_f32_16x16x32_bf16 v[52:55], v[92:95], v[44:47], v[52:55]
	s_waitcnt vmcnt(10)
	v_exp_f32_e32 v195, v194
	ds_write_b128 v212, v[140:143]
	v_mul_f32_e32 v24, v24, v195
	v_mul_f32_e32 v25, v25, v195
	ds_write_b128 v212, v[144:147] offset:8192
	v_mul_f32_e32 v26, v26, v195
	ds_write_b128 v212, v[132:135] offset:16384
	v_mul_f32_e32 v27, v27, v195
	ds_write_b128 v212, v[136:139] offset:24576
	s_waitcnt lgkmcnt(11)
	v_sub_f32_e32 v184, v194, v96
	v_sub_f32_e32 v200, v117, v116
	v_sub_f32_e32 v185, v194, v97
	v_mul_f32_e32 v200, 0x3fb8aa3b, v200
	v_sub_f32_e32 v186, v194, v98
	v_sub_f32_e32 v187, v194, v99
	v_exp_f32_e32 v200, v200
	v_exp_f32_e32 v184, v184
	v_lshlrev_b32_e32 v196, 16, v4
	v_exp_f32_e32 v185, v185
	v_and_b32_e32 v197, 0xffff0000, v4
	v_exp_f32_e32 v186, v186
	v_lshlrev_b32_e32 v198, 16, v5
	v_exp_f32_e32 v187, v187
	v_and_b32_e32 v199, 0xffff0000, v5
	v_mul_f32_e32 v184, v48, v184
	v_mul_f32_e32 v185, v49, v185
	v_mul_f32_e32 v196, v196, v6
	v_mul_f32_e32 v186, v50, v186
	v_mul_f32_e32 v197, v197, v6
	v_mul_f32_e32 v187, v51, v187
	v_mul_f32_e32 v198, v198, v6
	v_cvt_pk_bf16_f32 v184, v184, v185
	v_mul_f32_e32 v199, v199, v6
	v_cvt_pk_bf16_f32 v185, v186, v187
	v_cvt_pk_bf16_f32 v202, v196, v197
	ds_write_b64 v250, v[184:185] offset:11016
	s_waitcnt lgkmcnt(11)
	v_sub_f32_e32 v188, v194, v100
	v_cvt_pk_bf16_f32 v203, v198, v199
	v_sub_f32_e32 v189, v194, v101
	ds_write_b64 v214, v[202:203] offset:32768
	v_sub_f32_e32 v190, v194, v102
	v_mul_f32_e32 v196, v196, v200
	v_sub_f32_e32 v191, v194, v103
	v_mul_f32_e32 v197, v197, v200
	v_exp_f32_e32 v188, v188
	v_mul_f32_e32 v198, v198, v200
	v_exp_f32_e32 v189, v189
	v_exp_f32_e32 v190, v190
	v_mul_f32_e32 v199, v199, v200
	v_exp_f32_e32 v191, v191
	v_cvt_pk_bf16_f32 v192, v196, v197
	v_mul_f32_e32 v188, v52, v188
	v_cvt_pk_bf16_f32 v193, v198, v199
	v_mul_f32_e32 v189, v53, v189
	ds_write_b64 v214, v[192:193] offset:37888
	v_mul_f32_e32 v190, v54, v190
	ds_write_b64 v216, v[4:5] offset:43008
	v_mul_f32_e32 v191, v55, v191
	v_cndmask_b32_e64 v188, 0, v188, s[14:15]
	ds_write_b64 v216, v[36:37] offset:47616
	v_cndmask_b32_e64 v189, 0, v189, s[16:17]
	v_mul_f32_e32 v201, 0x3fb8aa3b, v116
	v_cndmask_b32_e64 v190, 0, v190, s[22:23]
	s_waitcnt lgkmcnt(11)
	ds_write_b32 v218, v201
	v_cndmask_b32_e64 v191, 0, v191, s[34:35]
	v_mul_f32_e32 v174, 0x3fb8aa3b, v117
	v_cvt_pk_bf16_f32 v188, v188, v189
	v_exp_f32_e32 v174, v174
	v_cvt_pk_bf16_f32 v189, v190, v191
	ds_write_b64 v250, v[188:189] offset:12040
	s_waitcnt lgkmcnt(0)
	s_barrier
	ds_read_b128 v[128:131], v250 offset:11008
	ds_read_b128 v[184:187], v250 offset:12032
	v_lshlrev_b32_e32 v112, 16, v126
	v_and_b32_e32 v113, 0xffff0000, v126
	v_lshlrev_b32_e32 v114, 16, v127
	v_and_b32_e32 v115, 0xffff0000, v127
	v_mul_f32_e32 v120, 0xbfb8aa3b, v112
	v_mul_f32_e32 v121, 0xbfb8aa3b, v113
	v_mul_f32_e32 v122, 0xbfb8aa3b, v114
	v_mul_f32_e32 v123, 0xbfb8aa3b, v115
	v_exp_f32_e32 v120, v120
	v_exp_f32_e32 v121, v121
	v_exp_f32_e32 v122, v122
	v_exp_f32_e32 v123, v123
	v_add_f32_e32 v120, 1.0, v120
	v_add_f32_e32 v121, 1.0, v121
	v_add_f32_e32 v122, 1.0, v122
	v_add_f32_e32 v123, 1.0, v123
	v_rcp_f32_e32 v120, v120
	v_rcp_f32_e32 v121, v121
	v_rcp_f32_e32 v122, v122
	v_rcp_f32_e32 v123, v123
	v_mul_f32_e32 v112, v120, v112
	v_mul_f32_e32 v113, v121, v113
	v_mul_f32_e32 v114, v122, v114
	v_mul_f32_e32 v115, v123, v115
	v_lshlrev_b32_e32 v120, 16, v124
	v_and_b32_e32 v121, 0xffff0000, v124
	v_lshlrev_b32_e32 v122, 16, v125
	v_and_b32_e32 v123, 0xffff0000, v125
	s_waitcnt lgkmcnt(1)
	v_mfma_f32_16x16x32_bf16 v[24:27], v[56:59], v[128:131], v[24:27]
	s_waitcnt lgkmcnt(0)
	v_mfma_f32_16x16x32_bf16 v[24:27], v[60:63], v[184:187], v[24:27]
	s_mul_i32 s65, s56, 0x2000
	s_add_u32 s65, s65, 0x304f1000
	s_add_u32 s48, s0, s65
	s_addc_u32 s49, s1, 0
	s_nop 3
	v_fma_f32 v188, s61, v120, v24
	v_fma_f32 v189, s61, v121, v25
	v_fma_f32 v190, s61, v122, v26
	v_fma_f32 v191, s61, v123, v27
	v_mul_f32_e32 v188, v188, v112
	v_mul_f32_e32 v189, v189, v113
	v_mul_f32_e32 v190, v190, v114
	v_mul_f32_e32 v191, v191, v115
	v_cvt_pk_bf16_f32 v170, v188, v189
	v_cvt_pk_bf16_f32 v171, v190, v191
	global_store_dwordx2 v210, v[170:171], s[48:49]
	s_add_u32 s65, s54, 1
	s_sub_u32 s65, s65, s60
	s_lshl_b32 s65, s65, 6
	s_add_u32 s56, s65, s20
	s_add_u32 s54, s54, 1
	s_cmp_lt_u32 s54, s39
	s_cbranch_scc1 .Lssd_loop31
